# 14 wave_sum xor-butterfly reductions (6 ds_bpermute round trips each) replaced by DPP quad_perm/mirror + permlane16/32 swaps (same summation order)
# baseline (speedup 1.0000x reference)
; __device__ __forceinline__ float wave_sum(float v) {
; #pragma unroll
;     for (int o = 1; o < 64; o <<= 1) v += __shfl_xor(v, o);
;     return v;
; __device__ __forceinline__ void rms_row_bf16(const Ctx& c, const float* xrow, const float* gain, bf16* orow, float* copy) {
;     const f32x4* xr = (const f32x4*)xrow + c.lane; f32x4 v[8]; float s = 0.f;
; #pragma unroll
;     for (int j = 0; j < 8; ++j) { v[j] = xr[64 * j]; s += (v[j].x * v[j].x + v[j].y * v[j].y) + (v[j].z * v[j].z + v[j].w * v[j].w); }
;     const float rs = rsqrtf(wave_sum(s) * (1.f / DM) + EPS);
.LBB0_187:
	global_load_dwordx4 v[30:33], v[44:45], off offset:-4096
	global_load_dwordx4 v[26:29], v[44:45], off offset:-3072
	global_load_dwordx4 v[22:25], v[44:45], off offset:-2048
	global_load_dwordx4 v[14:17], v[44:45], off
	global_load_dwordx4 v[18:21], v[44:45], off offset:-1024
	global_load_dwordx4 v[10:13], v[44:45], off offset:1024
	global_load_dwordx4 v[2:5], v[44:45], off offset:3072
	global_load_dwordx4 v[6:9], v[44:45], off offset:2048
	global_load_dwordx4 v[56:59], v[34:35], off
	s_add_i32 s2, s2, s86
	v_lshl_add_u64 v[44:45], v[44:45], 0, s[6:7]
	s_cmpk_gt_i32 s2, 0x3ff
	s_waitcnt vmcnt(8)
	v_mov_b32_e32 v62, v31
	s_waitcnt vmcnt(7)
	v_mov_b32_e32 v63, v27
	v_mov_b32_e32 v66, v33
	v_mov_b32_e32 v67, v29
	v_mov_b32_e32 v60, v30
	v_mov_b32_e32 v61, v26
	v_mov_b32_e32 v64, v32
	v_mov_b32_e32 v65, v28
	s_waitcnt vmcnt(6)
	v_pk_mul_f32 v[68:69], v[24:25], v[24:25]
	v_pk_mul_f32 v[70:71], v[22:23], v[22:23]
	v_pk_mul_f32 v[62:63], v[62:63], v[62:63]
	v_pk_mul_f32 v[66:67], v[66:67], v[66:67]
	v_mov_b32_e32 v84, v30
	v_mov_b32_e32 v85, v32
	v_mov_b32_e32 v32, v31
	v_mov_b32_e32 v30, v26
	v_mov_b32_e32 v31, v28
	v_mov_b32_e32 v28, v27
	v_pk_mov_b32 v[26:27], v[70:71], v[68:69] op_sel:[1,0]
	v_mov_b32_e32 v71, v69
	v_pk_fma_f32 v[60:61], v[60:61], v[60:61], v[62:63]
	v_pk_fma_f32 v[62:63], v[64:65], v[64:65], v[66:67]
	s_waitcnt vmcnt(4)
	v_mul_f32_e32 v72, v19, v19
	v_mul_f32_e32 v74, v21, v21
	v_pk_add_f32 v[26:27], v[26:27], v[70:71]
	v_pk_add_f32 v[60:61], v[60:61], v[62:63]
	v_mul_f32_e32 v55, v14, v14
	v_mul_f32_e32 v81, v15, v15
	v_mul_f32_e32 v83, v16, v16
	v_mul_f32_e32 v88, v17, v17
	v_pk_fma_f32 v[68:69], v[18:19], v[18:19], v[72:73] op_sel_hi:[1,1,0]
	v_pk_fma_f32 v[72:73], v[20:21], v[20:21], v[74:75] op_sel_hi:[1,1,0]
	v_pk_add_f32 v[26:27], v[26:27], v[26:27] op_sel:[0,1] op_sel_hi:[1,0]
	v_pk_add_f32 v[60:61], v[60:61], v[60:61] op_sel:[0,1] op_sel_hi:[1,0]
	s_waitcnt vmcnt(3)
	v_pk_mul_f32 v[76:77], v[12:13], v[12:13]
	v_pk_mul_f32 v[78:79], v[10:11], v[10:11]
	v_mov_b32_e32 v69, v83
	v_mov_b32_e32 v73, v88
	v_mov_b32_e32 v27, v81
	v_mov_b32_e32 v61, v55
	s_waitcnt vmcnt(0)
	v_mov_b32_e32 v86, v56
	v_mov_b32_e32 v87, v58
	v_mov_b32_e32 v58, v57
	v_pk_mov_b32 v[56:57], v[78:79], v[76:77] op_sel:[1,0]
	v_mov_b32_e32 v79, v77
	v_pk_add_f32 v[62:63], v[68:69], v[72:73]
	v_pk_add_f32 v[26:27], v[60:61], v[26:27]
	v_mul_f32_e32 v80, v7, v7
	v_mul_f32_e32 v82, v9, v9
	v_pk_add_f32 v[56:57], v[56:57], v[78:79]
	v_pk_add_f32 v[26:27], v[26:27], v[62:63]
	v_mul_f32_e32 v89, v2, v2
	v_mul_f32_e32 v90, v3, v3
	v_mul_f32_e32 v91, v4, v4
	v_mul_f32_e32 v92, v5, v5
	v_pk_fma_f32 v[74:75], v[6:7], v[6:7], v[80:81] op_sel_hi:[1,1,0]
	v_pk_fma_f32 v[76:77], v[8:9], v[8:9], v[82:83] op_sel_hi:[1,1,0]
	v_pk_add_f32 v[56:57], v[56:57], v[56:57] op_sel:[0,1] op_sel_hi:[1,0]
	v_pk_add_f32 v[26:27], v[26:27], v[26:27] op_sel:[0,1] op_sel_hi:[1,0]
	v_mov_b32_e32 v75, v91
	v_mov_b32_e32 v77, v92
	v_mov_b32_e32 v57, v90
	v_mov_b32_e32 v27, v89
	v_pk_add_f32 v[64:65], v[74:75], v[76:77]
	v_pk_add_f32 v[26:27], v[26:27], v[56:57]
	s_nop 0
	v_pk_add_f32 v[26:27], v[26:27], v[64:65]
	s_nop 0
	v_add_f32_e32 v26, v26, v27
	s_waitcnt lgkmcnt(0)
	s_nop 1
	v_add_f32_dpp v26, v26, v26 quad_perm:[1,0,3,2] row_mask:0xf bank_mask:0xf
	s_waitcnt lgkmcnt(0)
	s_nop 1
	v_add_f32_dpp v26, v26, v26 quad_perm:[2,3,0,1] row_mask:0xf bank_mask:0xf
	s_waitcnt lgkmcnt(0)
	s_nop 1
	v_add_f32_dpp v26, v26, v26 row_half_mirror row_mask:0xf bank_mask:0xf
	s_waitcnt lgkmcnt(0)
	s_nop 1
	v_add_f32_dpp v26, v26, v26 row_mirror row_mask:0xf bank_mask:0xf
	s_waitcnt lgkmcnt(0)
	v_mov_b32_e32 v27, v26
	s_nop 1
	v_permlane16_swap_b32_e32 v26, v27
	v_add_f32_e32 v26, v26, v27
	s_waitcnt lgkmcnt(0)
	v_mov_b32_e32 v27, v26
	s_nop 1
	v_permlane32_swap_b32_e32 v26, v27
	v_add_f32_e32 v26, v26, v27
	v_fmamk_f32 v26, v26, 0x3a000000, v53
	v_mul_f32_e32 v27, 0x4b800000, v26
	v_cmp_gt_f32_e32 vcc, s0, v26
	s_nop 1
	v_cndmask_b32_e32 v26, v26, v27, vcc
	v_rsq_f32_e32 v26, v26
	s_nop 0
	v_mul_f32_e32 v27, 0x45800000, v26
	v_cndmask_b32_e32 v26, v26, v27, vcc
	v_pk_mul_f32 v[56:57], v[84:85], v[26:27] op_sel_hi:[1,0]
	v_pk_mul_f32 v[32:33], v[32:33], v[26:27] op_sel_hi:[1,0]
	v_pk_mul_f32 v[60:61], v[30:31], v[26:27] op_sel_hi:[1,0]
	v_pk_mul_f32 v[30:31], v[86:87], v[56:57]
	v_pk_mul_f32 v[32:33], v[58:59], v[32:33]
	v_and_b32_sdwa v27, v31, v54 dst_sel:DWORD dst_unused:UNUSED_PAD src0_sel:WORD_1 src1_sel:DWORD
	v_and_b32_sdwa v56, v33, v54 dst_sel:DWORD dst_unused:UNUSED_PAD src0_sel:WORD_1 src1_sel:DWORD
	s_nop 1
	v_add3_u32 v27, v31, v27, s1
	v_add3_u32 v31, v33, v56, s1
	s_nop 1
	v_and_b32_e32 v31, 0xffff0000, v31
	s_nop 0
	v_or_b32_sdwa v31, v31, v27 dst_sel:DWORD dst_unused:UNUSED_PAD src0_sel:DWORD src1_sel:WORD_1
	v_cvt_pk_bf16_f32 v30, v30, v32
	global_store_dwordx2 v[46:47], v[30:31], off
	global_load_dwordx4 v[30:33], v[34:35], off offset:1024
	v_pk_mul_f32 v[28:29], v[28:29], v[26:27] op_sel_hi:[1,0]
	s_waitcnt vmcnt(0)
; __device__ __forceinline__ unsigned pk2(float lo, float hi) { return f2bf(lo) | (f2bf(hi) << 16); }
; __device__ __forceinline__ void rms_row_bf16(const Ctx& c, const float* xrow, const float* gain, bf16* orow, float* copy) {
;     ...
;     const f32x4* gr = (const f32x4*)gain + c.lane; v2u* o8 = (v2u*)orow + c.lane;
; #pragma unroll
;     for (int j = 0; j < 8; ++j) { const f32x4 g = gr[64 * j]; v2u o; o.x = pk2(v[j].x * rs * g.x, v[j].y * rs * g.y); o.y = pk2(v[j].z * rs * g.z, v[j].w * rs * g.w); o8[64 * j] = o; }
	v_mov_b32_e32 v57, v32
	v_mov_b32_e32 v32, v31
	v_mov_b32_e32 v56, v30
	v_pk_mul_f32 v[28:29], v[32:33], v[28:29]
	v_pk_mul_f32 v[30:31], v[56:57], v[60:61]
	v_and_b32_sdwa v33, v29, v54 dst_sel:DWORD dst_unused:UNUSED_PAD src0_sel:WORD_1 src1_sel:DWORD
	s_nop 0
	v_and_b32_sdwa v27, v31, v54 dst_sel:DWORD dst_unused:UNUSED_PAD src0_sel:WORD_1 src1_sel:DWORD
	s_nop 0
	v_add3_u32 v29, v29, v33, s1
	s_nop 1
	v_add3_u32 v27, v31, v27, s1
	v_and_b32_e32 v29, 0xffff0000, v29
	s_nop 0
	v_or_b32_sdwa v29, v29, v27 dst_sel:DWORD dst_unused:UNUSED_PAD src0_sel:DWORD src1_sel:WORD_1
	v_cvt_pk_bf16_f32 v28, v30, v28
	global_store_dwordx2 v[46:47], v[28:29], off offset:512
	global_load_dwordx4 v[28:31], v[34:35], off offset:2048
	v_mov_b32_e32 v32, v22
	v_mov_b32_e32 v33, v24
	v_mov_b32_e32 v24, v23
	v_pk_mul_f32 v[22:23], v[32:33], v[26:27] op_sel_hi:[1,0]
	v_pk_mul_f32 v[24:25], v[24:25], v[26:27] op_sel_hi:[1,0]
	s_waitcnt vmcnt(0)
	v_mov_b32_e32 v33, v30
	v_mov_b32_e32 v30, v29
	v_mov_b32_e32 v32, v28
	v_pk_mul_f32 v[24:25], v[30:31], v[24:25]
	v_pk_mul_f32 v[22:23], v[32:33], v[22:23]
	v_and_b32_sdwa v29, v25, v54 dst_sel:DWORD dst_unused:UNUSED_PAD src0_sel:WORD_1 src1_sel:DWORD
	s_nop 0
	v_and_b32_sdwa v27, v23, v54 dst_sel:DWORD dst_unused:UNUSED_PAD src0_sel:WORD_1 src1_sel:DWORD
	s_nop 0
	v_add3_u32 v25, v25, v29, s1
	s_nop 1
	v_add3_u32 v23, v23, v27, s1
	v_and_b32_e32 v25, 0xffff0000, v25
	s_nop 0
	v_or_b32_sdwa v23, v25, v23 dst_sel:DWORD dst_unused:UNUSED_PAD src0_sel:DWORD src1_sel:WORD_1
	v_cvt_pk_bf16_f32 v22, v22, v24
	global_store_dwordx2 v[46:47], v[22:23], off offset:1024
	global_load_dwordx4 v[22:25], v[34:35], off offset:3072
	v_mov_b32_e32 v28, v18
	v_mov_b32_e32 v29, v20
	v_mov_b32_e32 v20, v19
	v_pk_mul_f32 v[18:19], v[28:29], v[26:27] op_sel_hi:[1,0]
	v_pk_mul_f32 v[20:21], v[20:21], v[26:27] op_sel_hi:[1,0]
	s_waitcnt vmcnt(0)
	v_mov_b32_e32 v29, v24
	v_mov_b32_e32 v24, v23
	v_mov_b32_e32 v28, v22
	v_pk_mul_f32 v[20:21], v[24:25], v[20:21]
	v_pk_mul_f32 v[18:19], v[28:29], v[18:19]
	s_nop 7
	s_nop 1
	v_cvt_pk_bf16_f32 v19, v19, v21
	v_cvt_pk_bf16_f32 v18, v18, v20
	global_store_dwordx2 v[46:47], v[18:19], off offset:1536
	global_load_dwordx4 v[18:21], v[36:37], off
	v_mov_b32_e32 v22, v14
	v_mov_b32_e32 v23, v16
	v_mov_b32_e32 v16, v15
	v_pk_mul_f32 v[14:15], v[22:23], v[26:27] op_sel_hi:[1,0]
	v_pk_mul_f32 v[16:17], v[16:17], v[26:27] op_sel_hi:[1,0]
	s_waitcnt vmcnt(0)
	v_mov_b32_e32 v23, v20
	v_mov_b32_e32 v20, v19
	v_mov_b32_e32 v22, v18
	v_pk_mul_f32 v[16:17], v[20:21], v[16:17]
	v_pk_mul_f32 v[14:15], v[22:23], v[14:15]
	s_nop 7
	s_nop 1
	v_cvt_pk_bf16_f32 v15, v15, v17
	v_cvt_pk_bf16_f32 v14, v14, v16
	global_store_dwordx2 v[46:47], v[14:15], off offset:2048
	global_load_dwordx4 v[14:17], v[38:39], off
	v_mov_b32_e32 v18, v10
	v_mov_b32_e32 v19, v12
	v_mov_b32_e32 v12, v11
	v_pk_mul_f32 v[10:11], v[18:19], v[26:27] op_sel_hi:[1,0]
	v_pk_mul_f32 v[12:13], v[12:13], v[26:27] op_sel_hi:[1,0]
	s_waitcnt vmcnt(0)
	v_mov_b32_e32 v19, v16
	v_mov_b32_e32 v16, v15
	v_mov_b32_e32 v18, v14
	v_pk_mul_f32 v[12:13], v[16:17], v[12:13]
	v_pk_mul_f32 v[10:11], v[18:19], v[10:11]
	s_nop 7
	s_nop 1
	v_cvt_pk_bf16_f32 v11, v11, v13
	v_cvt_pk_bf16_f32 v10, v10, v12
	global_store_dwordx2 v[46:47], v[10:11], off offset:2560
	global_load_dwordx4 v[10:13], v[40:41], off
	v_mov_b32_e32 v14, v6
	v_mov_b32_e32 v15, v8
	v_mov_b32_e32 v8, v7
	v_pk_mul_f32 v[6:7], v[14:15], v[26:27] op_sel_hi:[1,0]
	v_pk_mul_f32 v[8:9], v[8:9], v[26:27] op_sel_hi:[1,0]
	s_waitcnt vmcnt(0)
	v_mov_b32_e32 v15, v12
	v_mov_b32_e32 v12, v11
	v_mov_b32_e32 v14, v10
	v_pk_mul_f32 v[8:9], v[8:9], v[12:13]
	v_pk_mul_f32 v[6:7], v[6:7], v[14:15]
	s_nop 7
	s_nop 1
	v_cvt_pk_bf16_f32 v7, v7, v9
	v_cvt_pk_bf16_f32 v6, v6, v8
	global_store_dwordx2 v[46:47], v[6:7], off offset:3072
	global_load_dwordx4 v[6:9], v[42:43], off
	v_mov_b32_e32 v10, v2
	v_mov_b32_e32 v11, v4
	v_mov_b32_e32 v4, v3
	v_pk_mul_f32 v[2:3], v[10:11], v[26:27] op_sel_hi:[1,0]
	v_pk_mul_f32 v[4:5], v[4:5], v[26:27] op_sel_hi:[1,0]
	s_waitcnt vmcnt(0)
	v_mov_b32_e32 v11, v8
	v_mov_b32_e32 v8, v7
	v_mov_b32_e32 v10, v6
	v_pk_mul_f32 v[4:5], v[4:5], v[8:9]
	v_pk_mul_f32 v[2:3], v[2:3], v[10:11]
	v_and_b32_sdwa v8, v5, v54 dst_sel:DWORD dst_unused:UNUSED_PAD src0_sel:WORD_1 src1_sel:DWORD
	v_and_b32_sdwa v9, v4, v54 dst_sel:DWORD dst_unused:UNUSED_PAD src0_sel:WORD_1 src1_sel:DWORD
	v_and_b32_sdwa v6, v3, v54 dst_sel:DWORD dst_unused:UNUSED_PAD src0_sel:WORD_1 src1_sel:DWORD
	v_and_b32_sdwa v7, v2, v54 dst_sel:DWORD dst_unused:UNUSED_PAD src0_sel:WORD_1 src1_sel:DWORD
	v_add3_u32 v5, v5, v8, s1
	v_add3_u32 v4, v4, v9, s1
	v_add3_u32 v2, v2, v7, s1
	v_add3_u32 v3, v3, v6, s1
	v_and_b32_e32 v5, 0xffff0000, v5
	v_and_b32_e32 v4, 0xffff0000, v4
	v_or_b32_sdwa v3, v5, v3 dst_sel:DWORD dst_unused:UNUSED_PAD src0_sel:DWORD src1_sel:WORD_1
	v_or_b32_sdwa v2, v4, v2 dst_sel:DWORD dst_unused:UNUSED_PAD src0_sel:DWORD src1_sel:WORD_1
	global_store_dwordx2 v[46:47], v[2:3], off offset:3584
	v_lshl_add_u64 v[46:47], v[46:47], 0, s[8:9]
	s_cbranch_scc0 .LBB0_187

; __device__ __forceinline__ float wave_sum(float v) {
; #pragma unroll
;     for (int o = 1; o < 64; o <<= 1) v += __shfl_xor(v, o);
;     return v;
; __device__ __forceinline__ void x_to_xb(const Ctx& c, const float* X, bf16* XB, float* RS) {
;     for (int row = c.gw; row < MT; row += c.NGW) {
;         const f32x4* xr = (const f32x4*)(X + (size_t)row * DM) + c.lane; f32x4 v[8]; float s = 0.f;
; #pragma unroll
;         for (int j = 0; j < 8; ++j) { v[j] = xr[64 * j]; s += (v[j].x * v[j].x + v[j].y * v[j].y) + (v[j].z * v[j].z + v[j].w * v[j].w); }
;         const float rs = rsqrtf(wave_sum(s) * (1.f / DM) + EPS); if (c.lane == 0) RS[row] = rs;
.LBB0_191:
	global_load_dwordx4 v[30:33], v[36:37], off offset:-4096
	global_load_dwordx4 v[26:29], v[36:37], off offset:-3072
	global_load_dwordx4 v[22:25], v[36:37], off offset:-2048
	global_load_dwordx4 v[18:21], v[36:37], off offset:-1024
	global_load_dwordx4 v[14:17], v[36:37], off
	global_load_dwordx4 v[10:13], v[36:37], off offset:1024
	global_load_dwordx4 v[6:9], v[36:37], off offset:2048
	global_load_dwordx4 v[2:5], v[36:37], off offset:3072
	s_waitcnt vmcnt(7)
	v_mul_f32_e32 v45, v31, v31
	v_mul_f32_e32 v46, v33, v33
	s_waitcnt vmcnt(6)
	v_mul_f32_e32 v47, v27, v27
	v_mul_f32_e32 v48, v29, v29
	s_waitcnt vmcnt(5)
	v_mul_f32_e32 v49, v23, v23
	v_mul_f32_e32 v50, v25, v25
	v_fmac_f32_e32 v45, v30, v30
	v_fmac_f32_e32 v46, v32, v32
	v_fmac_f32_e32 v47, v26, v26
	v_fmac_f32_e32 v48, v28, v28
	s_waitcnt vmcnt(4)
	v_mul_f32_e32 v51, v19, v19
	v_mul_f32_e32 v52, v21, v21
	v_fmac_f32_e32 v49, v22, v22
	v_fmac_f32_e32 v50, v24, v24
	v_add_f32_e32 v45, v45, v46
	v_add_f32_e32 v46, v47, v48
	s_waitcnt vmcnt(3)
	v_mul_f32_e32 v53, v15, v15
	v_mul_f32_e32 v54, v17, v17
	v_fmac_f32_e32 v51, v18, v18
	v_fmac_f32_e32 v52, v20, v20
	v_add_f32_e32 v47, v49, v50
	v_add_f32_e32 v45, v45, v46
	s_waitcnt vmcnt(2)
	v_mul_f32_e32 v55, v11, v11
	v_mul_f32_e32 v56, v13, v13
	v_fmac_f32_e32 v53, v14, v14
	v_fmac_f32_e32 v54, v16, v16
	v_add_f32_e32 v48, v51, v52
	v_add_f32_e32 v45, v45, v47
	s_waitcnt vmcnt(1)
	v_mul_f32_e32 v57, v7, v7
	v_mul_f32_e32 v58, v9, v9
	v_fmac_f32_e32 v55, v10, v10
	v_fmac_f32_e32 v56, v12, v12
	v_add_f32_e32 v49, v53, v54
	v_add_f32_e32 v45, v45, v48
	s_waitcnt vmcnt(0)
	v_mul_f32_e32 v59, v3, v3
	v_mul_f32_e32 v60, v5, v5
	v_fmac_f32_e32 v57, v6, v6
	v_fmac_f32_e32 v58, v8, v8
	v_add_f32_e32 v50, v55, v56
	v_add_f32_e32 v45, v45, v49
	v_fmac_f32_e32 v59, v2, v2
	v_fmac_f32_e32 v60, v4, v4
	v_add_f32_e32 v51, v57, v58
	v_add_f32_e32 v45, v45, v50
	v_add_f32_e32 v45, v45, v51
	v_add_f32_e32 v46, v59, v60
	v_add_f32_e32 v45, v45, v46
	s_waitcnt lgkmcnt(0)
	s_nop 1
	v_add_f32_dpp v45, v45, v45 quad_perm:[1,0,3,2] row_mask:0xf bank_mask:0xf
	s_waitcnt lgkmcnt(0)
	s_nop 1
	v_add_f32_dpp v45, v45, v45 quad_perm:[2,3,0,1] row_mask:0xf bank_mask:0xf
	s_waitcnt lgkmcnt(0)
	s_nop 1
	v_add_f32_dpp v45, v45, v45 row_half_mirror row_mask:0xf bank_mask:0xf
	s_waitcnt lgkmcnt(0)
	s_nop 1
	v_add_f32_dpp v45, v45, v45 row_mirror row_mask:0xf bank_mask:0xf
	s_waitcnt lgkmcnt(0)
	v_mov_b32_e32 v46, v45
	s_nop 1
	v_permlane16_swap_b32_e32 v45, v46
	v_add_f32_e32 v45, v45, v46
	ds_bpermute_b32 v46, v44, v45
	s_and_saveexec_b64 s[12:13], s[2:3]
	s_cbranch_execz .LBB0_190
	s_waitcnt lgkmcnt(0)
	v_add_f32_e32 v45, v45, v46
	v_fmamk_f32 v45, v45, 0x3a000000, v34
	s_mov_b32 s18, 0x800000
	v_mul_f32_e32 v46, 0x4b800000, v45
	v_cmp_gt_f32_e32 vcc, s18, v45
	s_load_dwordx2 s[18:19], s[52:53], 0x120
	s_waitcnt lgkmcnt(0)
	s_add_u32 s18, s18, s0
	v_cndmask_b32_e32 v45, v45, v46, vcc
	v_rsq_f32_e32 v45, v45
	s_addc_u32 s19, s19, s1
	v_mul_f32_e32 v46, 0x45800000, v45
	v_cndmask_b32_e32 v45, v45, v46, vcc
	global_store_dword v35, v45, s[18:19]
	s_branch .LBB0_190

; __device__ __forceinline__ float siluf_(float x) { return x * sigmoidf_(x); }
; __device__ __forceinline__ void ssd_gnorm(const Ctx& c, bf16* X2, const bf16* P, const float* g) {
;     for (int row = c.gw; row < MT; row += c.NGW) {
;         v4u* yr = (v4u*)(X2 + (size_t)row * 6144) + c.lane; const v4u* zr = (const v4u*)(P + (size_t)row * SSD_NP) + c.lane;
;         float v[8][8]; float s = 0.f;
; #pragma unroll
;         for (int j = 0; j < 8; ++j) { const v4u y = yr[64 * j], z = zr[64 * j];
; #pragma unroll
;             for (int k = 0; k < 4; ++k) { const float a = bflo(y[k]) * siluf_(bflo(z[k])), b = bfhi(y[k]) * siluf_(bfhi(z[k])); v[j][2 * k] = a; v[j][2 * k + 1] = b; s += a * a + b * b; } }
.LBB0_550:
	s_nop 0
	v_lshl_add_u64 v[64:65], s[8:9], 0, v[130:131]
	v_add_co_u32_e32 v134, vcc, 0x23400000, v64
	v_lshl_add_u64 v[66:67], s[6:7], 0, v[130:131]
	s_nop 0
	v_addc_co_u32_e32 v135, vcc, 0, v65, vcc
	v_add_co_u32_e32 v68, vcc, 0xd400000, v66
	global_load_dwordx4 v[120:123], v[134:135], off
	s_nop 0
	v_addc_co_u32_e32 v69, vcc, 0, v67, vcc
	global_load_dwordx4 v[124:127], v[68:69], off
	global_load_dwordx4 v[112:115], v[134:135], off offset:1024
	global_load_dwordx4 v[116:119], v[68:69], off offset:1024
	global_load_dwordx4 v[104:107], v[134:135], off offset:2048
	global_load_dwordx4 v[108:111], v[68:69], off offset:2048
	global_load_dwordx4 v[96:99], v[134:135], off offset:3072
	global_load_dwordx4 v[100:103], v[68:69], off offset:3072
	v_add_co_u32_e32 v132, vcc, s14, v64
	s_add_i32 s19, s19, s86
	s_nop 0
	v_addc_co_u32_e32 v133, vcc, 0, v65, vcc
	v_add_co_u32_e32 v68, vcc, s15, v66
	global_load_dwordx4 v[88:91], v[132:133], off
	s_nop 0
	v_addc_co_u32_e32 v69, vcc, 0, v67, vcc
	global_load_dwordx4 v[92:95], v[68:69], off
	global_load_dwordx4 v[80:83], v[132:133], off offset:1024
	global_load_dwordx4 v[84:87], v[68:69], off offset:1024
	global_load_dwordx4 v[72:75], v[132:133], off offset:2048
	global_load_dwordx4 v[76:79], v[68:69], off offset:2048
	global_load_dwordx4 v[64:67], v[132:133], off offset:3072
	s_nop 0
	global_load_dwordx4 v[68:71], v[68:69], off offset:3072
	s_add_u32 s6, s6, s11
	s_addc_u32 s7, s7, s10
	s_add_u32 s8, s8, s13
	s_addc_u32 s9, s9, s12
	s_cmpk_lt_i32 s19, 0x4000
	s_waitcnt vmcnt(14)
	v_lshlrev_b32_e32 v137, 16, v125
	v_lshlrev_b32_e32 v136, 16, v124
	v_mul_f32_e32 v138, 0xbfb8aa3b, v136
	v_mul_f32_e32 v139, 0xbfb8aa3b, v137
	v_exp_f32_e32 v138, v138
	v_exp_f32_e32 v139, v139
	v_and_b32_e32 v140, 0xffff0000, v124
	v_mul_f32_e32 v124, 0xbfb8aa3b, v140
	v_and_b32_e32 v141, 0xffff0000, v125
	v_pk_add_f32 v[138:139], v[138:139], 1.0 op_sel_hi:[1,0]
	v_exp_f32_e32 v142, v124
	v_div_scale_f32 v143, s[0:1], v139, v139, 1.0
	v_rcp_f32_e32 v144, v143
	v_lshlrev_b32_e32 v125, 16, v121
	v_lshlrev_b32_e32 v124, 16, v120
	v_and_b32_e32 v121, 0xffff0000, v121
	v_fma_f32 v145, -v143, v144, 1.0
	v_fmac_f32_e32 v144, v145, v144
	v_div_scale_f32 v145, vcc, 1.0, v139, 1.0
	v_mul_f32_e32 v146, v145, v144
	v_fma_f32 v147, -v143, v146, v145
	v_fmac_f32_e32 v146, v147, v144
	v_fma_f32 v143, -v143, v146, v145
	v_div_fmas_f32 v143, v143, v144, v146
	v_div_fixup_f32 v139, v143, v139, 1.0
	v_div_scale_f32 v143, s[0:1], v138, v138, 1.0
	v_rcp_f32_e32 v144, v143
	v_and_b32_e32 v120, 0xffff0000, v120
	v_fma_f32 v145, -v143, v144, 1.0
	v_fmac_f32_e32 v144, v145, v144
	v_div_scale_f32 v145, vcc, 1.0, v138, 1.0
	v_mul_f32_e32 v146, v145, v144
	v_fma_f32 v147, -v143, v146, v145
	v_fmac_f32_e32 v146, v147, v144
	v_fma_f32 v143, -v143, v146, v145
	v_div_fmas_f32 v143, v143, v144, v146
	v_div_fixup_f32 v138, v143, v138, 1.0
	v_pk_mul_f32 v[136:137], v[138:139], v[136:137]
	s_nop 0
	v_pk_mul_f32 v[124:125], v[136:137], v[124:125]
	v_mul_f32_e32 v136, 0xbfb8aa3b, v141
	v_exp_f32_e32 v143, v136
	s_nop 0
	v_pk_add_f32 v[136:137], v[142:143], 1.0 op_sel_hi:[1,0]
	s_nop 0
	v_div_scale_f32 v138, s[0:1], v137, v137, 1.0
	v_rcp_f32_e32 v139, v138
	s_nop 0
	v_fma_f32 v142, -v138, v139, 1.0
	v_fmac_f32_e32 v139, v142, v139
	v_div_scale_f32 v142, vcc, 1.0, v137, 1.0
	v_mul_f32_e32 v143, v142, v139
	v_fma_f32 v144, -v138, v143, v142
	v_fmac_f32_e32 v143, v144, v139
	v_fma_f32 v138, -v138, v143, v142
	v_div_fmas_f32 v138, v138, v139, v143
	v_div_fixup_f32 v137, v138, v137, 1.0
	v_div_scale_f32 v138, s[0:1], v136, v136, 1.0
	v_rcp_f32_e32 v139, v138
	s_nop 0
	v_fma_f32 v142, -v138, v139, 1.0
	v_fmac_f32_e32 v139, v142, v139
	v_div_scale_f32 v142, vcc, 1.0, v136, 1.0
	v_mul_f32_e32 v143, v142, v139
	v_fma_f32 v144, -v138, v143, v142
	v_fmac_f32_e32 v143, v144, v139
	v_fma_f32 v138, -v138, v143, v142
	v_div_fmas_f32 v138, v138, v139, v143
	v_div_fixup_f32 v136, v138, v136, 1.0
	v_lshlrev_b32_e32 v143, 16, v127
	v_lshlrev_b32_e32 v142, 16, v126
	v_pk_mul_f32 v[136:137], v[136:137], v[140:141]
	v_mul_f32_e32 v138, 0xbfb8aa3b, v142
	v_mul_f32_e32 v141, 0xbfb8aa3b, v143
	v_exp_f32_e32 v144, v138
	v_exp_f32_e32 v145, v141
	v_and_b32_e32 v139, 0xffff0000, v127
	v_and_b32_e32 v138, 0xffff0000, v126
	v_mul_f32_e32 v126, 0xbfb8aa3b, v138
	v_pk_add_f32 v[144:145], v[144:145], 1.0 op_sel_hi:[1,0]
	v_exp_f32_e32 v140, v126
	v_div_scale_f32 v141, s[0:1], v145, v145, 1.0
	v_rcp_f32_e32 v146, v141
	v_lshlrev_b32_e32 v127, 16, v123
	v_lshlrev_b32_e32 v126, 16, v122
	v_pk_mul_f32 v[120:121], v[136:137], v[120:121]
	v_fma_f32 v147, -v141, v146, 1.0
	v_fmac_f32_e32 v146, v147, v146
	v_div_scale_f32 v147, vcc, 1.0, v145, 1.0
	v_mul_f32_e32 v148, v147, v146
	v_fma_f32 v149, -v141, v148, v147
	v_fmac_f32_e32 v148, v149, v146
	v_fma_f32 v141, -v141, v148, v147
	v_div_fmas_f32 v141, v141, v146, v148
	v_div_fixup_f32 v145, v141, v145, 1.0
	v_div_scale_f32 v141, s[0:1], v144, v144, 1.0
	v_rcp_f32_e32 v146, v141
	v_and_b32_e32 v123, 0xffff0000, v123
	v_and_b32_e32 v122, 0xffff0000, v122
	v_pk_mul_f32 v[136:137], v[120:121], v[120:121]
	v_fma_f32 v147, -v141, v146, 1.0
	v_fmac_f32_e32 v146, v147, v146
	v_div_scale_f32 v147, vcc, 1.0, v144, 1.0
	v_mul_f32_e32 v148, v147, v146
	v_fma_f32 v149, -v141, v148, v147
	v_fmac_f32_e32 v148, v149, v146
	v_fma_f32 v141, -v141, v148, v147
	v_div_fmas_f32 v141, v141, v146, v148
	v_div_fixup_f32 v144, v141, v144, 1.0
	v_mul_f32_e32 v141, 0xbfb8aa3b, v139
	v_exp_f32_e32 v141, v141
	v_pk_mul_f32 v[142:143], v[144:145], v[142:143]
	v_pk_fma_f32 v[136:137], v[124:125], v[124:125], v[136:137]
	v_pk_mul_f32 v[126:127], v[142:143], v[126:127]
	v_pk_add_f32 v[140:141], v[140:141], 1.0 op_sel_hi:[1,0]
	v_add_f32_e32 v136, v136, v137
	v_div_scale_f32 v142, s[0:1], v141, v141, 1.0
	v_rcp_f32_e32 v143, v142
	s_nop 0
	v_fma_f32 v144, -v142, v143, 1.0
	v_fmac_f32_e32 v143, v144, v143
	v_div_scale_f32 v144, vcc, 1.0, v141, 1.0
	v_mul_f32_e32 v145, v144, v143
	v_fma_f32 v146, -v142, v145, v144
	v_fmac_f32_e32 v145, v146, v143
	v_fma_f32 v142, -v142, v145, v144
	v_div_fmas_f32 v142, v142, v143, v145
	v_div_fixup_f32 v141, v142, v141, 1.0
	v_div_scale_f32 v142, s[0:1], v140, v140, 1.0
	v_rcp_f32_e32 v143, v142
	s_nop 0
	v_fma_f32 v144, -v142, v143, 1.0
	v_fmac_f32_e32 v143, v144, v143
	v_div_scale_f32 v144, vcc, 1.0, v140, 1.0
	v_mul_f32_e32 v145, v144, v143
	v_fma_f32 v146, -v142, v145, v144
	v_fmac_f32_e32 v145, v146, v143
	v_fma_f32 v142, -v142, v145, v144
	v_div_fmas_f32 v142, v142, v143, v145
	v_div_fixup_f32 v140, v142, v140, 1.0
	s_waitcnt vmcnt(12)
; __device__ __forceinline__ float siluf_(float x) { return x * sigmoidf_(x); }
; __device__ __forceinline__ void ssd_gnorm(const Ctx& c, bf16* X2, const bf16* P, const float* g) {
;     ...
;         for (int j = 0; j < 8; ++j) { const v4u y = yr[64 * j], z = zr[64 * j];
; #pragma unroll
;             for (int k = 0; k < 4; ++k) { const float a = bflo(y[k]) * siluf_(bflo(z[k])), b = bfhi(y[k]) * siluf_(bfhi(z[k])); v[j][2 * k] = a; v[j][2 * k + 1] = b; s += a * a + b * b; } }
	v_lshlrev_b32_e32 v145, 16, v117
	v_lshlrev_b32_e32 v144, 16, v116
	v_pk_mul_f32 v[138:139], v[140:141], v[138:139]
	v_mul_f32_e32 v140, 0xbfb8aa3b, v144
	v_mul_f32_e32 v143, 0xbfb8aa3b, v145
	v_exp_f32_e32 v146, v140
	v_exp_f32_e32 v147, v143
	v_and_b32_e32 v141, 0xffff0000, v117
	v_and_b32_e32 v140, 0xffff0000, v116
	v_mul_f32_e32 v116, 0xbfb8aa3b, v140
	v_pk_add_f32 v[146:147], v[146:147], 1.0 op_sel_hi:[1,0]
	v_exp_f32_e32 v142, v116
	v_div_scale_f32 v143, s[0:1], v147, v147, 1.0
	v_rcp_f32_e32 v148, v143
	v_lshlrev_b32_e32 v117, 16, v113
	v_lshlrev_b32_e32 v116, 16, v112
	v_pk_mul_f32 v[122:123], v[138:139], v[122:123]
	v_fma_f32 v149, -v143, v148, 1.0
	v_fmac_f32_e32 v148, v149, v148
	v_div_scale_f32 v149, vcc, 1.0, v147, 1.0
	v_mul_f32_e32 v150, v149, v148
	v_fma_f32 v151, -v143, v150, v149
	v_fmac_f32_e32 v150, v151, v148
	v_fma_f32 v143, -v143, v150, v149
	v_div_fmas_f32 v143, v143, v148, v150
	v_div_fixup_f32 v147, v143, v147, 1.0
	v_div_scale_f32 v143, s[0:1], v146, v146, 1.0
	v_rcp_f32_e32 v148, v143
	v_pk_mul_f32 v[138:139], v[122:123], v[122:123]
	v_and_b32_e32 v113, 0xffff0000, v113
	v_and_b32_e32 v112, 0xffff0000, v112
	v_fma_f32 v149, -v143, v148, 1.0
	v_fmac_f32_e32 v148, v149, v148
	v_div_scale_f32 v149, vcc, 1.0, v146, 1.0
	v_mul_f32_e32 v150, v149, v148
	v_fma_f32 v151, -v143, v150, v149
	v_fmac_f32_e32 v150, v151, v148
	v_fma_f32 v143, -v143, v150, v149
	v_div_fmas_f32 v143, v143, v148, v150
	v_div_fixup_f32 v146, v143, v146, 1.0
	v_mul_f32_e32 v143, 0xbfb8aa3b, v141
	v_exp_f32_e32 v143, v143
	v_pk_mul_f32 v[144:145], v[146:147], v[144:145]
	v_pk_fma_f32 v[138:139], v[126:127], v[126:127], v[138:139]
	v_pk_mul_f32 v[116:117], v[144:145], v[116:117]
	v_pk_add_f32 v[142:143], v[142:143], 1.0 op_sel_hi:[1,0]
	v_add_f32_e32 v136, v138, v136
	v_div_scale_f32 v144, s[0:1], v143, v143, 1.0
	v_rcp_f32_e32 v145, v144
	v_add_f32_e32 v136, v139, v136
	v_fma_f32 v146, -v144, v145, 1.0
	v_fmac_f32_e32 v145, v146, v145
	v_div_scale_f32 v146, vcc, 1.0, v143, 1.0
	v_mul_f32_e32 v147, v146, v145
	v_fma_f32 v148, -v144, v147, v146
	v_fmac_f32_e32 v147, v148, v145
	v_fma_f32 v144, -v144, v147, v146
	v_div_fmas_f32 v144, v144, v145, v147
	v_div_fixup_f32 v143, v144, v143, 1.0
	v_div_scale_f32 v144, s[0:1], v142, v142, 1.0
	v_rcp_f32_e32 v145, v144
	s_nop 0
	v_fma_f32 v146, -v144, v145, 1.0
	v_fmac_f32_e32 v145, v146, v145
	v_div_scale_f32 v146, vcc, 1.0, v142, 1.0
	v_mul_f32_e32 v147, v146, v145
	v_fma_f32 v148, -v144, v147, v146
	v_fmac_f32_e32 v147, v148, v145
	v_fma_f32 v144, -v144, v147, v146
	v_div_fmas_f32 v144, v144, v145, v147
	v_div_fixup_f32 v142, v144, v142, 1.0
	v_lshlrev_b32_e32 v147, 16, v119
	v_lshlrev_b32_e32 v146, 16, v118
	v_pk_mul_f32 v[140:141], v[142:143], v[140:141]
	v_mul_f32_e32 v142, 0xbfb8aa3b, v146
	v_mul_f32_e32 v145, 0xbfb8aa3b, v147
	v_exp_f32_e32 v148, v142
	v_exp_f32_e32 v149, v145
	v_and_b32_e32 v143, 0xffff0000, v119
	v_and_b32_e32 v142, 0xffff0000, v118
	v_mul_f32_e32 v118, 0xbfb8aa3b, v142
	v_pk_add_f32 v[148:149], v[148:149], 1.0 op_sel_hi:[1,0]
	v_exp_f32_e32 v144, v118
	v_div_scale_f32 v145, s[0:1], v149, v149, 1.0
	v_rcp_f32_e32 v150, v145
	v_lshlrev_b32_e32 v119, 16, v115
	v_lshlrev_b32_e32 v118, 16, v114
	v_pk_mul_f32 v[112:113], v[140:141], v[112:113]
	v_fma_f32 v151, -v145, v150, 1.0
	v_fmac_f32_e32 v150, v151, v150
	v_div_scale_f32 v151, vcc, 1.0, v149, 1.0
	v_mul_f32_e32 v152, v151, v150
	v_fma_f32 v153, -v145, v152, v151
	v_fmac_f32_e32 v152, v153, v150
	v_fma_f32 v145, -v145, v152, v151
	v_div_fmas_f32 v145, v145, v150, v152
	v_div_fixup_f32 v149, v145, v149, 1.0
	v_div_scale_f32 v145, s[0:1], v148, v148, 1.0
	v_rcp_f32_e32 v150, v145
	v_pk_mul_f32 v[140:141], v[112:113], v[112:113]
	v_and_b32_e32 v115, 0xffff0000, v115
	v_and_b32_e32 v114, 0xffff0000, v114
	v_fma_f32 v151, -v145, v150, 1.0
	v_fmac_f32_e32 v150, v151, v150
	v_div_scale_f32 v151, vcc, 1.0, v148, 1.0
	v_mul_f32_e32 v152, v151, v150
	v_fma_f32 v153, -v145, v152, v151
	v_fmac_f32_e32 v152, v153, v150
	v_fma_f32 v145, -v145, v152, v151
	v_div_fmas_f32 v145, v145, v150, v152
	v_div_fixup_f32 v148, v145, v148, 1.0
	v_mul_f32_e32 v145, 0xbfb8aa3b, v143
	v_exp_f32_e32 v145, v145
	v_pk_mul_f32 v[146:147], v[148:149], v[146:147]
	v_pk_fma_f32 v[140:141], v[116:117], v[116:117], v[140:141]
	v_pk_mul_f32 v[118:119], v[146:147], v[118:119]
	v_pk_add_f32 v[144:145], v[144:145], 1.0 op_sel_hi:[1,0]
	v_add_f32_e32 v136, v140, v136
	v_div_scale_f32 v146, s[0:1], v145, v145, 1.0
	v_rcp_f32_e32 v147, v146
	v_add_f32_e32 v136, v141, v136
	v_fma_f32 v148, -v146, v147, 1.0
	v_fmac_f32_e32 v147, v148, v147
	v_div_scale_f32 v148, vcc, 1.0, v145, 1.0
	v_mul_f32_e32 v149, v148, v147
	v_fma_f32 v150, -v146, v149, v148
	v_fmac_f32_e32 v149, v150, v147
	v_fma_f32 v146, -v146, v149, v148
	v_div_fmas_f32 v146, v146, v147, v149
	v_div_fixup_f32 v145, v146, v145, 1.0
	v_div_scale_f32 v146, s[0:1], v144, v144, 1.0
	v_rcp_f32_e32 v147, v146
	s_nop 0
	v_fma_f32 v148, -v146, v147, 1.0
	v_fmac_f32_e32 v147, v148, v147
	v_div_scale_f32 v148, vcc, 1.0, v144, 1.0
	v_mul_f32_e32 v149, v148, v147
	v_fma_f32 v150, -v146, v149, v148
	v_fmac_f32_e32 v149, v150, v147
	v_fma_f32 v146, -v146, v149, v148
	v_div_fmas_f32 v146, v146, v147, v149
	v_div_fixup_f32 v144, v146, v144, 1.0
	s_waitcnt vmcnt(10)
; __device__ __forceinline__ float siluf_(float x) { return x * sigmoidf_(x); }
; __device__ __forceinline__ void ssd_gnorm(const Ctx& c, bf16* X2, const bf16* P, const float* g) {
;     ...
;         for (int j = 0; j < 8; ++j) { const v4u y = yr[64 * j], z = zr[64 * j];
; #pragma unroll
;             for (int k = 0; k < 4; ++k) { const float a = bflo(y[k]) * siluf_(bflo(z[k])), b = bfhi(y[k]) * siluf_(bfhi(z[k])); v[j][2 * k] = a; v[j][2 * k + 1] = b; s += a * a + b * b; } }
	v_lshlrev_b32_e32 v149, 16, v109
	v_lshlrev_b32_e32 v148, 16, v108
	v_pk_mul_f32 v[142:143], v[144:145], v[142:143]
	v_mul_f32_e32 v144, 0xbfb8aa3b, v148
	v_mul_f32_e32 v147, 0xbfb8aa3b, v149
	v_exp_f32_e32 v150, v144
	v_exp_f32_e32 v151, v147
	v_and_b32_e32 v145, 0xffff0000, v109
	v_and_b32_e32 v144, 0xffff0000, v108
	v_mul_f32_e32 v108, 0xbfb8aa3b, v144
	v_pk_add_f32 v[150:151], v[150:151], 1.0 op_sel_hi:[1,0]
	v_exp_f32_e32 v146, v108
	v_div_scale_f32 v147, s[0:1], v151, v151, 1.0
	v_rcp_f32_e32 v152, v147
	v_lshlrev_b32_e32 v109, 16, v105
	v_lshlrev_b32_e32 v108, 16, v104
	v_pk_mul_f32 v[114:115], v[142:143], v[114:115]
	v_fma_f32 v153, -v147, v152, 1.0
	v_fmac_f32_e32 v152, v153, v152
	v_div_scale_f32 v153, vcc, 1.0, v151, 1.0
	v_mul_f32_e32 v154, v153, v152
	v_fma_f32 v155, -v147, v154, v153
	v_fmac_f32_e32 v154, v155, v152
	v_fma_f32 v147, -v147, v154, v153
	v_div_fmas_f32 v147, v147, v152, v154
	v_div_fixup_f32 v151, v147, v151, 1.0
	v_div_scale_f32 v147, s[0:1], v150, v150, 1.0
	v_rcp_f32_e32 v152, v147
	v_pk_mul_f32 v[142:143], v[114:115], v[114:115]
	v_and_b32_e32 v105, 0xffff0000, v105
	v_and_b32_e32 v104, 0xffff0000, v104
	v_fma_f32 v153, -v147, v152, 1.0
	v_fmac_f32_e32 v152, v153, v152
	v_div_scale_f32 v153, vcc, 1.0, v150, 1.0
	v_mul_f32_e32 v154, v153, v152
	v_fma_f32 v155, -v147, v154, v153
	v_fmac_f32_e32 v154, v155, v152
	v_fma_f32 v147, -v147, v154, v153
	v_div_fmas_f32 v147, v147, v152, v154
	v_div_fixup_f32 v150, v147, v150, 1.0
	v_mul_f32_e32 v147, 0xbfb8aa3b, v145
	v_exp_f32_e32 v147, v147
	v_pk_mul_f32 v[148:149], v[150:151], v[148:149]
	v_pk_fma_f32 v[142:143], v[118:119], v[118:119], v[142:143]
	v_pk_mul_f32 v[108:109], v[148:149], v[108:109]
	v_pk_add_f32 v[146:147], v[146:147], 1.0 op_sel_hi:[1,0]
	v_add_f32_e32 v136, v142, v136
	v_div_scale_f32 v148, s[0:1], v147, v147, 1.0
	v_rcp_f32_e32 v149, v148
	v_add_f32_e32 v136, v143, v136
	v_fma_f32 v150, -v148, v149, 1.0
	v_fmac_f32_e32 v149, v150, v149
	v_div_scale_f32 v150, vcc, 1.0, v147, 1.0
	v_mul_f32_e32 v151, v150, v149
	v_fma_f32 v152, -v148, v151, v150
	v_fmac_f32_e32 v151, v152, v149
	v_fma_f32 v148, -v148, v151, v150
	v_div_fmas_f32 v148, v148, v149, v151
	v_div_fixup_f32 v147, v148, v147, 1.0
	v_div_scale_f32 v148, s[0:1], v146, v146, 1.0
	v_rcp_f32_e32 v149, v148
	s_nop 0
	v_fma_f32 v150, -v148, v149, 1.0
	v_fmac_f32_e32 v149, v150, v149
	v_div_scale_f32 v150, vcc, 1.0, v146, 1.0
	v_mul_f32_e32 v151, v150, v149
	v_fma_f32 v152, -v148, v151, v150
	v_fmac_f32_e32 v151, v152, v149
	v_fma_f32 v148, -v148, v151, v150
	v_div_fmas_f32 v148, v148, v149, v151
	v_div_fixup_f32 v146, v148, v146, 1.0
	v_lshlrev_b32_e32 v151, 16, v111
	v_lshlrev_b32_e32 v150, 16, v110
	v_pk_mul_f32 v[144:145], v[146:147], v[144:145]
	v_mul_f32_e32 v146, 0xbfb8aa3b, v150
	v_mul_f32_e32 v149, 0xbfb8aa3b, v151
	v_exp_f32_e32 v152, v146
	v_exp_f32_e32 v153, v149
	v_and_b32_e32 v147, 0xffff0000, v111
	v_and_b32_e32 v146, 0xffff0000, v110
	v_mul_f32_e32 v110, 0xbfb8aa3b, v146
	v_pk_add_f32 v[152:153], v[152:153], 1.0 op_sel_hi:[1,0]
	v_exp_f32_e32 v148, v110
	v_div_scale_f32 v149, s[0:1], v153, v153, 1.0
	v_rcp_f32_e32 v154, v149
	v_lshlrev_b32_e32 v111, 16, v107
	v_lshlrev_b32_e32 v110, 16, v106
	v_pk_mul_f32 v[104:105], v[144:145], v[104:105]
	v_fma_f32 v155, -v149, v154, 1.0
	v_fmac_f32_e32 v154, v155, v154
	v_div_scale_f32 v155, vcc, 1.0, v153, 1.0
	v_mul_f32_e32 v156, v155, v154
	v_fma_f32 v157, -v149, v156, v155
	v_fmac_f32_e32 v156, v157, v154
	v_fma_f32 v149, -v149, v156, v155
	v_div_fmas_f32 v149, v149, v154, v156
	v_div_fixup_f32 v153, v149, v153, 1.0
	v_div_scale_f32 v149, s[0:1], v152, v152, 1.0
	v_rcp_f32_e32 v154, v149
	v_pk_mul_f32 v[144:145], v[104:105], v[104:105]
	v_and_b32_e32 v107, 0xffff0000, v107
	v_and_b32_e32 v106, 0xffff0000, v106
	v_fma_f32 v155, -v149, v154, 1.0
	v_fmac_f32_e32 v154, v155, v154
	v_div_scale_f32 v155, vcc, 1.0, v152, 1.0
	v_mul_f32_e32 v156, v155, v154
	v_fma_f32 v157, -v149, v156, v155
	v_fmac_f32_e32 v156, v157, v154
	v_fma_f32 v149, -v149, v156, v155
	v_div_fmas_f32 v149, v149, v154, v156
	v_div_fixup_f32 v152, v149, v152, 1.0
	v_mul_f32_e32 v149, 0xbfb8aa3b, v147
	v_exp_f32_e32 v149, v149
	v_pk_mul_f32 v[150:151], v[152:153], v[150:151]
	v_pk_fma_f32 v[144:145], v[108:109], v[108:109], v[144:145]
	v_pk_mul_f32 v[110:111], v[150:151], v[110:111]
	v_pk_add_f32 v[148:149], v[148:149], 1.0 op_sel_hi:[1,0]
	v_add_f32_e32 v136, v144, v136
	v_div_scale_f32 v150, s[0:1], v149, v149, 1.0
	v_rcp_f32_e32 v151, v150
	v_add_f32_e32 v136, v145, v136
	v_fma_f32 v152, -v150, v151, 1.0
	v_fmac_f32_e32 v151, v152, v151
	v_div_scale_f32 v152, vcc, 1.0, v149, 1.0
	v_mul_f32_e32 v153, v152, v151
	v_fma_f32 v154, -v150, v153, v152
	v_fmac_f32_e32 v153, v154, v151
	v_fma_f32 v150, -v150, v153, v152
	v_div_fmas_f32 v150, v150, v151, v153
	v_div_fixup_f32 v149, v150, v149, 1.0
	v_div_scale_f32 v150, s[0:1], v148, v148, 1.0
	v_rcp_f32_e32 v151, v150
	s_nop 0
	v_fma_f32 v152, -v150, v151, 1.0
	v_fmac_f32_e32 v151, v152, v151
	v_div_scale_f32 v152, vcc, 1.0, v148, 1.0
	v_mul_f32_e32 v153, v152, v151
	v_fma_f32 v154, -v150, v153, v152
	v_fmac_f32_e32 v153, v154, v151
	v_fma_f32 v150, -v150, v153, v152
	v_div_fmas_f32 v150, v150, v151, v153
	v_div_fixup_f32 v148, v150, v148, 1.0
	s_waitcnt vmcnt(8)
; __device__ __forceinline__ float siluf_(float x) { return x * sigmoidf_(x); }
; __device__ __forceinline__ void ssd_gnorm(const Ctx& c, bf16* X2, const bf16* P, const float* g) {
;     ...
;         for (int j = 0; j < 8; ++j) { const v4u y = yr[64 * j], z = zr[64 * j];
; #pragma unroll
;             for (int k = 0; k < 4; ++k) { const float a = bflo(y[k]) * siluf_(bflo(z[k])), b = bfhi(y[k]) * siluf_(bfhi(z[k])); v[j][2 * k] = a; v[j][2 * k + 1] = b; s += a * a + b * b; } }
	v_lshlrev_b32_e32 v153, 16, v101
	v_lshlrev_b32_e32 v152, 16, v100
	v_pk_mul_f32 v[146:147], v[148:149], v[146:147]
	v_mul_f32_e32 v148, 0xbfb8aa3b, v152
	v_mul_f32_e32 v151, 0xbfb8aa3b, v153
	v_exp_f32_e32 v154, v148
	v_exp_f32_e32 v155, v151
	v_and_b32_e32 v149, 0xffff0000, v101
	v_and_b32_e32 v148, 0xffff0000, v100
	v_mul_f32_e32 v100, 0xbfb8aa3b, v148
	v_pk_add_f32 v[154:155], v[154:155], 1.0 op_sel_hi:[1,0]
	v_exp_f32_e32 v150, v100
	v_div_scale_f32 v151, s[0:1], v155, v155, 1.0
	v_rcp_f32_e32 v156, v151
	v_lshlrev_b32_e32 v101, 16, v97
	v_lshlrev_b32_e32 v100, 16, v96
	v_pk_mul_f32 v[106:107], v[146:147], v[106:107]
	v_fma_f32 v157, -v151, v156, 1.0
	v_fmac_f32_e32 v156, v157, v156
	v_div_scale_f32 v157, vcc, 1.0, v155, 1.0
	v_mul_f32_e32 v158, v157, v156
	v_fma_f32 v159, -v151, v158, v157
	v_fmac_f32_e32 v158, v159, v156
	v_fma_f32 v151, -v151, v158, v157
	v_div_fmas_f32 v151, v151, v156, v158
	v_div_fixup_f32 v155, v151, v155, 1.0
	v_div_scale_f32 v151, s[0:1], v154, v154, 1.0
	v_rcp_f32_e32 v156, v151
	v_pk_mul_f32 v[146:147], v[106:107], v[106:107]
	v_and_b32_e32 v97, 0xffff0000, v97
	v_and_b32_e32 v96, 0xffff0000, v96
	v_fma_f32 v157, -v151, v156, 1.0
	v_fmac_f32_e32 v156, v157, v156
	v_div_scale_f32 v157, vcc, 1.0, v154, 1.0
	v_mul_f32_e32 v158, v157, v156
	v_fma_f32 v159, -v151, v158, v157
	v_fmac_f32_e32 v158, v159, v156
	v_fma_f32 v151, -v151, v158, v157
	v_div_fmas_f32 v151, v151, v156, v158
	v_div_fixup_f32 v154, v151, v154, 1.0
	v_mul_f32_e32 v151, 0xbfb8aa3b, v149
	v_exp_f32_e32 v151, v151
	v_pk_mul_f32 v[152:153], v[154:155], v[152:153]
	v_pk_fma_f32 v[146:147], v[110:111], v[110:111], v[146:147]
	v_pk_mul_f32 v[100:101], v[152:153], v[100:101]
	v_pk_add_f32 v[150:151], v[150:151], 1.0 op_sel_hi:[1,0]
	v_add_f32_e32 v136, v146, v136
	v_div_scale_f32 v152, s[0:1], v151, v151, 1.0
	v_rcp_f32_e32 v153, v152
	v_add_f32_e32 v136, v147, v136
	v_fma_f32 v154, -v152, v153, 1.0
	v_fmac_f32_e32 v153, v154, v153
	v_div_scale_f32 v154, vcc, 1.0, v151, 1.0
	v_mul_f32_e32 v155, v154, v153
	v_fma_f32 v156, -v152, v155, v154
	v_fmac_f32_e32 v155, v156, v153
	v_fma_f32 v152, -v152, v155, v154
	v_div_fmas_f32 v152, v152, v153, v155
	v_div_fixup_f32 v151, v152, v151, 1.0
	v_div_scale_f32 v152, s[0:1], v150, v150, 1.0
	v_rcp_f32_e32 v153, v152
	s_nop 0
	v_fma_f32 v154, -v152, v153, 1.0
	v_fmac_f32_e32 v153, v154, v153
	v_div_scale_f32 v154, vcc, 1.0, v150, 1.0
	v_mul_f32_e32 v155, v154, v153
	v_fma_f32 v156, -v152, v155, v154
	v_fmac_f32_e32 v155, v156, v153
	v_fma_f32 v152, -v152, v155, v154
	v_div_fmas_f32 v152, v152, v153, v155
	v_div_fixup_f32 v150, v152, v150, 1.0
	v_lshlrev_b32_e32 v155, 16, v103
	v_lshlrev_b32_e32 v154, 16, v102
	v_pk_mul_f32 v[148:149], v[150:151], v[148:149]
	v_mul_f32_e32 v150, 0xbfb8aa3b, v154
	v_mul_f32_e32 v153, 0xbfb8aa3b, v155
	v_exp_f32_e32 v156, v150
	v_exp_f32_e32 v157, v153
	v_and_b32_e32 v151, 0xffff0000, v103
	v_and_b32_e32 v150, 0xffff0000, v102
	v_mul_f32_e32 v102, 0xbfb8aa3b, v150
	v_pk_add_f32 v[156:157], v[156:157], 1.0 op_sel_hi:[1,0]
	v_exp_f32_e32 v152, v102
	v_div_scale_f32 v153, s[0:1], v157, v157, 1.0
	v_rcp_f32_e32 v158, v153
	v_lshlrev_b32_e32 v103, 16, v99
	v_lshlrev_b32_e32 v102, 16, v98
	v_pk_mul_f32 v[96:97], v[148:149], v[96:97]
	v_fma_f32 v159, -v153, v158, 1.0
	v_fmac_f32_e32 v158, v159, v158
	v_div_scale_f32 v159, vcc, 1.0, v157, 1.0
	v_mul_f32_e32 v160, v159, v158
	v_fma_f32 v161, -v153, v160, v159
	v_fmac_f32_e32 v160, v161, v158
	v_fma_f32 v153, -v153, v160, v159
	v_div_fmas_f32 v153, v153, v158, v160
	v_div_fixup_f32 v157, v153, v157, 1.0
	v_div_scale_f32 v153, s[0:1], v156, v156, 1.0
	v_rcp_f32_e32 v158, v153
	v_pk_mul_f32 v[148:149], v[96:97], v[96:97]
	v_and_b32_e32 v99, 0xffff0000, v99
	v_and_b32_e32 v98, 0xffff0000, v98
	v_fma_f32 v159, -v153, v158, 1.0
	v_fmac_f32_e32 v158, v159, v158
	v_div_scale_f32 v159, vcc, 1.0, v156, 1.0
	v_mul_f32_e32 v160, v159, v158
	v_fma_f32 v161, -v153, v160, v159
	v_fmac_f32_e32 v160, v161, v158
	v_fma_f32 v153, -v153, v160, v159
	v_div_fmas_f32 v153, v153, v158, v160
	v_div_fixup_f32 v156, v153, v156, 1.0
	v_mul_f32_e32 v153, 0xbfb8aa3b, v151
	v_exp_f32_e32 v153, v153
	v_pk_mul_f32 v[154:155], v[156:157], v[154:155]
	v_pk_fma_f32 v[148:149], v[100:101], v[100:101], v[148:149]
	v_pk_mul_f32 v[102:103], v[154:155], v[102:103]
	v_pk_add_f32 v[152:153], v[152:153], 1.0 op_sel_hi:[1,0]
	v_add_f32_e32 v136, v148, v136
	v_div_scale_f32 v154, s[0:1], v153, v153, 1.0
	v_rcp_f32_e32 v155, v154
	v_add_f32_e32 v136, v149, v136
	v_fma_f32 v156, -v154, v155, 1.0
	v_fmac_f32_e32 v155, v156, v155
	v_div_scale_f32 v156, vcc, 1.0, v153, 1.0
	v_mul_f32_e32 v157, v156, v155
	v_fma_f32 v158, -v154, v157, v156
	v_fmac_f32_e32 v157, v158, v155
	v_fma_f32 v154, -v154, v157, v156
	v_div_fmas_f32 v154, v154, v155, v157
	v_div_fixup_f32 v153, v154, v153, 1.0
	v_div_scale_f32 v154, s[0:1], v152, v152, 1.0
	v_rcp_f32_e32 v155, v154
	s_nop 0
	v_fma_f32 v156, -v154, v155, 1.0
	v_fmac_f32_e32 v155, v156, v155
	v_div_scale_f32 v156, vcc, 1.0, v152, 1.0
	v_mul_f32_e32 v157, v156, v155
	v_fma_f32 v158, -v154, v157, v156
	v_fmac_f32_e32 v157, v158, v155
	v_fma_f32 v154, -v154, v157, v156
	v_div_fmas_f32 v154, v154, v155, v157
	v_div_fixup_f32 v152, v154, v152, 1.0
	s_waitcnt vmcnt(6)
; __device__ __forceinline__ float siluf_(float x) { return x * sigmoidf_(x); }
; __device__ __forceinline__ void ssd_gnorm(const Ctx& c, bf16* X2, const bf16* P, const float* g) {
;     ...
;         for (int j = 0; j < 8; ++j) { const v4u y = yr[64 * j], z = zr[64 * j];
; #pragma unroll
;             for (int k = 0; k < 4; ++k) { const float a = bflo(y[k]) * siluf_(bflo(z[k])), b = bfhi(y[k]) * siluf_(bfhi(z[k])); v[j][2 * k] = a; v[j][2 * k + 1] = b; s += a * a + b * b; } }
	v_lshlrev_b32_e32 v157, 16, v93
	v_lshlrev_b32_e32 v156, 16, v92
	v_pk_mul_f32 v[150:151], v[152:153], v[150:151]
	v_mul_f32_e32 v152, 0xbfb8aa3b, v156
	v_mul_f32_e32 v155, 0xbfb8aa3b, v157
	v_exp_f32_e32 v158, v152
	v_exp_f32_e32 v159, v155
	v_and_b32_e32 v153, 0xffff0000, v93
	v_and_b32_e32 v152, 0xffff0000, v92
	v_mul_f32_e32 v92, 0xbfb8aa3b, v152
	v_pk_add_f32 v[158:159], v[158:159], 1.0 op_sel_hi:[1,0]
	v_exp_f32_e32 v154, v92
	v_div_scale_f32 v155, s[0:1], v159, v159, 1.0
	v_rcp_f32_e32 v160, v155
	v_lshlrev_b32_e32 v93, 16, v89
	v_lshlrev_b32_e32 v92, 16, v88
	v_pk_mul_f32 v[98:99], v[150:151], v[98:99]
	v_fma_f32 v161, -v155, v160, 1.0
	v_fmac_f32_e32 v160, v161, v160
	v_div_scale_f32 v161, vcc, 1.0, v159, 1.0
	v_mul_f32_e32 v162, v161, v160
	v_fma_f32 v163, -v155, v162, v161
	v_fmac_f32_e32 v162, v163, v160
	v_fma_f32 v155, -v155, v162, v161
	v_div_fmas_f32 v155, v155, v160, v162
	v_div_fixup_f32 v159, v155, v159, 1.0
	v_div_scale_f32 v155, s[0:1], v158, v158, 1.0
	v_rcp_f32_e32 v160, v155
	v_pk_mul_f32 v[150:151], v[98:99], v[98:99]
	v_and_b32_e32 v89, 0xffff0000, v89
	v_and_b32_e32 v88, 0xffff0000, v88
	v_fma_f32 v161, -v155, v160, 1.0
	v_fmac_f32_e32 v160, v161, v160
	v_div_scale_f32 v161, vcc, 1.0, v158, 1.0
	v_mul_f32_e32 v162, v161, v160
	v_fma_f32 v163, -v155, v162, v161
	v_fmac_f32_e32 v162, v163, v160
	v_fma_f32 v155, -v155, v162, v161
	v_div_fmas_f32 v155, v155, v160, v162
	v_div_fixup_f32 v158, v155, v158, 1.0
	v_mul_f32_e32 v155, 0xbfb8aa3b, v153
	v_exp_f32_e32 v155, v155
	v_pk_mul_f32 v[156:157], v[158:159], v[156:157]
	v_pk_fma_f32 v[150:151], v[102:103], v[102:103], v[150:151]
	v_pk_mul_f32 v[92:93], v[156:157], v[92:93]
	v_pk_add_f32 v[154:155], v[154:155], 1.0 op_sel_hi:[1,0]
	v_add_f32_e32 v136, v150, v136
	v_div_scale_f32 v156, s[0:1], v155, v155, 1.0
	v_rcp_f32_e32 v157, v156
	v_add_f32_e32 v136, v151, v136
	v_fma_f32 v158, -v156, v157, 1.0
	v_fmac_f32_e32 v157, v158, v157
	v_div_scale_f32 v158, vcc, 1.0, v155, 1.0
	v_mul_f32_e32 v159, v158, v157
	v_fma_f32 v160, -v156, v159, v158
	v_fmac_f32_e32 v159, v160, v157
	v_fma_f32 v156, -v156, v159, v158
	v_div_fmas_f32 v156, v156, v157, v159
	v_div_fixup_f32 v155, v156, v155, 1.0
	v_div_scale_f32 v156, s[0:1], v154, v154, 1.0
	v_rcp_f32_e32 v157, v156
	s_nop 0
	v_fma_f32 v158, -v156, v157, 1.0
	v_fmac_f32_e32 v157, v158, v157
	v_div_scale_f32 v158, vcc, 1.0, v154, 1.0
	v_mul_f32_e32 v159, v158, v157
	v_fma_f32 v160, -v156, v159, v158
	v_fmac_f32_e32 v159, v160, v157
	v_fma_f32 v156, -v156, v159, v158
	v_div_fmas_f32 v156, v156, v157, v159
	v_div_fixup_f32 v154, v156, v154, 1.0
	v_lshlrev_b32_e32 v159, 16, v95
	v_lshlrev_b32_e32 v158, 16, v94
	v_pk_mul_f32 v[152:153], v[154:155], v[152:153]
	v_mul_f32_e32 v154, 0xbfb8aa3b, v158
	v_mul_f32_e32 v157, 0xbfb8aa3b, v159
	v_exp_f32_e32 v160, v154
	v_exp_f32_e32 v161, v157
	v_and_b32_e32 v155, 0xffff0000, v95
	v_and_b32_e32 v154, 0xffff0000, v94
	v_mul_f32_e32 v94, 0xbfb8aa3b, v154
	v_pk_add_f32 v[160:161], v[160:161], 1.0 op_sel_hi:[1,0]
	v_exp_f32_e32 v156, v94
	v_div_scale_f32 v157, s[0:1], v161, v161, 1.0
	v_rcp_f32_e32 v162, v157
	v_lshlrev_b32_e32 v95, 16, v91
	v_lshlrev_b32_e32 v94, 16, v90
	v_pk_mul_f32 v[88:89], v[152:153], v[88:89]
	v_fma_f32 v163, -v157, v162, 1.0
	v_fmac_f32_e32 v162, v163, v162
	v_div_scale_f32 v163, vcc, 1.0, v161, 1.0
	v_mul_f32_e32 v165, v163, v162
	v_fma_f32 v166, -v157, v165, v163
	v_fmac_f32_e32 v165, v166, v162
	v_fma_f32 v157, -v157, v165, v163
	v_div_fmas_f32 v157, v157, v162, v165
	v_div_fixup_f32 v161, v157, v161, 1.0
	v_div_scale_f32 v157, s[0:1], v160, v160, 1.0
	v_rcp_f32_e32 v162, v157
	v_pk_mul_f32 v[152:153], v[88:89], v[88:89]
	v_and_b32_e32 v91, 0xffff0000, v91
	v_and_b32_e32 v90, 0xffff0000, v90
	v_fma_f32 v163, -v157, v162, 1.0
	v_fmac_f32_e32 v162, v163, v162
	v_div_scale_f32 v163, vcc, 1.0, v160, 1.0
	v_mul_f32_e32 v165, v163, v162
	v_fma_f32 v166, -v157, v165, v163
	v_fmac_f32_e32 v165, v166, v162
	v_fma_f32 v157, -v157, v165, v163
	v_div_fmas_f32 v157, v157, v162, v165
	v_div_fixup_f32 v160, v157, v160, 1.0
	v_mul_f32_e32 v157, 0xbfb8aa3b, v155
	v_exp_f32_e32 v157, v157
	v_pk_mul_f32 v[158:159], v[160:161], v[158:159]
	v_pk_fma_f32 v[152:153], v[92:93], v[92:93], v[152:153]
	v_pk_mul_f32 v[94:95], v[158:159], v[94:95]
	v_pk_add_f32 v[156:157], v[156:157], 1.0 op_sel_hi:[1,0]
	v_add_f32_e32 v136, v152, v136
	v_div_scale_f32 v158, s[0:1], v157, v157, 1.0
	v_rcp_f32_e32 v159, v158
	v_add_f32_e32 v136, v153, v136
	v_fma_f32 v160, -v158, v159, 1.0
	v_fmac_f32_e32 v159, v160, v159
	v_div_scale_f32 v160, vcc, 1.0, v157, 1.0
	v_mul_f32_e32 v161, v160, v159
	v_fma_f32 v162, -v158, v161, v160
	v_fmac_f32_e32 v161, v162, v159
	v_fma_f32 v158, -v158, v161, v160
	v_div_fmas_f32 v158, v158, v159, v161
	v_div_fixup_f32 v157, v158, v157, 1.0
	v_div_scale_f32 v158, s[0:1], v156, v156, 1.0
	v_rcp_f32_e32 v159, v158
	s_nop 0
	v_fma_f32 v160, -v158, v159, 1.0
	v_fmac_f32_e32 v159, v160, v159
	v_div_scale_f32 v160, vcc, 1.0, v156, 1.0
	v_mul_f32_e32 v161, v160, v159
	v_fma_f32 v162, -v158, v161, v160
	v_fmac_f32_e32 v161, v162, v159
	v_fma_f32 v158, -v158, v161, v160
	v_div_fmas_f32 v158, v158, v159, v161
	v_div_fixup_f32 v156, v158, v156, 1.0
	s_waitcnt vmcnt(4)
; __device__ __forceinline__ float siluf_(float x) { return x * sigmoidf_(x); }
; __device__ __forceinline__ void ssd_gnorm(const Ctx& c, bf16* X2, const bf16* P, const float* g) {
;     ...
;         for (int j = 0; j < 8; ++j) { const v4u y = yr[64 * j], z = zr[64 * j];
; #pragma unroll
;             for (int k = 0; k < 4; ++k) { const float a = bflo(y[k]) * siluf_(bflo(z[k])), b = bfhi(y[k]) * siluf_(bfhi(z[k])); v[j][2 * k] = a; v[j][2 * k + 1] = b; s += a * a + b * b; } }
	v_lshlrev_b32_e32 v161, 16, v85
	v_lshlrev_b32_e32 v160, 16, v84
	v_pk_mul_f32 v[154:155], v[156:157], v[154:155]
	v_mul_f32_e32 v156, 0xbfb8aa3b, v160
	v_mul_f32_e32 v159, 0xbfb8aa3b, v161
	v_exp_f32_e32 v162, v156
	v_exp_f32_e32 v163, v159
	v_and_b32_e32 v157, 0xffff0000, v85
	v_and_b32_e32 v156, 0xffff0000, v84
	v_mul_f32_e32 v84, 0xbfb8aa3b, v156
	v_pk_add_f32 v[162:163], v[162:163], 1.0 op_sel_hi:[1,0]
	v_exp_f32_e32 v158, v84
	v_div_scale_f32 v159, s[0:1], v163, v163, 1.0
	v_rcp_f32_e32 v165, v159
	v_lshlrev_b32_e32 v85, 16, v81
	v_lshlrev_b32_e32 v84, 16, v80
	v_pk_mul_f32 v[90:91], v[154:155], v[90:91]
	v_fma_f32 v166, -v159, v165, 1.0
	v_fmac_f32_e32 v165, v166, v165
	v_div_scale_f32 v166, vcc, 1.0, v163, 1.0
	v_mul_f32_e32 v168, v166, v165
	v_fma_f32 v169, -v159, v168, v166
	v_fmac_f32_e32 v168, v169, v165
	v_fma_f32 v159, -v159, v168, v166
	v_div_fmas_f32 v159, v159, v165, v168
	v_div_fixup_f32 v163, v159, v163, 1.0
	v_div_scale_f32 v159, s[0:1], v162, v162, 1.0
	v_rcp_f32_e32 v165, v159
	v_pk_mul_f32 v[154:155], v[90:91], v[90:91]
	v_and_b32_e32 v81, 0xffff0000, v81
	v_and_b32_e32 v80, 0xffff0000, v80
	v_fma_f32 v166, -v159, v165, 1.0
	v_fmac_f32_e32 v165, v166, v165
	v_div_scale_f32 v166, vcc, 1.0, v162, 1.0
	v_mul_f32_e32 v168, v166, v165
	v_fma_f32 v169, -v159, v168, v166
	v_fmac_f32_e32 v168, v169, v165
	v_fma_f32 v159, -v159, v168, v166
	v_div_fmas_f32 v159, v159, v165, v168
	v_div_fixup_f32 v162, v159, v162, 1.0
	v_mul_f32_e32 v159, 0xbfb8aa3b, v157
	v_exp_f32_e32 v159, v159
	v_pk_mul_f32 v[160:161], v[162:163], v[160:161]
	v_pk_fma_f32 v[154:155], v[94:95], v[94:95], v[154:155]
	v_pk_mul_f32 v[84:85], v[160:161], v[84:85]
	v_pk_add_f32 v[158:159], v[158:159], 1.0 op_sel_hi:[1,0]
	v_add_f32_e32 v136, v154, v136
	v_div_scale_f32 v160, s[0:1], v159, v159, 1.0
	v_rcp_f32_e32 v161, v160
	v_add_f32_e32 v136, v155, v136
	v_fma_f32 v162, -v160, v161, 1.0
	v_fmac_f32_e32 v161, v162, v161
	v_div_scale_f32 v162, vcc, 1.0, v159, 1.0
	v_mul_f32_e32 v163, v162, v161
	v_fma_f32 v165, -v160, v163, v162
	v_fmac_f32_e32 v163, v165, v161
	v_fma_f32 v160, -v160, v163, v162
	v_div_fmas_f32 v160, v160, v161, v163
	v_div_fixup_f32 v159, v160, v159, 1.0
	v_div_scale_f32 v160, s[0:1], v158, v158, 1.0
	v_rcp_f32_e32 v161, v160
	s_nop 0
	v_fma_f32 v162, -v160, v161, 1.0
	v_fmac_f32_e32 v161, v162, v161
	v_div_scale_f32 v162, vcc, 1.0, v158, 1.0
	v_mul_f32_e32 v163, v162, v161
	v_fma_f32 v165, -v160, v163, v162
	v_fmac_f32_e32 v163, v165, v161
	v_fma_f32 v160, -v160, v163, v162
	v_div_fmas_f32 v160, v160, v161, v163
	v_div_fixup_f32 v158, v160, v158, 1.0
	v_lshlrev_b32_e32 v163, 16, v87
	v_lshlrev_b32_e32 v162, 16, v86
	v_pk_mul_f32 v[156:157], v[158:159], v[156:157]
	v_mul_f32_e32 v158, 0xbfb8aa3b, v162
	v_mul_f32_e32 v161, 0xbfb8aa3b, v163
	v_exp_f32_e32 v168, v158
	v_exp_f32_e32 v169, v161
	v_and_b32_e32 v159, 0xffff0000, v87
	v_and_b32_e32 v158, 0xffff0000, v86
	v_mul_f32_e32 v86, 0xbfb8aa3b, v158
	v_pk_add_f32 v[168:169], v[168:169], 1.0 op_sel_hi:[1,0]
	v_exp_f32_e32 v160, v86
	v_div_scale_f32 v161, s[0:1], v169, v169, 1.0
	v_rcp_f32_e32 v165, v161
	v_lshlrev_b32_e32 v87, 16, v83
	v_lshlrev_b32_e32 v86, 16, v82
	v_pk_mul_f32 v[80:81], v[156:157], v[80:81]
	v_fma_f32 v166, -v161, v165, 1.0
	v_fmac_f32_e32 v165, v166, v165
	v_div_scale_f32 v166, vcc, 1.0, v169, 1.0
	v_mul_f32_e32 v170, v166, v165
	v_fma_f32 v171, -v161, v170, v166
	v_fmac_f32_e32 v170, v171, v165
	v_fma_f32 v161, -v161, v170, v166
	v_div_fmas_f32 v161, v161, v165, v170
	v_div_fixup_f32 v169, v161, v169, 1.0
	v_div_scale_f32 v161, s[0:1], v168, v168, 1.0
	v_rcp_f32_e32 v165, v161
	v_pk_mul_f32 v[156:157], v[80:81], v[80:81]
	v_and_b32_e32 v83, 0xffff0000, v83
	v_and_b32_e32 v82, 0xffff0000, v82
	v_fma_f32 v166, -v161, v165, 1.0
	v_fmac_f32_e32 v165, v166, v165
	v_div_scale_f32 v166, vcc, 1.0, v168, 1.0
	v_mul_f32_e32 v170, v166, v165
	v_fma_f32 v171, -v161, v170, v166
	v_fmac_f32_e32 v170, v171, v165
	v_fma_f32 v161, -v161, v170, v166
	v_div_fmas_f32 v161, v161, v165, v170
	v_div_fixup_f32 v168, v161, v168, 1.0
	v_mul_f32_e32 v161, 0xbfb8aa3b, v159
	v_exp_f32_e32 v161, v161
	v_pk_mul_f32 v[162:163], v[168:169], v[162:163]
	s_waitcnt vmcnt(2)
	v_lshlrev_b32_e32 v169, 16, v77
	v_pk_mul_f32 v[86:87], v[162:163], v[86:87]
	v_pk_add_f32 v[160:161], v[160:161], 1.0 op_sel_hi:[1,0]
	v_pk_fma_f32 v[156:157], v[84:85], v[84:85], v[156:157]
	v_div_scale_f32 v162, s[0:1], v161, v161, 1.0
	v_rcp_f32_e32 v163, v162
	v_add_f32_e32 v136, v156, v136
	v_add_f32_e32 v136, v157, v136
	v_fma_f32 v165, -v162, v163, 1.0
	v_fmac_f32_e32 v163, v165, v163
	v_div_scale_f32 v165, vcc, 1.0, v161, 1.0
	v_mul_f32_e32 v166, v165, v163
	v_fma_f32 v168, -v162, v166, v165
	v_fmac_f32_e32 v166, v168, v163
	v_fma_f32 v162, -v162, v166, v165
	v_div_fmas_f32 v162, v162, v163, v166
	v_div_fixup_f32 v161, v162, v161, 1.0
	v_div_scale_f32 v162, s[0:1], v160, v160, 1.0
	v_rcp_f32_e32 v163, v162
	s_nop 0
	v_fma_f32 v165, -v162, v163, 1.0
	v_fmac_f32_e32 v163, v165, v163
	v_div_scale_f32 v165, vcc, 1.0, v160, 1.0
	v_mul_f32_e32 v166, v165, v163
	v_fma_f32 v168, -v162, v166, v165
	v_fmac_f32_e32 v166, v168, v163
	v_fma_f32 v162, -v162, v166, v165
	v_div_fmas_f32 v162, v162, v163, v166
	v_div_fixup_f32 v160, v162, v160, 1.0
	v_lshlrev_b32_e32 v168, 16, v76
	v_pk_mul_f32 v[158:159], v[160:161], v[158:159]
	v_mul_f32_e32 v160, 0xbfb8aa3b, v168
	v_mul_f32_e32 v163, 0xbfb8aa3b, v169
	v_exp_f32_e32 v170, v160
	v_exp_f32_e32 v171, v163
	v_and_b32_e32 v161, 0xffff0000, v77
	v_and_b32_e32 v160, 0xffff0000, v76
	v_mul_f32_e32 v76, 0xbfb8aa3b, v160
	v_pk_add_f32 v[170:171], v[170:171], 1.0 op_sel_hi:[1,0]
	v_exp_f32_e32 v162, v76
; __device__ __forceinline__ float siluf_(float x) { return x * sigmoidf_(x); }
; __device__ __forceinline__ void ssd_gnorm(const Ctx& c, bf16* X2, const bf16* P, const float* g) {
;     ...
;         for (int j = 0; j < 8; ++j) { const v4u y = yr[64 * j], z = zr[64 * j];
; #pragma unroll
;             for (int k = 0; k < 4; ++k) { const float a = bflo(y[k]) * siluf_(bflo(z[k])), b = bfhi(y[k]) * siluf_(bfhi(z[k])); v[j][2 * k] = a; v[j][2 * k + 1] = b; s += a * a + b * b; } }
	v_div_scale_f32 v163, s[0:1], v171, v171, 1.0
	v_rcp_f32_e32 v165, v163
	v_lshlrev_b32_e32 v77, 16, v73
	v_lshlrev_b32_e32 v76, 16, v72
	v_pk_mul_f32 v[82:83], v[158:159], v[82:83]
	v_fma_f32 v166, -v163, v165, 1.0
	v_fmac_f32_e32 v165, v166, v165
	v_div_scale_f32 v166, vcc, 1.0, v171, 1.0
	v_mul_f32_e32 v172, v166, v165
	v_fma_f32 v173, -v163, v172, v166
	v_fmac_f32_e32 v172, v173, v165
	v_fma_f32 v163, -v163, v172, v166
	v_div_fmas_f32 v163, v163, v165, v172
	v_div_fixup_f32 v171, v163, v171, 1.0
	v_div_scale_f32 v163, s[0:1], v170, v170, 1.0
	v_rcp_f32_e32 v165, v163
	v_pk_mul_f32 v[158:159], v[82:83], v[82:83]
	v_and_b32_e32 v73, 0xffff0000, v73
	v_and_b32_e32 v72, 0xffff0000, v72
	v_fma_f32 v166, -v163, v165, 1.0
	v_fmac_f32_e32 v165, v166, v165
	v_div_scale_f32 v166, vcc, 1.0, v170, 1.0
	v_mul_f32_e32 v172, v166, v165
	v_fma_f32 v173, -v163, v172, v166
	v_fmac_f32_e32 v172, v173, v165
	v_fma_f32 v163, -v163, v172, v166
	v_div_fmas_f32 v163, v163, v165, v172
	v_div_fixup_f32 v170, v163, v170, 1.0
	v_mul_f32_e32 v163, 0xbfb8aa3b, v161
	v_exp_f32_e32 v163, v163
	v_pk_mul_f32 v[168:169], v[170:171], v[168:169]
	v_lshlrev_b32_e32 v171, 16, v79
	v_pk_mul_f32 v[76:77], v[168:169], v[76:77]
	v_pk_add_f32 v[162:163], v[162:163], 1.0 op_sel_hi:[1,0]
	v_pk_fma_f32 v[158:159], v[86:87], v[86:87], v[158:159]
	v_div_scale_f32 v165, s[0:1], v163, v163, 1.0
	v_rcp_f32_e32 v166, v165
	v_add_f32_e32 v136, v158, v136
	v_add_f32_e32 v136, v159, v136
	v_fma_f32 v168, -v165, v166, 1.0
	v_fmac_f32_e32 v166, v168, v166
	v_div_scale_f32 v168, vcc, 1.0, v163, 1.0
	v_mul_f32_e32 v169, v168, v166
	v_fma_f32 v170, -v165, v169, v168
	v_fmac_f32_e32 v169, v170, v166
	v_fma_f32 v165, -v165, v169, v168
	v_div_fmas_f32 v165, v165, v166, v169
	v_div_fixup_f32 v163, v165, v163, 1.0
	v_div_scale_f32 v165, s[0:1], v162, v162, 1.0
	v_rcp_f32_e32 v166, v165
	s_nop 0
	v_fma_f32 v168, -v165, v166, 1.0
	v_fmac_f32_e32 v166, v168, v166
	v_div_scale_f32 v168, vcc, 1.0, v162, 1.0
	v_mul_f32_e32 v169, v168, v166
	v_fma_f32 v170, -v165, v169, v168
	v_fmac_f32_e32 v169, v170, v166
	v_fma_f32 v165, -v165, v169, v168
	v_div_fmas_f32 v165, v165, v166, v169
	v_div_fixup_f32 v162, v165, v162, 1.0
	v_lshlrev_b32_e32 v170, 16, v78
	v_pk_mul_f32 v[160:161], v[162:163], v[160:161]
	v_mul_f32_e32 v162, 0xbfb8aa3b, v170
	v_mul_f32_e32 v165, 0xbfb8aa3b, v171
	v_exp_f32_e32 v172, v162
	v_exp_f32_e32 v173, v165
	v_and_b32_e32 v163, 0xffff0000, v79
	v_and_b32_e32 v162, 0xffff0000, v78
	v_mul_f32_e32 v78, 0xbfb8aa3b, v162
	v_pk_add_f32 v[172:173], v[172:173], 1.0 op_sel_hi:[1,0]
	v_exp_f32_e32 v168, v78
	v_div_scale_f32 v165, s[0:1], v173, v173, 1.0
	v_rcp_f32_e32 v166, v165
	v_lshlrev_b32_e32 v79, 16, v75
	v_lshlrev_b32_e32 v78, 16, v74
	v_pk_mul_f32 v[72:73], v[160:161], v[72:73]
	v_fma_f32 v169, -v165, v166, 1.0
	v_fmac_f32_e32 v166, v169, v166
	v_div_scale_f32 v169, vcc, 1.0, v173, 1.0
	v_mul_f32_e32 v180, v169, v166
	v_fma_f32 v181, -v165, v180, v169
	v_fmac_f32_e32 v180, v181, v166
	v_fma_f32 v165, -v165, v180, v169
	v_div_fmas_f32 v165, v165, v166, v180
	v_div_fixup_f32 v173, v165, v173, 1.0
	v_div_scale_f32 v165, s[0:1], v172, v172, 1.0
	v_rcp_f32_e32 v166, v165
	v_pk_mul_f32 v[160:161], v[72:73], v[72:73]
	v_and_b32_e32 v75, 0xffff0000, v75
	v_and_b32_e32 v74, 0xffff0000, v74
	v_fma_f32 v169, -v165, v166, 1.0
	v_fmac_f32_e32 v166, v169, v166
	v_div_scale_f32 v169, vcc, 1.0, v172, 1.0
	v_mul_f32_e32 v180, v169, v166
	v_fma_f32 v181, -v165, v180, v169
	v_fmac_f32_e32 v180, v181, v166
	v_fma_f32 v165, -v165, v180, v169
	v_div_fmas_f32 v165, v165, v166, v180
	v_div_fixup_f32 v172, v165, v172, 1.0
	v_mul_f32_e32 v165, 0xbfb8aa3b, v163
	v_exp_f32_e32 v169, v165
	v_pk_mul_f32 v[170:171], v[172:173], v[170:171]
	s_waitcnt vmcnt(0)
	v_lshlrev_b32_e32 v173, 16, v69
	v_pk_mul_f32 v[78:79], v[170:171], v[78:79]
	v_pk_add_f32 v[168:169], v[168:169], 1.0 op_sel_hi:[1,0]
	v_pk_fma_f32 v[160:161], v[76:77], v[76:77], v[160:161]
	v_div_scale_f32 v165, s[0:1], v169, v169, 1.0
	v_rcp_f32_e32 v166, v165
	v_add_f32_e32 v136, v160, v136
	v_add_f32_e32 v136, v161, v136
	v_fma_f32 v170, -v165, v166, 1.0
	v_fmac_f32_e32 v166, v170, v166
	v_div_scale_f32 v170, vcc, 1.0, v169, 1.0
	v_mul_f32_e32 v171, v170, v166
	v_fma_f32 v172, -v165, v171, v170
	v_fmac_f32_e32 v171, v172, v166
	v_fma_f32 v165, -v165, v171, v170
	v_div_fmas_f32 v165, v165, v166, v171
	v_div_fixup_f32 v169, v165, v169, 1.0
	v_div_scale_f32 v165, s[0:1], v168, v168, 1.0
	v_rcp_f32_e32 v166, v165
	s_nop 0
	v_fma_f32 v170, -v165, v166, 1.0
	v_fmac_f32_e32 v166, v170, v166
	v_div_scale_f32 v170, vcc, 1.0, v168, 1.0
	v_mul_f32_e32 v171, v170, v166
	v_fma_f32 v172, -v165, v171, v170
	v_fmac_f32_e32 v171, v172, v166
	v_fma_f32 v165, -v165, v171, v170
	v_div_fmas_f32 v165, v165, v166, v171
	v_lshlrev_b32_e32 v172, 16, v68
	v_div_fixup_f32 v168, v165, v168, 1.0
	v_mul_f32_e32 v165, 0xbfb8aa3b, v172
	v_exp_f32_e32 v180, v165
	v_mul_f32_e32 v165, 0xbfb8aa3b, v173
	v_exp_f32_e32 v181, v165
	v_pk_mul_f32 v[162:163], v[168:169], v[162:163]
	v_and_b32_e32 v169, 0xffff0000, v69
	v_and_b32_e32 v168, 0xffff0000, v68
	v_pk_add_f32 v[180:181], v[180:181], 1.0 op_sel_hi:[1,0]
	v_mul_f32_e32 v68, 0xbfb8aa3b, v168
	v_div_scale_f32 v165, s[0:1], v181, v181, 1.0
	v_rcp_f32_e32 v166, v165
	v_exp_f32_e32 v170, v68
	v_lshlrev_b32_e32 v69, 16, v65
	v_lshlrev_b32_e32 v68, 16, v64
	v_fma_f32 v171, -v165, v166, 1.0
	v_fmac_f32_e32 v166, v171, v166
	v_div_scale_f32 v171, vcc, 1.0, v181, 1.0
	v_mul_f32_e32 v182, v171, v166
	v_fma_f32 v183, -v165, v182, v171
	v_fmac_f32_e32 v182, v183, v166
	v_fma_f32 v165, -v165, v182, v171
	v_div_fmas_f32 v165, v165, v166, v182
; __device__ __forceinline__ float siluf_(float x) { return x * sigmoidf_(x); }
; __device__ __forceinline__ float wave_sum(float v) {
; #pragma unroll
;     for (int o = 1; o < 64; o <<= 1) v += __shfl_xor(v, o);
;     return v;
; __device__ __forceinline__ void ssd_gnorm(const Ctx& c, bf16* X2, const bf16* P, const float* g) {
;     ...
;         for (int j = 0; j < 8; ++j) { const v4u y = yr[64 * j], z = zr[64 * j];
; #pragma unroll
;             for (int k = 0; k < 4; ++k) { const float a = bflo(y[k]) * siluf_(bflo(z[k])), b = bfhi(y[k]) * siluf_(bfhi(z[k])); v[j][2 * k] = a; v[j][2 * k + 1] = b; s += a * a + b * b; } }
;         const float rs = rsqrtf(wave_sum(s) * (1.f / 4096.f) + EPS);
	v_div_fixup_f32 v181, v165, v181, 1.0
	v_div_scale_f32 v165, s[0:1], v180, v180, 1.0
	v_rcp_f32_e32 v166, v165
	v_pk_mul_f32 v[74:75], v[162:163], v[74:75]
	v_and_b32_e32 v65, 0xffff0000, v65
	v_pk_mul_f32 v[162:163], v[74:75], v[74:75]
	v_fma_f32 v171, -v165, v166, 1.0
	v_fmac_f32_e32 v166, v171, v166
	v_div_scale_f32 v171, vcc, 1.0, v180, 1.0
	v_mul_f32_e32 v182, v171, v166
	v_fma_f32 v183, -v165, v182, v171
	v_fmac_f32_e32 v182, v183, v166
	v_fma_f32 v165, -v165, v182, v171
	v_div_fmas_f32 v165, v165, v166, v182
	v_div_fixup_f32 v180, v165, v180, 1.0
	v_mul_f32_e32 v165, 0xbfb8aa3b, v169
	v_exp_f32_e32 v171, v165
	v_pk_mul_f32 v[172:173], v[180:181], v[172:173]
	v_lshlrev_b32_e32 v181, 16, v71
	v_pk_mul_f32 v[68:69], v[172:173], v[68:69]
	v_pk_add_f32 v[170:171], v[170:171], 1.0 op_sel_hi:[1,0]
	v_and_b32_e32 v64, 0xffff0000, v64
	v_div_scale_f32 v165, s[0:1], v171, v171, 1.0
	v_rcp_f32_e32 v166, v165
	v_pk_fma_f32 v[162:163], v[78:79], v[78:79], v[162:163]
	v_fma_f32 v172, -v165, v166, 1.0
	v_fmac_f32_e32 v166, v172, v166
	v_div_scale_f32 v172, vcc, 1.0, v171, 1.0
	v_mul_f32_e32 v173, v172, v166
	v_fma_f32 v180, -v165, v173, v172
	v_fmac_f32_e32 v173, v180, v166
	v_fma_f32 v165, -v165, v173, v172
	v_div_fmas_f32 v165, v165, v166, v173
	v_div_fixup_f32 v171, v165, v171, 1.0
	v_div_scale_f32 v165, s[0:1], v170, v170, 1.0
	v_rcp_f32_e32 v166, v165
	v_add_f32_e32 v136, v162, v136
	v_add_f32_e32 v136, v163, v136
	v_fma_f32 v172, -v165, v166, 1.0
	v_fmac_f32_e32 v166, v172, v166
	v_div_scale_f32 v172, vcc, 1.0, v170, 1.0
	v_mul_f32_e32 v173, v172, v166
	v_fma_f32 v180, -v165, v173, v172
	v_fmac_f32_e32 v173, v180, v166
	v_fma_f32 v165, -v165, v173, v172
	v_div_fmas_f32 v165, v165, v166, v173
	v_lshlrev_b32_e32 v180, 16, v70
	v_div_fixup_f32 v170, v165, v170, 1.0
	v_mul_f32_e32 v165, 0xbfb8aa3b, v180
	v_exp_f32_e32 v182, v165
	v_mul_f32_e32 v165, 0xbfb8aa3b, v181
	v_exp_f32_e32 v183, v165
	v_pk_mul_f32 v[168:169], v[170:171], v[168:169]
	v_and_b32_e32 v171, 0xffff0000, v71
	v_and_b32_e32 v170, 0xffff0000, v70
	v_pk_add_f32 v[182:183], v[182:183], 1.0 op_sel_hi:[1,0]
	v_mul_f32_e32 v70, 0xbfb8aa3b, v170
	v_div_scale_f32 v165, s[0:1], v183, v183, 1.0
	v_rcp_f32_e32 v166, v165
	v_exp_f32_e32 v172, v70
	v_lshlrev_b32_e32 v71, 16, v67
	v_lshlrev_b32_e32 v70, 16, v66
	v_fma_f32 v173, -v165, v166, 1.0
	v_fmac_f32_e32 v166, v173, v166
	v_div_scale_f32 v173, vcc, 1.0, v183, 1.0
	v_mul_f32_e32 v184, v173, v166
	v_fma_f32 v185, -v165, v184, v173
	v_fmac_f32_e32 v184, v185, v166
	v_fma_f32 v165, -v165, v184, v173
	v_div_fmas_f32 v165, v165, v166, v184
	v_div_fixup_f32 v183, v165, v183, 1.0
	v_div_scale_f32 v165, s[0:1], v182, v182, 1.0
	v_rcp_f32_e32 v166, v165
	v_pk_mul_f32 v[64:65], v[168:169], v[64:65]
	v_and_b32_e32 v67, 0xffff0000, v67
	v_pk_mul_f32 v[168:169], v[64:65], v[64:65]
	v_fma_f32 v173, -v165, v166, 1.0
	v_fmac_f32_e32 v166, v173, v166
	v_div_scale_f32 v173, vcc, 1.0, v182, 1.0
	v_mul_f32_e32 v184, v173, v166
	v_fma_f32 v185, -v165, v184, v173
	v_fmac_f32_e32 v184, v185, v166
	v_fma_f32 v165, -v165, v184, v173
	v_div_fmas_f32 v165, v165, v166, v184
	v_div_fixup_f32 v182, v165, v182, 1.0
	v_mul_f32_e32 v165, 0xbfb8aa3b, v171
	v_exp_f32_e32 v173, v165
	v_pk_mul_f32 v[180:181], v[182:183], v[180:181]
	v_and_b32_e32 v66, 0xffff0000, v66
	v_pk_mul_f32 v[70:71], v[180:181], v[70:71]
	v_pk_add_f32 v[172:173], v[172:173], 1.0 op_sel_hi:[1,0]
	v_pk_fma_f32 v[168:169], v[68:69], v[68:69], v[168:169]
	v_div_scale_f32 v165, s[0:1], v173, v173, 1.0
	v_rcp_f32_e32 v166, v165
	v_add_f32_e32 v136, v168, v136
	v_add_f32_e32 v136, v169, v136
	v_fma_f32 v180, -v165, v166, 1.0
	v_fmac_f32_e32 v166, v180, v166
	v_div_scale_f32 v180, vcc, 1.0, v173, 1.0
	v_mul_f32_e32 v181, v180, v166
	v_fma_f32 v182, -v165, v181, v180
	v_fmac_f32_e32 v181, v182, v166
	v_fma_f32 v165, -v165, v181, v180
	v_div_fmas_f32 v165, v165, v166, v181
	v_div_fixup_f32 v173, v165, v173, 1.0
	v_div_scale_f32 v165, s[0:1], v172, v172, 1.0
	v_rcp_f32_e32 v166, v165
	s_nop 0
	v_fma_f32 v180, -v165, v166, 1.0
	v_fmac_f32_e32 v166, v180, v166
	v_div_scale_f32 v180, vcc, 1.0, v172, 1.0
	v_mul_f32_e32 v181, v180, v166
	v_fma_f32 v182, -v165, v181, v180
	v_fmac_f32_e32 v181, v182, v166
	v_fma_f32 v165, -v165, v181, v180
	v_div_fmas_f32 v165, v165, v166, v181
	v_div_fixup_f32 v172, v165, v172, 1.0
	v_pk_mul_f32 v[170:171], v[172:173], v[170:171]
	s_nop 0
	v_pk_mul_f32 v[66:67], v[170:171], v[66:67]
	s_nop 0
	v_pk_mul_f32 v[170:171], v[66:67], v[66:67]
	s_nop 0
	v_pk_fma_f32 v[170:171], v[70:71], v[70:71], v[170:171]
	s_nop 0
	v_add_f32_e32 v136, v170, v136
	v_add_f32_e32 v136, v171, v136
	s_waitcnt lgkmcnt(0)
	s_nop 1
	v_add_f32_dpp v136, v136, v136 quad_perm:[1,0,3,2] row_mask:0xf bank_mask:0xf
	s_waitcnt lgkmcnt(0)
	s_nop 1
	v_add_f32_dpp v136, v136, v136 quad_perm:[2,3,0,1] row_mask:0xf bank_mask:0xf
	s_waitcnt lgkmcnt(0)
	s_nop 1
	v_add_f32_dpp v136, v136, v136 row_half_mirror row_mask:0xf bank_mask:0xf
	s_waitcnt lgkmcnt(0)
	s_nop 1
	v_add_f32_dpp v136, v136, v136 row_mirror row_mask:0xf bank_mask:0xf
	s_waitcnt lgkmcnt(0)
	v_mov_b32_e32 v137, v136
	s_nop 1
	v_permlane16_swap_b32_e32 v136, v137
	v_add_f32_e32 v136, v136, v137
	s_waitcnt lgkmcnt(0)
; __device__ __forceinline__ unsigned pk2(float lo, float hi) { return f2bf(lo) | (f2bf(hi) << 16); }
; __device__ __forceinline__ void ssd_gnorm(const Ctx& c, bf16* X2, const bf16* P, const float* g) {
;     ...
;         const float rs = rsqrtf(wave_sum(s) * (1.f / 4096.f) + EPS);
; #pragma unroll
;         for (int j = 0; j < 8; ++j) { const float* gg = g + (c.lane + 64 * j) * 8; const f32x4 g0 = *(CF4)gg, g1 = *(CF4)(gg + 4);
;             v4u w; w.x = pk2(v[j][0] * rs * g0.x, v[j][1] * rs * g0.y); w.y = pk2(v[j][2] * rs * g0.z, v[j][3] * rs * g0.w); w.z = pk2(v[j][4] * rs * g1.x, v[j][5] * rs * g1.y); w.w = pk2(v[j][6] * rs * g1.z, v[j][7] * rs * g1.w);
;             yr[64 * j] = w; }
	v_mov_b32_e32 v137, v136
	s_nop 1
	v_permlane32_swap_b32_e32 v136, v137
	v_add_f32_e32 v136, v136, v137
	v_fmamk_f32 v136, v136, 0x39800000, v167
	v_cmp_gt_f32_e32 vcc, s17, v136
	v_mul_f32_e32 v137, 0x4b800000, v136
	s_nop 0
	v_cndmask_b32_e32 v136, v136, v137, vcc
	v_rsq_f32_e32 v136, v136
	s_nop 0
	v_mul_f32_e32 v137, 0x45800000, v136
	v_cndmask_b32_e32 v136, v136, v137, vcc
	v_pk_mul_f32 v[120:121], v[120:121], v[136:137] op_sel_hi:[1,0]
	v_pk_mul_f32 v[122:123], v[122:123], v[136:137] op_sel_hi:[1,0]
	v_pk_mul_f32 v[124:125], v[124:125], v[136:137] op_sel_hi:[1,0]
	v_pk_mul_f32 v[120:121], v[128:129], v[120:121]
	v_pk_mul_f32 v[126:127], v[126:127], v[136:137] op_sel_hi:[1,0]
	v_pk_mul_f32 v[122:123], v[4:5], v[122:123]
	v_pk_mul_f32 v[124:125], v[2:3], v[124:125]
	v_pk_mul_f32 v[126:127], v[6:7], v[126:127]
	s_nop 2
	v_bfe_u32 v140, v120, 16, 1
	v_add3_u32 v120, v120, v140, s18
	s_nop 2
	v_bfe_u32 v137, v124, 16, 1
	s_nop 5
	v_add3_u32 v124, v124, v137, s18
	v_lshrrev_b32_e32 v124, 16, v124
	s_nop 2
	v_pk_mul_f32 v[112:113], v[112:113], v[136:137] op_sel_hi:[1,0]
	v_pk_mul_f32 v[114:115], v[114:115], v[136:137] op_sel_hi:[1,0]
	v_cvt_pk_bf16_f32 v123, v127, v123
	v_cvt_pk_bf16_f32 v122, v126, v122
	v_cvt_pk_bf16_f32 v121, v125, v121
	v_and_or_b32 v120, v120, s16, v124
	v_pk_mul_f32 v[116:117], v[116:117], v[136:137] op_sel_hi:[1,0]
	v_pk_mul_f32 v[112:113], v[8:9], v[112:113]
	v_pk_mul_f32 v[118:119], v[118:119], v[136:137] op_sel_hi:[1,0]
	v_pk_mul_f32 v[114:115], v[12:13], v[114:115]
	global_store_dwordx4 v[134:135], v[120:123], off
	v_pk_mul_f32 v[116:117], v[10:11], v[116:117]
	v_pk_mul_f32 v[118:119], v[14:15], v[118:119]
	v_bfe_u32 v120, v115, 16, 1
	v_bfe_u32 v121, v114, 16, 1
	v_bfe_u32 v122, v113, 16, 1
	v_bfe_u32 v123, v112, 16, 1
	v_add3_u32 v112, v112, v123, s18
	v_add3_u32 v113, v113, v122, s18
	v_add3_u32 v114, v114, v121, s18
	v_add3_u32 v115, v115, v120, s18
	v_bfe_u32 v120, v116, 16, 1
	v_bfe_u32 v121, v117, 16, 1
	v_bfe_u32 v122, v118, 16, 1
	v_bfe_u32 v123, v119, 16, 1
	v_add3_u32 v119, v119, v123, s18
	v_add3_u32 v118, v118, v122, s18
	v_add3_u32 v117, v117, v121, s18
	v_add3_u32 v116, v116, v120, s18
	v_lshrrev_b32_e32 v116, 16, v116
	v_lshrrev_b32_e32 v117, 16, v117
	v_lshrrev_b32_e32 v118, 16, v118
	v_lshrrev_b32_e32 v119, 16, v119
	v_pk_mul_f32 v[104:105], v[104:105], v[136:137] op_sel_hi:[1,0]
	v_pk_mul_f32 v[106:107], v[106:107], v[136:137] op_sel_hi:[1,0]
	v_and_or_b32 v115, v115, s16, v119
	v_and_or_b32 v114, v114, s16, v118
	v_and_or_b32 v113, v113, s16, v117
	v_and_or_b32 v112, v112, s16, v116
	v_pk_mul_f32 v[108:109], v[108:109], v[136:137] op_sel_hi:[1,0]
	v_pk_mul_f32 v[104:105], v[16:17], v[104:105]
	v_pk_mul_f32 v[110:111], v[110:111], v[136:137] op_sel_hi:[1,0]
	v_pk_mul_f32 v[106:107], v[20:21], v[106:107]
	global_store_dwordx4 v[134:135], v[112:115], off offset:1024
	v_pk_mul_f32 v[108:109], v[18:19], v[108:109]
	v_pk_mul_f32 v[110:111], v[22:23], v[110:111]
	v_bfe_u32 v112, v107, 16, 1
	v_bfe_u32 v113, v106, 16, 1
	v_bfe_u32 v114, v105, 16, 1
	v_bfe_u32 v115, v104, 16, 1
	v_add3_u32 v104, v104, v115, s18
	v_add3_u32 v105, v105, v114, s18
	v_add3_u32 v106, v106, v113, s18
	v_add3_u32 v107, v107, v112, s18
	v_bfe_u32 v112, v108, 16, 1
	v_bfe_u32 v113, v109, 16, 1
	v_bfe_u32 v114, v110, 16, 1
	v_bfe_u32 v115, v111, 16, 1
	v_add3_u32 v111, v111, v115, s18
	v_add3_u32 v110, v110, v114, s18
	v_add3_u32 v109, v109, v113, s18
	v_add3_u32 v108, v108, v112, s18
	v_lshrrev_b32_e32 v108, 16, v108
	v_lshrrev_b32_e32 v109, 16, v109
	v_lshrrev_b32_e32 v110, 16, v110
	v_lshrrev_b32_e32 v111, 16, v111
	v_pk_mul_f32 v[96:97], v[96:97], v[136:137] op_sel_hi:[1,0]
	v_pk_mul_f32 v[98:99], v[98:99], v[136:137] op_sel_hi:[1,0]
	v_and_or_b32 v107, v107, s16, v111
	v_and_or_b32 v106, v106, s16, v110
	v_and_or_b32 v105, v105, s16, v109
	v_and_or_b32 v104, v104, s16, v108
	v_pk_mul_f32 v[100:101], v[100:101], v[136:137] op_sel_hi:[1,0]
	v_pk_mul_f32 v[96:97], v[24:25], v[96:97]
	v_pk_mul_f32 v[102:103], v[102:103], v[136:137] op_sel_hi:[1,0]
	v_pk_mul_f32 v[98:99], v[28:29], v[98:99]
	global_store_dwordx4 v[134:135], v[104:107], off offset:2048
	v_pk_mul_f32 v[100:101], v[26:27], v[100:101]
	v_pk_mul_f32 v[102:103], v[30:31], v[102:103]
	v_bfe_u32 v104, v99, 16, 1
	v_bfe_u32 v105, v98, 16, 1
	v_bfe_u32 v106, v97, 16, 1
	v_bfe_u32 v107, v96, 16, 1
	v_add3_u32 v96, v96, v107, s18
	v_add3_u32 v97, v97, v106, s18
; __device__ __forceinline__ unsigned pk2(float lo, float hi) { return f2bf(lo) | (f2bf(hi) << 16); }
; __device__ __forceinline__ void ssd_gnorm(const Ctx& c, bf16* X2, const bf16* P, const float* g) {
;     ...
;         for (int j = 0; j < 8; ++j) { const float* gg = g + (c.lane + 64 * j) * 8; const f32x4 g0 = *(CF4)gg, g1 = *(CF4)(gg + 4);
;             v4u w; w.x = pk2(v[j][0] * rs * g0.x, v[j][1] * rs * g0.y); w.y = pk2(v[j][2] * rs * g0.z, v[j][3] * rs * g0.w); w.z = pk2(v[j][4] * rs * g1.x, v[j][5] * rs * g1.y); w.w = pk2(v[j][6] * rs * g1.z, v[j][7] * rs * g1.w);
;             yr[64 * j] = w; }
	v_add3_u32 v98, v98, v105, s18
	v_add3_u32 v99, v99, v104, s18
	v_bfe_u32 v104, v100, 16, 1
	v_bfe_u32 v105, v101, 16, 1
	v_bfe_u32 v106, v102, 16, 1
	v_bfe_u32 v107, v103, 16, 1
	v_add3_u32 v103, v103, v107, s18
	v_add3_u32 v102, v102, v106, s18
	v_add3_u32 v101, v101, v105, s18
	v_add3_u32 v100, v100, v104, s18
	v_lshrrev_b32_e32 v100, 16, v100
	v_lshrrev_b32_e32 v101, 16, v101
	v_lshrrev_b32_e32 v102, 16, v102
	v_lshrrev_b32_e32 v103, 16, v103
	v_pk_mul_f32 v[88:89], v[88:89], v[136:137] op_sel_hi:[1,0]
	v_pk_mul_f32 v[90:91], v[90:91], v[136:137] op_sel_hi:[1,0]
	v_and_or_b32 v99, v99, s16, v103
	v_and_or_b32 v98, v98, s16, v102
	v_and_or_b32 v97, v97, s16, v101
	v_and_or_b32 v96, v96, s16, v100
	v_pk_mul_f32 v[92:93], v[92:93], v[136:137] op_sel_hi:[1,0]
	v_pk_mul_f32 v[88:89], v[32:33], v[88:89]
	v_pk_mul_f32 v[94:95], v[94:95], v[136:137] op_sel_hi:[1,0]
	v_pk_mul_f32 v[90:91], v[36:37], v[90:91]
	global_store_dwordx4 v[134:135], v[96:99], off offset:3072
	v_pk_mul_f32 v[92:93], v[34:35], v[92:93]
	v_pk_mul_f32 v[94:95], v[38:39], v[94:95]
	v_bfe_u32 v96, v91, 16, 1
	v_bfe_u32 v97, v90, 16, 1
	v_bfe_u32 v98, v89, 16, 1
	v_bfe_u32 v99, v88, 16, 1
	v_add3_u32 v88, v88, v99, s18
	v_add3_u32 v89, v89, v98, s18
	v_add3_u32 v90, v90, v97, s18
	v_add3_u32 v91, v91, v96, s18
	v_bfe_u32 v96, v92, 16, 1
	v_bfe_u32 v97, v93, 16, 1
	v_bfe_u32 v98, v94, 16, 1
	v_bfe_u32 v99, v95, 16, 1
	v_add3_u32 v95, v95, v99, s18
	v_add3_u32 v94, v94, v98, s18
	v_add3_u32 v93, v93, v97, s18
	v_add3_u32 v92, v92, v96, s18
	v_lshrrev_b32_e32 v92, 16, v92
	v_lshrrev_b32_e32 v93, 16, v93
	v_lshrrev_b32_e32 v94, 16, v94
	v_lshrrev_b32_e32 v95, 16, v95
	v_pk_mul_f32 v[80:81], v[80:81], v[136:137] op_sel_hi:[1,0]
	v_pk_mul_f32 v[82:83], v[82:83], v[136:137] op_sel_hi:[1,0]
	v_and_or_b32 v91, v91, s16, v95
	v_and_or_b32 v90, v90, s16, v94
	v_and_or_b32 v89, v89, s16, v93
	v_and_or_b32 v88, v88, s16, v92
	v_pk_mul_f32 v[84:85], v[84:85], v[136:137] op_sel_hi:[1,0]
	v_pk_mul_f32 v[80:81], v[40:41], v[80:81]
	v_pk_mul_f32 v[86:87], v[86:87], v[136:137] op_sel_hi:[1,0]
	v_pk_mul_f32 v[82:83], v[48:49], v[82:83]
	global_store_dwordx4 v[132:133], v[88:91], off
	v_pk_mul_f32 v[84:85], v[46:47], v[84:85]
	v_pk_mul_f32 v[86:87], v[42:43], v[86:87]
	v_bfe_u32 v88, v83, 16, 1
	s_nop 0
	v_bfe_u32 v90, v81, 16, 1
	s_nop 1
	v_add3_u32 v81, v81, v90, s18
	s_nop 0
	v_add3_u32 v83, v83, v88, s18
	s_nop 0
	v_bfe_u32 v89, v85, 16, 1
	s_nop 0
	v_bfe_u32 v91, v87, 16, 1
	v_add3_u32 v87, v87, v91, s18
	s_nop 0
	v_add3_u32 v85, v85, v89, s18
	s_nop 1
	v_lshrrev_b32_e32 v85, 16, v85
	s_nop 0
	v_lshrrev_b32_e32 v87, 16, v87
	v_pk_mul_f32 v[72:73], v[72:73], v[136:137] op_sel_hi:[1,0]
	v_pk_mul_f32 v[74:75], v[74:75], v[136:137] op_sel_hi:[1,0]
	v_and_or_b32 v83, v83, s16, v87
	v_cvt_pk_bf16_f32 v82, v86, v82
	v_and_or_b32 v81, v81, s16, v85
	v_cvt_pk_bf16_f32 v80, v84, v80
	v_pk_mul_f32 v[76:77], v[76:77], v[136:137] op_sel_hi:[1,0]
	v_pk_mul_f32 v[72:73], v[44:45], v[72:73]
	v_pk_mul_f32 v[78:79], v[78:79], v[136:137] op_sel_hi:[1,0]
	v_pk_mul_f32 v[74:75], v[52:53], v[74:75]
	global_store_dwordx4 v[132:133], v[80:83], off offset:1024
	v_pk_mul_f32 v[76:77], v[50:51], v[76:77]
	v_pk_mul_f32 v[78:79], v[54:55], v[78:79]
	s_nop 1
	v_bfe_u32 v82, v73, 16, 1
	s_nop 1
	v_add3_u32 v73, v73, v82, s18
	s_nop 2
	v_bfe_u32 v81, v77, 16, 1
	s_nop 3
	v_add3_u32 v77, v77, v81, s18
	s_nop 1
	v_lshrrev_b32_e32 v77, 16, v77
	s_nop 1
	v_pk_mul_f32 v[64:65], v[64:65], v[136:137] op_sel_hi:[1,0]
	v_pk_mul_f32 v[66:67], v[66:67], v[136:137] op_sel_hi:[1,0]
	v_cvt_pk_bf16_f32 v75, v79, v75
	v_cvt_pk_bf16_f32 v74, v78, v74
	v_and_or_b32 v73, v73, s16, v77
	v_cvt_pk_bf16_f32 v72, v76, v72
	v_pk_mul_f32 v[68:69], v[68:69], v[136:137] op_sel_hi:[1,0]
	v_pk_mul_f32 v[64:65], v[56:57], v[64:65]
	v_pk_mul_f32 v[70:71], v[70:71], v[136:137] op_sel_hi:[1,0]
	v_pk_mul_f32 v[66:67], v[60:61], v[66:67]
	global_store_dwordx4 v[132:133], v[72:75], off offset:2048
	v_pk_mul_f32 v[68:69], v[58:59], v[68:69]
	v_pk_mul_f32 v[70:71], v[62:63], v[70:71]
	v_bfe_u32 v72, v67, 16, 1
	s_nop 5
	v_add3_u32 v67, v67, v72, s18
	s_nop 2
	v_bfe_u32 v75, v71, 16, 1
	v_add3_u32 v71, v71, v75, s18
	s_nop 5
	v_lshrrev_b32_e32 v71, 16, v71
	v_and_or_b32 v67, v67, s16, v71
	v_cvt_pk_bf16_f32 v66, v70, v66
	v_cvt_pk_bf16_f32 v65, v69, v65
	v_cvt_pk_bf16_f32 v64, v68, v64
	global_store_dwordx4 v[132:133], v[64:67], off offset:3072
	s_cbranch_scc1 .LBB0_550

; __device__ __forceinline__ void postnorm(const Ctx& c, const bf16* MF, bf16* XB, float* RS, const float* gpost, float* OUT) {
;     for (int row = c.gw; row < MT; row += c.NGW) {
;         const v4u* mr = (const v4u*)(MF + (size_t)row * DM) + c.lane; v4u* xr = (v4u*)(XB + (size_t)row * DM) + c.lane;
;         v4u mv[4], xv[4]; float v[4][8]; float s = 0.f;
; #pragma unroll
;         for (int j = 0; j < 4; ++j) { mv[j] = mr[64 * j]; xv[j] = xr[64 * j]; }
; #pragma unroll
;         for (int j = 0; j < 4; ++j)
; #pragma unroll
;             for (int k = 0; k < 4; ++k) { v[j][2 * k] = bflo(mv[j][k]); v[j][2 * k + 1] = bfhi(mv[j][k]); s += v[j][2 * k] * v[j][2 * k] + v[j][2 * k + 1] * v[j][2 * k + 1]; }
;         const float rs = rsqrtf(wave_sum(s) * (1.f / DM) + EPS);
.LBB0_685:
	s_load_dwordx2 s[4:5], s[52:53], 0x120
	s_waitcnt lgkmcnt(0)
	v_lshl_add_u64 v[32:33], s[4:5], 0, v[34:35]
	v_add_co_u32_e32 v58, vcc, 0xd400000, v32
	s_nop 1
	v_addc_co_u32_e32 v59, vcc, 0, v33, vcc
	global_load_dwordx4 v[46:49], v[58:59], off
	global_load_dwordx4 v[50:53], v[58:59], off offset:1024
	global_load_dwordx4 v[54:57], v[58:59], off offset:2048
	s_nop 0
	global_load_dwordx4 v[58:61], v[58:59], off offset:3072
	v_add_co_u32_e32 v32, vcc, 0x9400000, v32
	s_waitcnt vmcnt(3)
	v_lshlrev_b32_e32 v79, 16, v47
	v_addc_co_u32_e32 v33, vcc, 0, v33, vcc
	global_load_dwordx4 v[62:65], v[32:33], off
	global_load_dwordx4 v[66:69], v[32:33], off offset:1024
	global_load_dwordx4 v[70:73], v[32:33], off offset:2048
	global_load_dwordx4 v[74:77], v[32:33], off offset:3072
	v_lshlrev_b32_e32 v78, 16, v46
	v_and_b32_e32 v47, 0xffff0000, v47
	v_and_b32_e32 v46, 0xffff0000, v46
	v_lshlrev_b32_e32 v81, 16, v49
	v_lshlrev_b32_e32 v80, 16, v48
	v_and_b32_e32 v49, 0xffff0000, v49
	v_and_b32_e32 v48, 0xffff0000, v48
	v_pk_mul_f32 v[94:95], v[46:47], v[46:47]
	v_pk_mul_f32 v[98:99], v[48:49], v[48:49]
	v_pk_fma_f32 v[94:95], v[78:79], v[78:79], v[94:95]
	s_waitcnt vmcnt(6)
	v_lshlrev_b32_e32 v83, 16, v51
	v_lshlrev_b32_e32 v82, 16, v50
	v_and_b32_e32 v51, 0xffff0000, v51
	v_and_b32_e32 v50, 0xffff0000, v50
	v_pk_fma_f32 v[98:99], v[80:81], v[80:81], v[98:99]
	v_add_f32_e32 v45, v94, v95
	v_pk_mul_f32 v[102:103], v[50:51], v[50:51]
	v_add_f32_e32 v45, v98, v45
	v_lshlrev_b32_e32 v85, 16, v53
	v_lshlrev_b32_e32 v84, 16, v52
	v_and_b32_e32 v53, 0xffff0000, v53
	v_and_b32_e32 v52, 0xffff0000, v52
	v_pk_fma_f32 v[102:103], v[82:83], v[82:83], v[102:103]
	v_add_f32_e32 v45, v99, v45
	v_pk_mul_f32 v[104:105], v[52:53], v[52:53]
	v_add_f32_e32 v45, v102, v45
	s_waitcnt vmcnt(5)
	v_lshlrev_b32_e32 v87, 16, v55
	v_lshlrev_b32_e32 v86, 16, v54
	v_and_b32_e32 v55, 0xffff0000, v55
	v_and_b32_e32 v54, 0xffff0000, v54
	v_pk_fma_f32 v[104:105], v[84:85], v[84:85], v[104:105]
	v_add_f32_e32 v45, v103, v45
	v_pk_mul_f32 v[106:107], v[54:55], v[54:55]
	v_add_f32_e32 v45, v104, v45
	v_lshlrev_b32_e32 v89, 16, v57
	v_lshlrev_b32_e32 v88, 16, v56
	v_and_b32_e32 v57, 0xffff0000, v57
	v_and_b32_e32 v56, 0xffff0000, v56
	v_pk_fma_f32 v[106:107], v[86:87], v[86:87], v[106:107]
	v_add_f32_e32 v45, v105, v45
	v_pk_mul_f32 v[108:109], v[56:57], v[56:57]
	v_add_f32_e32 v45, v106, v45
	s_waitcnt vmcnt(4)
	v_lshlrev_b32_e32 v91, 16, v59
	v_lshlrev_b32_e32 v90, 16, v58
	v_and_b32_e32 v59, 0xffff0000, v59
	v_and_b32_e32 v58, 0xffff0000, v58
	v_pk_fma_f32 v[108:109], v[88:89], v[88:89], v[108:109]
	v_add_f32_e32 v45, v107, v45
	v_pk_mul_f32 v[110:111], v[58:59], v[58:59]
	v_add_f32_e32 v45, v108, v45
	v_lshlrev_b32_e32 v93, 16, v61
	v_lshlrev_b32_e32 v92, 16, v60
	v_and_b32_e32 v61, 0xffff0000, v61
	v_and_b32_e32 v60, 0xffff0000, v60
	v_pk_fma_f32 v[110:111], v[90:91], v[90:91], v[110:111]
	v_add_f32_e32 v45, v109, v45
	v_pk_mul_f32 v[112:113], v[60:61], v[60:61]
	v_add_f32_e32 v45, v110, v45
	v_pk_fma_f32 v[112:113], v[92:93], v[92:93], v[112:113]
	v_add_f32_e32 v45, v111, v45
	v_add_f32_e32 v45, v112, v45
	v_add_f32_e32 v45, v113, v45
	s_waitcnt lgkmcnt(0)
	s_nop 1
	v_add_f32_dpp v45, v45, v45 quad_perm:[1,0,3,2] row_mask:0xf bank_mask:0xf
	s_waitcnt lgkmcnt(0)
	s_nop 1
	v_add_f32_dpp v45, v45, v45 quad_perm:[2,3,0,1] row_mask:0xf bank_mask:0xf
	s_waitcnt vmcnt(3)
	v_lshlrev_b32_e32 v97, 16, v63
	v_lshlrev_b32_e32 v96, 16, v62
	v_and_b32_e32 v63, 0xffff0000, v63
	s_waitcnt lgkmcnt(0)
	s_nop 1
	v_add_f32_dpp v45, v45, v45 row_half_mirror row_mask:0xf bank_mask:0xf
	v_and_b32_e32 v62, 0xffff0000, v62
	v_lshlrev_b32_e32 v101, 16, v65
	v_lshlrev_b32_e32 v100, 16, v64
	v_and_b32_e32 v65, 0xffff0000, v65
	s_waitcnt lgkmcnt(0)
	s_nop 1
	v_add_f32_dpp v45, v45, v45 row_mirror row_mask:0xf bank_mask:0xf
	v_and_b32_e32 v64, 0xffff0000, v64
	s_waitcnt vmcnt(0)
	v_lshlrev_b32_e32 v109, 16, v77
	v_and_b32_e32 v77, 0xffff0000, v77
	v_lshlrev_b32_e32 v95, 16, v67
	s_waitcnt lgkmcnt(0)
	v_mov_b32_e32 v106, v45
	s_nop 1
	v_permlane16_swap_b32_e32 v45, v106
	v_add_f32_e32 v45, v45, v106
	v_lshlrev_b32_e32 v94, 16, v66
	v_and_b32_e32 v67, 0xffff0000, v67
	v_and_b32_e32 v66, 0xffff0000, v66
	v_lshlrev_b32_e32 v99, 16, v69
	s_waitcnt lgkmcnt(0)
; __device__ __forceinline__ unsigned pk2(float lo, float hi) { return f2bf(lo) | (f2bf(hi) << 16); }
; __device__ __forceinline__ void postnorm(const Ctx& c, const bf16* MF, bf16* XB, float* RS, const float* gpost, float* OUT) {
;     ...
;         const float rs = rsqrtf(wave_sum(s) * (1.f / DM) + EPS);
;         float s2 = 0.f;
; #pragma unroll
;         for (int j = 0; j < 4; ++j) { const float* gp = gpost + (c.lane + 64 * j) * 8; const f32x4 g0 = *(CF4)gp, g1 = *(CF4)(gp + 4);
; #pragma unroll
;             for (int k = 0; k < 4; ++k) { const float ga = (k < 2) ? g0[2 * k] : g1[2 * k - 4], gb = (k < 2) ? g0[2 * k + 1] : g1[2 * k - 3];
;                 v[j][2 * k] = bflo(xv[j][k]) + v[j][2 * k] * rs * ga; v[j][2 * k + 1] = bfhi(xv[j][k]) + v[j][2 * k + 1] * rs * gb;
;                 s2 += v[j][2 * k] * v[j][2 * k] + v[j][2 * k + 1] * v[j][2 * k + 1]; } }
;         if (OUT) {
; #pragma unroll
;             for (int j = 0; j < 4; ++j) { float* op = OUT + (size_t)row * DM + (c.lane + 64 * j) * 8; *(f32x4*)op = (f32x4){v[j][0], v[j][1], v[j][2], v[j][3]}; *(f32x4*)(op + 4) = (f32x4){v[j][4], v[j][5], v[j][6], v[j][7]}; }
;         } else {
; #pragma unroll
;             for (int j = 0; j < 4; ++j) { v4u o; o.x = pk2(v[j][0], v[j][1]); o.y = pk2(v[j][2], v[j][3]); o.z = pk2(v[j][4], v[j][5]); o.w = pk2(v[j][6], v[j][7]); xr[64 * j] = o; }
;             const float rs2 = rsqrtf(wave_sum(s2) * (1.f / DM) + EPS); if (c.lane == 0) RS[row] = rs2;
	v_mov_b32_e32 v108, v45
	s_nop 1
	v_permlane32_swap_b32_e32 v45, v108
	v_add_f32_e32 v45, v45, v108
	v_fmamk_f32 v45, v45, 0x3a000000, v38
	v_mul_f32_e32 v108, 0x4b800000, v45
	v_cmp_gt_f32_e32 vcc, s1, v45
	v_lshlrev_b32_e32 v98, 16, v68
	v_and_b32_e32 v69, 0xffff0000, v69
	v_cndmask_b32_e32 v45, v45, v108, vcc
	v_rsq_f32_e32 v45, v45
	v_lshlrev_b32_e32 v108, 16, v76
	v_and_b32_e32 v76, 0xffff0000, v76
	v_and_b32_e32 v68, 0xffff0000, v68
	v_mul_f32_e32 v110, 0x45800000, v45
	v_cndmask_b32_e32 v110, v45, v110, vcc
	v_pk_mul_f32 v[46:47], v[110:111], v[46:47] op_sel_hi:[0,1]
	v_pk_mul_f32 v[78:79], v[110:111], v[78:79] op_sel_hi:[0,1]
	v_pk_mul_f32 v[48:49], v[110:111], v[48:49] op_sel_hi:[0,1]
	v_pk_fma_f32 v[46:47], v[36:37], v[46:47], v[62:63]
	v_pk_mul_f32 v[60:61], v[110:111], v[60:61] op_sel_hi:[0,1]
	v_pk_mul_f32 v[80:81], v[110:111], v[80:81] op_sel_hi:[0,1]
	v_pk_fma_f32 v[78:79], v[2:3], v[78:79], v[96:97]
	v_pk_fma_f32 v[48:49], v[4:5], v[48:49], v[64:65]
	v_pk_fma_f32 v[60:61], v[28:29], v[60:61], v[76:77]
	v_pk_mul_f32 v[76:77], v[46:47], v[46:47]
	v_pk_fma_f32 v[62:63], v[6:7], v[80:81], v[100:101]
	v_pk_fma_f32 v[76:77], v[78:79], v[78:79], v[76:77]
	v_pk_mul_f32 v[80:81], v[48:49], v[48:49]
	v_add_f32_e32 v45, v76, v77
	v_pk_fma_f32 v[80:81], v[62:63], v[62:63], v[80:81]
	v_pk_mul_f32 v[50:51], v[110:111], v[50:51] op_sel_hi:[0,1]
	v_add_f32_e32 v45, v80, v45
	v_pk_mul_f32 v[82:83], v[110:111], v[82:83] op_sel_hi:[0,1]
	v_pk_fma_f32 v[50:51], v[8:9], v[50:51], v[66:67]
	v_add_f32_e32 v45, v81, v45
	s_nop 1
	v_bfe_u32 v80, v47, 16, 1
	s_nop 0
	v_pk_mul_f32 v[52:53], v[110:111], v[52:53] op_sel_hi:[0,1]
	v_pk_fma_f32 v[64:65], v[14:15], v[82:83], v[94:95]
	v_pk_mul_f32 v[82:83], v[50:51], v[50:51]
	s_nop 0
	v_add3_u32 v47, v47, v80, s14
	s_nop 2
	v_bfe_u32 v77, v79, 16, 1
	s_nop 1
	v_pk_mul_f32 v[84:85], v[110:111], v[84:85] op_sel_hi:[0,1]
	v_pk_fma_f32 v[52:53], v[16:17], v[52:53], v[68:69]
	v_pk_fma_f32 v[82:83], v[64:65], v[64:65], v[82:83]
	s_nop 1
	v_add3_u32 v77, v79, v77, s14
	s_nop 0
	v_lshlrev_b32_e32 v103, 16, v71
	v_lshlrev_b32_e32 v102, 16, v70
	v_and_b32_e32 v71, 0xffff0000, v71
	v_and_b32_e32 v70, 0xffff0000, v70
	v_pk_fma_f32 v[66:67], v[10:11], v[84:85], v[98:99]
	v_pk_mul_f32 v[54:55], v[110:111], v[54:55] op_sel_hi:[0,1]
	v_pk_mul_f32 v[84:85], v[52:53], v[52:53]
	v_add_f32_e32 v45, v82, v45
	s_nop 0
	v_lshrrev_b32_e32 v77, 16, v77
	s_nop 1
	v_pk_mul_f32 v[68:69], v[110:111], v[86:87] op_sel_hi:[0,1]
	v_pk_fma_f32 v[54:55], v[12:13], v[54:55], v[70:71]
	v_pk_fma_f32 v[84:85], v[66:67], v[66:67], v[84:85]
	v_add_f32_e32 v45, v83, v45
	v_cvt_pk_bf16_f32 v49, v63, v49
	v_cvt_pk_bf16_f32 v48, v62, v48
	v_and_or_b32 v47, v47, s0, v77
	v_cvt_pk_bf16_f32 v46, v78, v46
	v_lshlrev_b32_e32 v105, 16, v73
	v_lshlrev_b32_e32 v104, 16, v72
	v_and_b32_e32 v73, 0xffff0000, v73
	v_and_b32_e32 v72, 0xffff0000, v72
	v_pk_fma_f32 v[68:69], v[18:19], v[68:69], v[102:103]
	v_pk_mul_f32 v[56:57], v[110:111], v[56:57] op_sel_hi:[0,1]
	v_pk_mul_f32 v[86:87], v[54:55], v[54:55]
	v_add_f32_e32 v45, v84, v45
	global_store_dwordx4 v[32:33], v[46:49], off
	v_pk_mul_f32 v[70:71], v[110:111], v[88:89] op_sel_hi:[0,1]
	v_pk_fma_f32 v[56:57], v[20:21], v[56:57], v[72:73]
	s_nop 3
	v_pk_fma_f32 v[86:87], v[68:69], v[68:69], v[86:87]
	v_add_f32_e32 v45, v85, v45
	s_nop 7
	v_lshlrev_b32_e32 v107, 16, v75
	v_lshlrev_b32_e32 v106, 16, v74
	v_and_b32_e32 v75, 0xffff0000, v75
	v_and_b32_e32 v74, 0xffff0000, v74
	v_pk_fma_f32 v[70:71], v[22:23], v[70:71], v[104:105]
	v_pk_mul_f32 v[58:59], v[110:111], v[58:59] op_sel_hi:[0,1]
	v_pk_mul_f32 v[88:89], v[56:57], v[56:57]
	v_add_f32_e32 v45, v86, v45
	s_nop 3
	v_pk_mul_f32 v[72:73], v[110:111], v[90:91] op_sel_hi:[0,1]
	v_pk_fma_f32 v[58:59], v[24:25], v[58:59], v[74:75]
	v_pk_fma_f32 v[88:89], v[70:71], v[70:71], v[88:89]
	v_add_f32_e32 v45, v87, v45
	s_nop 3
	v_pk_fma_f32 v[72:73], v[26:27], v[72:73], v[106:107]
	v_pk_mul_f32 v[90:91], v[58:59], v[58:59]
	v_add_f32_e32 v45, v88, v45
	v_cvt_pk_bf16_f32 v49, v67, v53
	v_cvt_pk_bf16_f32 v48, v66, v52
	v_cvt_pk_bf16_f32 v47, v65, v51
	v_cvt_pk_bf16_f32 v46, v64, v50
	v_pk_mul_f32 v[74:75], v[110:111], v[92:93] op_sel_hi:[0,1]
	v_pk_fma_f32 v[90:91], v[72:73], v[72:73], v[90:91]
	v_add_f32_e32 v45, v89, v45
	global_store_dwordx4 v[32:33], v[46:49], off offset:1024
	v_pk_fma_f32 v[74:75], v[30:31], v[74:75], v[108:109]
	v_pk_mul_f32 v[92:93], v[60:61], v[60:61]
	s_nop 1
	v_add_f32_e32 v45, v90, v45
	s_nop 5
	v_pk_fma_f32 v[92:93], v[74:75], v[74:75], v[92:93]
	v_add_f32_e32 v45, v91, v45
	s_nop 5
	v_add_f32_e32 v45, v92, v45
	s_nop 5
	v_add_f32_e32 v45, v93, v45
	v_cvt_pk_bf16_f32 v49, v71, v57
	v_cvt_pk_bf16_f32 v48, v70, v56
	v_cvt_pk_bf16_f32 v47, v69, v55
	v_cvt_pk_bf16_f32 v46, v68, v54
	global_store_dwordx4 v[32:33], v[46:49], off offset:2048
	s_nop 3
	s_waitcnt lgkmcnt(0)
	s_nop 1
	v_add_f32_dpp v45, v45, v45 quad_perm:[1,0,3,2] row_mask:0xf bank_mask:0xf
	s_nop 3
	s_waitcnt lgkmcnt(0)
	s_nop 1
	v_add_f32_dpp v45, v45, v45 quad_perm:[2,3,0,1] row_mask:0xf bank_mask:0xf
	s_nop 0
	v_cvt_pk_bf16_f32 v51, v75, v61
	s_nop 1
	s_waitcnt lgkmcnt(0)
	s_nop 1
	v_add_f32_dpp v45, v45, v45 row_half_mirror row_mask:0xf bank_mask:0xf
	s_nop 3
	s_waitcnt lgkmcnt(0)
	s_nop 1
	v_add_f32_dpp v45, v45, v45 row_mirror row_mask:0xf bank_mask:0xf
	s_nop 3
	s_waitcnt lgkmcnt(0)
	v_mov_b32_e32 v47, v45
	s_nop 1
	v_permlane16_swap_b32_e32 v45, v47
	v_add_f32_e32 v45, v45, v47
	ds_bpermute_b32 v46, v44, v45
	s_nop 0
	v_cvt_pk_bf16_f32 v50, v74, v60
	v_cvt_pk_bf16_f32 v49, v73, v59
	v_cvt_pk_bf16_f32 v48, v72, v58
	global_store_dwordx4 v[32:33], v[48:51], off offset:3072
	s_and_saveexec_b64 s[12:13], s[2:3]
	s_cbranch_execz .LBB0_684
	s_waitcnt lgkmcnt(0)
	v_add_f32_e32 v32, v45, v46
	v_fmamk_f32 v32, v32, 0x3a000000, v38
	v_mul_f32_e32 v33, 0x4b800000, v32
	v_cmp_gt_f32_e32 vcc, s1, v32
	s_load_dwordx2 s[4:5], s[52:53], 0x120
	s_waitcnt lgkmcnt(0)
	s_add_u32 s18, s4, s15
	v_cndmask_b32_e32 v32, v32, v33, vcc
	v_rsq_f32_e32 v32, v32
	s_addc_u32 s19, s5, s16
	v_mul_f32_e32 v33, 0x45800000, v32
	v_cndmask_b32_e32 v32, v32, v33, vcc
	global_store_dword v251, v32, s[18:19]
	s_branch .LBB0_684

; __device__ __forceinline__ unsigned pk2(float lo, float hi) { return f2bf(lo) | (f2bf(hi) << 16); }
; __device__ __forceinline__ void rms_row_bf16(const Ctx& c, const float* xrow, const float* gain, bf16* orow, float* copy) {
;     const f32x4* xr = (const f32x4*)xrow + c.lane; f32x4 v[8]; float s = 0.f;
; #pragma unroll
;     for (int j = 0; j < 8; ++j) { v[j] = xr[64 * j]; s += (v[j].x * v[j].x + v[j].y * v[j].y) + (v[j].z * v[j].z + v[j].w * v[j].w); }
;     const float rs = rsqrtf(wave_sum(s) * (1.f / DM) + EPS);
;     if (copy) {
; #pragma unroll
;         for (int j = 0; j < 8; ++j) ((f32x4*)copy + c.lane)[64 * j] = v[j]; }
;     const f32x4* gr = (const f32x4*)gain + c.lane; v2u* o8 = (v2u*)orow + c.lane;
; #pragma unroll
;     for (int j = 0; j < 8; ++j) { const f32x4 g = gr[64 * j]; v2u o; o.x = pk2(v[j].x * rs * g.x, v[j].y * rs * g.y); o.y = pk2(v[j].z * rs * g.z, v[j].w * rs * g.w); o8[64 * j] = o; }
.LBB0_1590:
	global_load_dwordx4 v[32:35], v[46:47], off offset:-4096
	global_load_dwordx4 v[28:31], v[46:47], off offset:-3072
	global_load_dwordx4 v[24:27], v[46:47], off offset:-2048
	global_load_dwordx4 v[20:23], v[46:47], off offset:-1024
	global_load_dwordx4 v[12:15], v[46:47], off
	global_load_dwordx4 v[16:19], v[46:47], off offset:1024
	s_add_i32 s2, s2, s86
	s_cmpk_lt_i32 s2, 0x400
	s_waitcnt vmcnt(0)
	v_mov_b32_e32 v6, v33
	v_mov_b32_e32 v7, v29
	v_mov_b32_e32 v4, v32
	v_mov_b32_e32 v5, v28
	v_pk_mul_f32 v[6:7], v[6:7], v[6:7]
	v_mov_b32_e32 v8, v35
	v_mov_b32_e32 v9, v31
	v_pk_fma_f32 v[4:5], v[4:5], v[4:5], v[6:7]
	v_mov_b32_e32 v6, v34
	v_mov_b32_e32 v7, v30
	v_pk_mul_f32 v[8:9], v[8:9], v[8:9]
	s_nop 0
	v_pk_fma_f32 v[6:7], v[6:7], v[6:7], v[8:9]
	v_pk_mul_f32 v[8:9], v[24:25], v[24:25]
	v_pk_add_f32 v[4:5], v[4:5], v[6:7]
	v_pk_mul_f32 v[6:7], v[26:27], v[26:27]
	v_pk_add_f32 v[4:5], v[4:5], v[4:5] op_sel:[0,1] op_sel_hi:[1,0]
	v_pk_mov_b32 v[10:11], v[8:9], v[6:7] op_sel:[1,0]
	v_mov_b32_e32 v9, v7
	v_pk_add_f32 v[6:7], v[10:11], v[8:9]
	v_mul_f32_e32 v8, v12, v12
	v_mul_f32_e32 v9, v13, v13
	v_pk_add_f32 v[6:7], v[6:7], v[6:7] op_sel:[0,1] op_sel_hi:[1,0]
	v_mov_b32_e32 v5, v8
	v_mov_b32_e32 v7, v9
	v_pk_add_f32 v[4:5], v[4:5], v[6:7]
	v_mul_f32_e32 v6, v21, v21
	v_mul_f32_e32 v8, v23, v23
	v_mul_f32_e32 v10, v14, v14
	v_mul_f32_e32 v11, v15, v15
	v_pk_fma_f32 v[6:7], v[20:21], v[20:21], v[6:7] op_sel_hi:[1,1,0]
	v_pk_fma_f32 v[8:9], v[22:23], v[22:23], v[8:9] op_sel_hi:[1,1,0]
	v_mov_b32_e32 v7, v10
	v_mov_b32_e32 v9, v11
	v_pk_add_f32 v[6:7], v[6:7], v[8:9]
	s_nop 0
	v_pk_add_f32 v[52:53], v[4:5], v[6:7]
	v_pk_mul_f32 v[4:5], v[18:19], v[18:19]
	v_pk_mul_f32 v[6:7], v[16:17], v[16:17]
	v_pk_add_f32 v[52:53], v[52:53], v[52:53] op_sel:[0,1] op_sel_hi:[1,0]
	v_pk_mov_b32 v[8:9], v[6:7], v[4:5] op_sel:[1,0]
	v_mov_b32_e32 v7, v5
	v_pk_add_f32 v[60:61], v[8:9], v[6:7]
	global_load_dwordx4 v[8:11], v[46:47], off offset:2048
	global_load_dwordx4 v[4:7], v[46:47], off offset:3072
	v_pk_add_f32 v[60:61], v[60:61], v[60:61] op_sel:[0,1] op_sel_hi:[1,0]
	v_lshl_add_u64 v[46:47], v[46:47], 0, s[6:7]
	s_waitcnt vmcnt(0)
	v_mul_f32_e32 v50, v4, v4
	v_mul_f32_e32 v62, v5, v5
	v_mov_b32_e32 v53, v50
	v_mov_b32_e32 v61, v62
	v_mul_f32_e32 v50, v9, v9
	v_mul_f32_e32 v63, v6, v6
	v_pk_add_f32 v[52:53], v[52:53], v[60:61]
	v_pk_fma_f32 v[60:61], v[8:9], v[8:9], v[50:51] op_sel_hi:[1,1,0]
	v_mul_f32_e32 v50, v11, v11
	v_mul_f32_e32 v64, v7, v7
	v_mov_b32_e32 v61, v63
	v_pk_fma_f32 v[62:63], v[10:11], v[10:11], v[50:51] op_sel_hi:[1,1,0]
	s_nop 0
	v_mov_b32_e32 v63, v64
	v_pk_add_f32 v[60:61], v[60:61], v[62:63]
	s_nop 0
	v_pk_add_f32 v[52:53], v[52:53], v[60:61]
	global_load_dwordx4 v[60:63], v[36:37], off
	v_add_f32_e32 v50, v52, v53
	v_mov_b32_e32 v53, v34
	v_mov_b32_e32 v34, v33
	s_waitcnt lgkmcnt(0)
	s_nop 1
	v_add_f32_dpp v50, v50, v50 quad_perm:[1,0,3,2] row_mask:0xf bank_mask:0xf
	s_waitcnt lgkmcnt(0)
	s_nop 1
	v_add_f32_dpp v50, v50, v50 quad_perm:[2,3,0,1] row_mask:0xf bank_mask:0xf
	s_waitcnt lgkmcnt(0)
	s_nop 1
	v_add_f32_dpp v50, v50, v50 row_half_mirror row_mask:0xf bank_mask:0xf
	s_waitcnt lgkmcnt(0)
	s_nop 1
	v_add_f32_dpp v50, v50, v50 row_mirror row_mask:0xf bank_mask:0xf
	s_waitcnt lgkmcnt(0)
	v_mov_b32_e32 v52, v50
	s_nop 1
	v_permlane16_swap_b32_e32 v50, v52
	v_add_f32_e32 v50, v50, v52
	s_waitcnt lgkmcnt(0)
	v_mov_b32_e32 v52, v50
	s_nop 1
	v_permlane32_swap_b32_e32 v50, v52
	v_add_f32_e32 v50, v50, v52
	v_fmamk_f32 v50, v50, 0x3a000000, v58
	v_cmp_gt_f32_e32 vcc, s10, v50
	v_mul_f32_e32 v52, 0x4b800000, v50
	s_waitcnt vmcnt(0)
	v_mov_b32_e32 v64, v60
	v_cndmask_b32_e32 v50, v50, v52, vcc
	v_rsq_f32_e32 v50, v50
	v_mov_b32_e32 v65, v62
	v_mov_b32_e32 v62, v61
	v_mul_f32_e32 v52, 0x45800000, v50
	v_cndmask_b32_e32 v50, v50, v52, vcc
	v_mov_b32_e32 v52, v32
	v_pk_mul_f32 v[52:53], v[52:53], v[50:51] op_sel_hi:[1,0]
	v_pk_mul_f32 v[32:33], v[34:35], v[50:51] op_sel_hi:[1,0]
	v_pk_mul_f32 v[52:53], v[64:65], v[52:53]
	v_pk_mul_f32 v[32:33], v[62:63], v[32:33]
	v_and_b32_sdwa v34, v53, v59 dst_sel:DWORD dst_unused:UNUSED_PAD src0_sel:WORD_1 src1_sel:DWORD
	v_and_b32_sdwa v35, v52, v59 dst_sel:DWORD dst_unused:UNUSED_PAD src0_sel:WORD_1 src1_sel:DWORD
	v_add3_u32 v35, v52, v35, s3
	v_add3_u32 v34, v53, v34, s3
	v_and_b32_sdwa v52, v33, v59 dst_sel:DWORD dst_unused:UNUSED_PAD src0_sel:WORD_1 src1_sel:DWORD
	v_and_b32_sdwa v53, v32, v59 dst_sel:DWORD dst_unused:UNUSED_PAD src0_sel:WORD_1 src1_sel:DWORD
	v_add3_u32 v33, v33, v52, s3
	v_add3_u32 v32, v32, v53, s3
	v_and_b32_e32 v33, 0xffff0000, v33
	v_and_b32_e32 v32, 0xffff0000, v32
	v_or_b32_sdwa v33, v33, v34 dst_sel:DWORD dst_unused:UNUSED_PAD src0_sel:DWORD src1_sel:WORD_1
	v_or_b32_sdwa v32, v32, v35 dst_sel:DWORD dst_unused:UNUSED_PAD src0_sel:DWORD src1_sel:WORD_1
	global_store_dwordx2 v[48:49], v[32:33], off
	global_load_dwordx4 v[32:35], v[36:37], off offset:1024
	v_mov_b32_e32 v53, v30
	v_mov_b32_e32 v30, v29
	v_mov_b32_e32 v52, v28
	v_pk_mul_f32 v[28:29], v[30:31], v[50:51] op_sel_hi:[1,0]
	v_pk_mul_f32 v[52:53], v[52:53], v[50:51] op_sel_hi:[1,0]
	s_waitcnt vmcnt(0)
; __device__ __forceinline__ unsigned pk2(float lo, float hi) { return f2bf(lo) | (f2bf(hi) << 16); }
; __device__ __forceinline__ void rms_row_bf16(const Ctx& c, const float* xrow, const float* gain, bf16* orow, float* copy) {
;     ...
;     const f32x4* gr = (const f32x4*)gain + c.lane; v2u* o8 = (v2u*)orow + c.lane;
; #pragma unroll
;     for (int j = 0; j < 8; ++j) { const f32x4 g = gr[64 * j]; v2u o; o.x = pk2(v[j].x * rs * g.x, v[j].y * rs * g.y); o.y = pk2(v[j].z * rs * g.z, v[j].w * rs * g.w); o8[64 * j] = o; }
	v_mov_b32_e32 v61, v34
	v_mov_b32_e32 v34, v33
	v_mov_b32_e32 v60, v32
	v_pk_mul_f32 v[28:29], v[34:35], v[28:29]
	v_pk_mul_f32 v[52:53], v[60:61], v[52:53]
	s_nop 7
	s_nop 1
	v_cvt_pk_bf16_f32 v29, v53, v29
	v_cvt_pk_bf16_f32 v28, v52, v28
	global_store_dwordx2 v[48:49], v[28:29], off offset:512
	global_load_dwordx4 v[28:31], v[36:37], off offset:2048
	v_mov_b32_e32 v33, v26
	v_mov_b32_e32 v26, v25
	v_mov_b32_e32 v32, v24
	v_pk_mul_f32 v[24:25], v[26:27], v[50:51] op_sel_hi:[1,0]
	v_pk_mul_f32 v[32:33], v[32:33], v[50:51] op_sel_hi:[1,0]
	s_waitcnt vmcnt(0)
	v_mov_b32_e32 v35, v30
	v_mov_b32_e32 v30, v29
	v_mov_b32_e32 v34, v28
	v_pk_mul_f32 v[24:25], v[30:31], v[24:25]
	v_pk_mul_f32 v[32:33], v[34:35], v[32:33]
	s_nop 7
	s_nop 1
	v_cvt_pk_bf16_f32 v25, v33, v25
	v_cvt_pk_bf16_f32 v24, v32, v24
	global_store_dwordx2 v[48:49], v[24:25], off offset:1024
	global_load_dwordx4 v[24:27], v[36:37], off offset:3072
	v_mov_b32_e32 v29, v22
	v_mov_b32_e32 v22, v21
	v_mov_b32_e32 v28, v20
	v_pk_mul_f32 v[20:21], v[22:23], v[50:51] op_sel_hi:[1,0]
	v_pk_mul_f32 v[28:29], v[28:29], v[50:51] op_sel_hi:[1,0]
	s_waitcnt vmcnt(0)
	v_mov_b32_e32 v31, v26
	v_mov_b32_e32 v26, v25
	v_mov_b32_e32 v30, v24
	v_pk_mul_f32 v[20:21], v[26:27], v[20:21]
	v_pk_mul_f32 v[28:29], v[30:31], v[28:29]
	s_nop 7
	s_nop 1
	v_cvt_pk_bf16_f32 v21, v29, v21
	v_cvt_pk_bf16_f32 v20, v28, v20
	global_store_dwordx2 v[48:49], v[20:21], off offset:1536
	global_load_dwordx4 v[20:23], v[38:39], off
	v_mov_b32_e32 v25, v14
	v_mov_b32_e32 v14, v13
	v_mov_b32_e32 v24, v12
	v_pk_mul_f32 v[12:13], v[14:15], v[50:51] op_sel_hi:[1,0]
	v_pk_mul_f32 v[24:25], v[24:25], v[50:51] op_sel_hi:[1,0]
	s_waitcnt vmcnt(0)
	v_mov_b32_e32 v27, v22
	v_mov_b32_e32 v22, v21
	v_mov_b32_e32 v26, v20
	v_pk_mul_f32 v[12:13], v[22:23], v[12:13]
	v_pk_mul_f32 v[24:25], v[26:27], v[24:25]
	s_nop 7
	s_nop 1
	v_cvt_pk_bf16_f32 v13, v25, v13
	v_cvt_pk_bf16_f32 v12, v24, v12
	global_store_dwordx2 v[48:49], v[12:13], off offset:2048
	global_load_dwordx4 v[12:15], v[40:41], off
	v_mov_b32_e32 v21, v18
	v_mov_b32_e32 v18, v17
	v_mov_b32_e32 v20, v16
	v_pk_mul_f32 v[16:17], v[18:19], v[50:51] op_sel_hi:[1,0]
	v_pk_mul_f32 v[20:21], v[20:21], v[50:51] op_sel_hi:[1,0]
	s_waitcnt vmcnt(0)
	v_mov_b32_e32 v23, v14
	v_mov_b32_e32 v14, v13
	v_mov_b32_e32 v22, v12
	v_pk_mul_f32 v[12:13], v[14:15], v[16:17]
	v_pk_mul_f32 v[20:21], v[22:23], v[20:21]
	s_nop 7
	s_nop 1
	v_cvt_pk_bf16_f32 v13, v21, v13
	v_cvt_pk_bf16_f32 v12, v20, v12
	global_store_dwordx2 v[48:49], v[12:13], off offset:2560
	global_load_dwordx4 v[12:15], v[42:43], off
	v_mov_b32_e32 v17, v10
	v_mov_b32_e32 v10, v9
	v_mov_b32_e32 v16, v8
	v_pk_mul_f32 v[8:9], v[10:11], v[50:51] op_sel_hi:[1,0]
	v_pk_mul_f32 v[16:17], v[16:17], v[50:51] op_sel_hi:[1,0]
	s_waitcnt vmcnt(0)
	v_mov_b32_e32 v19, v14
	v_mov_b32_e32 v14, v13
	v_mov_b32_e32 v18, v12
	v_pk_mul_f32 v[8:9], v[8:9], v[14:15]
	v_pk_mul_f32 v[16:17], v[16:17], v[18:19]
	s_nop 7
	s_nop 1
	v_cvt_pk_bf16_f32 v9, v17, v9
	v_cvt_pk_bf16_f32 v8, v16, v8
	global_store_dwordx2 v[48:49], v[8:9], off offset:3072
	global_load_dwordx4 v[8:11], v[44:45], off
	v_mov_b32_e32 v13, v6
	v_mov_b32_e32 v6, v5
	v_mov_b32_e32 v12, v4
	v_pk_mul_f32 v[4:5], v[6:7], v[50:51] op_sel_hi:[1,0]
	v_pk_mul_f32 v[12:13], v[12:13], v[50:51] op_sel_hi:[1,0]
	s_waitcnt vmcnt(0)
	v_mov_b32_e32 v15, v10
	v_mov_b32_e32 v10, v9
	v_mov_b32_e32 v14, v8
	v_pk_mul_f32 v[4:5], v[4:5], v[10:11]
	v_pk_mul_f32 v[12:13], v[12:13], v[14:15]
	v_and_b32_sdwa v8, v5, v59 dst_sel:DWORD dst_unused:UNUSED_PAD src0_sel:WORD_1 src1_sel:DWORD
	v_and_b32_sdwa v9, v4, v59 dst_sel:DWORD dst_unused:UNUSED_PAD src0_sel:WORD_1 src1_sel:DWORD
	v_and_b32_sdwa v6, v13, v59 dst_sel:DWORD dst_unused:UNUSED_PAD src0_sel:WORD_1 src1_sel:DWORD
	v_and_b32_sdwa v7, v12, v59 dst_sel:DWORD dst_unused:UNUSED_PAD src0_sel:WORD_1 src1_sel:DWORD
	v_add3_u32 v5, v5, v8, s3
	v_add3_u32 v4, v4, v9, s3
	v_add3_u32 v7, v12, v7, s3
	v_add3_u32 v6, v13, v6, s3
	v_and_b32_e32 v5, 0xffff0000, v5
	v_and_b32_e32 v4, 0xffff0000, v4
	v_or_b32_sdwa v5, v5, v6 dst_sel:DWORD dst_unused:UNUSED_PAD src0_sel:DWORD src1_sel:WORD_1
	v_or_b32_sdwa v4, v4, v7 dst_sel:DWORD dst_unused:UNUSED_PAD src0_sel:DWORD src1_sel:WORD_1
	global_store_dwordx2 v[48:49], v[4:5], off offset:3584
	v_lshl_add_u64 v[48:49], v[48:49], 0, s[8:9]
	s_cbranch_scc1 .LBB0_1590

; __device__ __forceinline__ unsigned pk2(float lo, float hi) { return f2bf(lo) | (f2bf(hi) << 16); }
; __device__ __forceinline__ void rms_row_bf16(const Ctx& c, const float* xrow, const float* gain, bf16* orow, float* copy) {
;     const f32x4* xr = (const f32x4*)xrow + c.lane; f32x4 v[8]; float s = 0.f;
; #pragma unroll
;     for (int j = 0; j < 8; ++j) { v[j] = xr[64 * j]; s += (v[j].x * v[j].x + v[j].y * v[j].y) + (v[j].z * v[j].z + v[j].w * v[j].w); }
;     const float rs = rsqrtf(wave_sum(s) * (1.f / DM) + EPS);
;     if (copy) {
; #pragma unroll
;         for (int j = 0; j < 8; ++j) ((f32x4*)copy + c.lane)[64 * j] = v[j]; }
;     const f32x4* gr = (const f32x4*)gain + c.lane; v2u* o8 = (v2u*)orow + c.lane;
; #pragma unroll
;     for (int j = 0; j < 8; ++j) { const f32x4 g = gr[64 * j]; v2u o; o.x = pk2(v[j].x * rs * g.x, v[j].y * rs * g.y); o.y = pk2(v[j].z * rs * g.z, v[j].w * rs * g.w); o8[64 * j] = o; }
.LBB0_3314:
	global_load_dwordx4 v[32:35], v[46:47], off offset:-4096
	global_load_dwordx4 v[28:31], v[46:47], off offset:-3072
	global_load_dwordx4 v[24:27], v[46:47], off offset:-2048
	global_load_dwordx4 v[20:23], v[46:47], off offset:-1024
	global_load_dwordx4 v[12:15], v[46:47], off
	global_load_dwordx4 v[16:19], v[46:47], off offset:1024
	s_add_i32 s6, s6, s86
	s_cmpk_lt_i32 s6, 0x400
	s_waitcnt vmcnt(0)
	v_mov_b32_e32 v6, v33
	v_mov_b32_e32 v7, v29
	v_mov_b32_e32 v4, v32
	v_mov_b32_e32 v5, v28
	v_pk_mul_f32 v[6:7], v[6:7], v[6:7]
	v_mov_b32_e32 v8, v35
	v_mov_b32_e32 v9, v31
	v_pk_fma_f32 v[4:5], v[4:5], v[4:5], v[6:7]
	v_mov_b32_e32 v6, v34
	v_mov_b32_e32 v7, v30
	v_pk_mul_f32 v[8:9], v[8:9], v[8:9]
	s_nop 0
	v_pk_fma_f32 v[6:7], v[6:7], v[6:7], v[8:9]
	v_pk_mul_f32 v[8:9], v[24:25], v[24:25]
	v_pk_add_f32 v[4:5], v[4:5], v[6:7]
	v_pk_mul_f32 v[6:7], v[26:27], v[26:27]
	v_pk_add_f32 v[4:5], v[4:5], v[4:5] op_sel:[0,1] op_sel_hi:[1,0]
	v_pk_mov_b32 v[10:11], v[8:9], v[6:7] op_sel:[1,0]
	v_mov_b32_e32 v9, v7
	v_pk_add_f32 v[6:7], v[10:11], v[8:9]
	v_mul_f32_e32 v8, v12, v12
	v_mul_f32_e32 v9, v13, v13
	v_pk_add_f32 v[6:7], v[6:7], v[6:7] op_sel:[0,1] op_sel_hi:[1,0]
	v_mov_b32_e32 v5, v8
	v_mov_b32_e32 v7, v9
	v_pk_add_f32 v[4:5], v[4:5], v[6:7]
	v_mul_f32_e32 v6, v21, v21
	v_mul_f32_e32 v8, v23, v23
	v_mul_f32_e32 v10, v14, v14
	v_mul_f32_e32 v11, v15, v15
	v_pk_fma_f32 v[6:7], v[20:21], v[20:21], v[6:7] op_sel_hi:[1,1,0]
	v_pk_fma_f32 v[8:9], v[22:23], v[22:23], v[8:9] op_sel_hi:[1,1,0]
	v_mov_b32_e32 v7, v10
	v_mov_b32_e32 v9, v11
	v_pk_add_f32 v[6:7], v[6:7], v[8:9]
	s_nop 0
	v_pk_add_f32 v[52:53], v[4:5], v[6:7]
	v_pk_mul_f32 v[4:5], v[18:19], v[18:19]
	v_pk_mul_f32 v[6:7], v[16:17], v[16:17]
	v_pk_add_f32 v[52:53], v[52:53], v[52:53] op_sel:[0,1] op_sel_hi:[1,0]
	v_pk_mov_b32 v[8:9], v[6:7], v[4:5] op_sel:[1,0]
	v_mov_b32_e32 v7, v5
	v_pk_add_f32 v[60:61], v[8:9], v[6:7]
	global_load_dwordx4 v[8:11], v[46:47], off offset:2048
	global_load_dwordx4 v[4:7], v[46:47], off offset:3072
	v_pk_add_f32 v[60:61], v[60:61], v[60:61] op_sel:[0,1] op_sel_hi:[1,0]
	v_lshl_add_u64 v[46:47], v[46:47], 0, s[8:9]
	s_waitcnt vmcnt(0)
	v_mul_f32_e32 v50, v4, v4
	v_mul_f32_e32 v62, v5, v5
	v_mov_b32_e32 v53, v50
	v_mov_b32_e32 v61, v62
	v_mul_f32_e32 v50, v9, v9
	v_mul_f32_e32 v63, v6, v6
	v_pk_add_f32 v[52:53], v[52:53], v[60:61]
	v_pk_fma_f32 v[60:61], v[8:9], v[8:9], v[50:51] op_sel_hi:[1,1,0]
	v_mul_f32_e32 v50, v11, v11
	v_mul_f32_e32 v64, v7, v7
	v_mov_b32_e32 v61, v63
	v_pk_fma_f32 v[62:63], v[10:11], v[10:11], v[50:51] op_sel_hi:[1,1,0]
	s_nop 0
	v_mov_b32_e32 v63, v64
	v_pk_add_f32 v[60:61], v[60:61], v[62:63]
	s_nop 0
	v_pk_add_f32 v[52:53], v[52:53], v[60:61]
	global_load_dwordx4 v[60:63], v[36:37], off
	v_add_f32_e32 v50, v52, v53
	v_mov_b32_e32 v53, v34
	v_mov_b32_e32 v34, v33
	s_waitcnt lgkmcnt(0)
	s_nop 1
	v_add_f32_dpp v50, v50, v50 quad_perm:[1,0,3,2] row_mask:0xf bank_mask:0xf
	s_waitcnt lgkmcnt(0)
	s_nop 1
	v_add_f32_dpp v50, v50, v50 quad_perm:[2,3,0,1] row_mask:0xf bank_mask:0xf
	s_waitcnt lgkmcnt(0)
	s_nop 1
	v_add_f32_dpp v50, v50, v50 row_half_mirror row_mask:0xf bank_mask:0xf
	s_waitcnt lgkmcnt(0)
	s_nop 1
	v_add_f32_dpp v50, v50, v50 row_mirror row_mask:0xf bank_mask:0xf
	s_waitcnt lgkmcnt(0)
	v_mov_b32_e32 v52, v50
	s_nop 1
	v_permlane16_swap_b32_e32 v50, v52
	v_add_f32_e32 v50, v50, v52
	s_waitcnt lgkmcnt(0)
	v_mov_b32_e32 v52, v50
	s_nop 1
	v_permlane32_swap_b32_e32 v50, v52
	v_add_f32_e32 v50, v50, v52
	v_fmamk_f32 v50, v50, 0x3a000000, v58
	v_cmp_gt_f32_e32 vcc, s12, v50
	v_mul_f32_e32 v52, 0x4b800000, v50
	s_waitcnt vmcnt(0)
	v_mov_b32_e32 v64, v60
	v_cndmask_b32_e32 v50, v50, v52, vcc
	v_rsq_f32_e32 v50, v50
	v_mov_b32_e32 v65, v62
	v_mov_b32_e32 v62, v61
	v_mul_f32_e32 v52, 0x45800000, v50
	v_cndmask_b32_e32 v50, v50, v52, vcc
	v_mov_b32_e32 v52, v32
	v_pk_mul_f32 v[52:53], v[52:53], v[50:51] op_sel_hi:[1,0]
	v_pk_mul_f32 v[32:33], v[34:35], v[50:51] op_sel_hi:[1,0]
	v_pk_mul_f32 v[52:53], v[64:65], v[52:53]
	v_pk_mul_f32 v[32:33], v[62:63], v[32:33]
	v_and_b32_sdwa v34, v53, v59 dst_sel:DWORD dst_unused:UNUSED_PAD src0_sel:WORD_1 src1_sel:DWORD
	v_and_b32_sdwa v35, v52, v59 dst_sel:DWORD dst_unused:UNUSED_PAD src0_sel:WORD_1 src1_sel:DWORD
	v_add3_u32 v35, v52, v35, s7
	v_add3_u32 v34, v53, v34, s7
	v_and_b32_sdwa v52, v33, v59 dst_sel:DWORD dst_unused:UNUSED_PAD src0_sel:WORD_1 src1_sel:DWORD
	v_and_b32_sdwa v53, v32, v59 dst_sel:DWORD dst_unused:UNUSED_PAD src0_sel:WORD_1 src1_sel:DWORD
	v_add3_u32 v33, v33, v52, s7
	v_add3_u32 v32, v32, v53, s7
	v_and_b32_e32 v33, 0xffff0000, v33
	v_and_b32_e32 v32, 0xffff0000, v32
	v_or_b32_sdwa v33, v33, v34 dst_sel:DWORD dst_unused:UNUSED_PAD src0_sel:DWORD src1_sel:WORD_1
	v_or_b32_sdwa v32, v32, v35 dst_sel:DWORD dst_unused:UNUSED_PAD src0_sel:DWORD src1_sel:WORD_1
	global_store_dwordx2 v[48:49], v[32:33], off
	global_load_dwordx4 v[32:35], v[36:37], off offset:1024
	v_mov_b32_e32 v53, v30
	v_mov_b32_e32 v30, v29
	v_mov_b32_e32 v52, v28
	v_pk_mul_f32 v[28:29], v[30:31], v[50:51] op_sel_hi:[1,0]
	v_pk_mul_f32 v[52:53], v[52:53], v[50:51] op_sel_hi:[1,0]
	s_waitcnt vmcnt(0)
; __device__ __forceinline__ unsigned pk2(float lo, float hi) { return f2bf(lo) | (f2bf(hi) << 16); }
; __device__ __forceinline__ void rms_row_bf16(const Ctx& c, const float* xrow, const float* gain, bf16* orow, float* copy) {
;     ...
;     const f32x4* gr = (const f32x4*)gain + c.lane; v2u* o8 = (v2u*)orow + c.lane;
; #pragma unroll
;     for (int j = 0; j < 8; ++j) { const f32x4 g = gr[64 * j]; v2u o; o.x = pk2(v[j].x * rs * g.x, v[j].y * rs * g.y); o.y = pk2(v[j].z * rs * g.z, v[j].w * rs * g.w); o8[64 * j] = o; }
	v_mov_b32_e32 v61, v34
	v_mov_b32_e32 v34, v33
	v_mov_b32_e32 v60, v32
	v_pk_mul_f32 v[28:29], v[34:35], v[28:29]
	v_pk_mul_f32 v[52:53], v[60:61], v[52:53]
	s_nop 7
	s_nop 1
	v_cvt_pk_bf16_f32 v29, v53, v29
	v_cvt_pk_bf16_f32 v28, v52, v28
	global_store_dwordx2 v[48:49], v[28:29], off offset:512
	global_load_dwordx4 v[28:31], v[36:37], off offset:2048
	v_mov_b32_e32 v33, v26
	v_mov_b32_e32 v26, v25
	v_mov_b32_e32 v32, v24
	v_pk_mul_f32 v[24:25], v[26:27], v[50:51] op_sel_hi:[1,0]
	v_pk_mul_f32 v[32:33], v[32:33], v[50:51] op_sel_hi:[1,0]
	s_waitcnt vmcnt(0)
	v_mov_b32_e32 v35, v30
	v_mov_b32_e32 v30, v29
	v_mov_b32_e32 v34, v28
	v_pk_mul_f32 v[24:25], v[30:31], v[24:25]
	v_pk_mul_f32 v[32:33], v[34:35], v[32:33]
	s_nop 7
	s_nop 1
	v_cvt_pk_bf16_f32 v25, v33, v25
	v_cvt_pk_bf16_f32 v24, v32, v24
	global_store_dwordx2 v[48:49], v[24:25], off offset:1024
	global_load_dwordx4 v[24:27], v[36:37], off offset:3072
	v_mov_b32_e32 v29, v22
	v_mov_b32_e32 v22, v21
	v_mov_b32_e32 v28, v20
	v_pk_mul_f32 v[20:21], v[22:23], v[50:51] op_sel_hi:[1,0]
	v_pk_mul_f32 v[28:29], v[28:29], v[50:51] op_sel_hi:[1,0]
	s_waitcnt vmcnt(0)
	v_mov_b32_e32 v31, v26
	v_mov_b32_e32 v26, v25
	v_mov_b32_e32 v30, v24
	v_pk_mul_f32 v[20:21], v[26:27], v[20:21]
	v_pk_mul_f32 v[28:29], v[30:31], v[28:29]
	s_nop 7
	s_nop 1
	v_cvt_pk_bf16_f32 v21, v29, v21
	v_cvt_pk_bf16_f32 v20, v28, v20
	global_store_dwordx2 v[48:49], v[20:21], off offset:1536
	global_load_dwordx4 v[20:23], v[38:39], off
	v_mov_b32_e32 v25, v14
	v_mov_b32_e32 v14, v13
	v_mov_b32_e32 v24, v12
	v_pk_mul_f32 v[12:13], v[14:15], v[50:51] op_sel_hi:[1,0]
	v_pk_mul_f32 v[24:25], v[24:25], v[50:51] op_sel_hi:[1,0]
	s_waitcnt vmcnt(0)
	v_mov_b32_e32 v27, v22
	v_mov_b32_e32 v22, v21
	v_mov_b32_e32 v26, v20
	v_pk_mul_f32 v[12:13], v[22:23], v[12:13]
	v_pk_mul_f32 v[24:25], v[26:27], v[24:25]
	s_nop 7
	s_nop 1
	v_cvt_pk_bf16_f32 v13, v25, v13
	v_cvt_pk_bf16_f32 v12, v24, v12
	global_store_dwordx2 v[48:49], v[12:13], off offset:2048
	global_load_dwordx4 v[12:15], v[40:41], off
	v_mov_b32_e32 v21, v18
	v_mov_b32_e32 v18, v17
	v_mov_b32_e32 v20, v16
	v_pk_mul_f32 v[16:17], v[18:19], v[50:51] op_sel_hi:[1,0]
	v_pk_mul_f32 v[20:21], v[20:21], v[50:51] op_sel_hi:[1,0]
	s_waitcnt vmcnt(0)
	v_mov_b32_e32 v23, v14
	v_mov_b32_e32 v14, v13
	v_mov_b32_e32 v22, v12
	v_pk_mul_f32 v[12:13], v[14:15], v[16:17]
	v_pk_mul_f32 v[20:21], v[22:23], v[20:21]
	s_nop 7
	s_nop 1
	v_cvt_pk_bf16_f32 v13, v21, v13
	v_cvt_pk_bf16_f32 v12, v20, v12
	global_store_dwordx2 v[48:49], v[12:13], off offset:2560
	global_load_dwordx4 v[12:15], v[42:43], off
	v_mov_b32_e32 v17, v10
	v_mov_b32_e32 v10, v9
	v_mov_b32_e32 v16, v8
	v_pk_mul_f32 v[8:9], v[10:11], v[50:51] op_sel_hi:[1,0]
	v_pk_mul_f32 v[16:17], v[16:17], v[50:51] op_sel_hi:[1,0]
	s_waitcnt vmcnt(0)
	v_mov_b32_e32 v19, v14
	v_mov_b32_e32 v14, v13
	v_mov_b32_e32 v18, v12
	v_pk_mul_f32 v[8:9], v[8:9], v[14:15]
	v_pk_mul_f32 v[16:17], v[16:17], v[18:19]
	s_nop 7
	s_nop 1
	v_cvt_pk_bf16_f32 v9, v17, v9
	v_cvt_pk_bf16_f32 v8, v16, v8
	global_store_dwordx2 v[48:49], v[8:9], off offset:3072
	global_load_dwordx4 v[8:11], v[44:45], off
	v_mov_b32_e32 v13, v6
	v_mov_b32_e32 v6, v5
	v_mov_b32_e32 v12, v4
	v_pk_mul_f32 v[4:5], v[6:7], v[50:51] op_sel_hi:[1,0]
	v_pk_mul_f32 v[12:13], v[12:13], v[50:51] op_sel_hi:[1,0]
	s_waitcnt vmcnt(0)
	v_mov_b32_e32 v15, v10
	v_mov_b32_e32 v10, v9
	v_mov_b32_e32 v14, v8
	v_pk_mul_f32 v[4:5], v[4:5], v[10:11]
	v_pk_mul_f32 v[12:13], v[12:13], v[14:15]
	v_and_b32_sdwa v8, v5, v59 dst_sel:DWORD dst_unused:UNUSED_PAD src0_sel:WORD_1 src1_sel:DWORD
	v_and_b32_sdwa v9, v4, v59 dst_sel:DWORD dst_unused:UNUSED_PAD src0_sel:WORD_1 src1_sel:DWORD
	v_and_b32_sdwa v6, v13, v59 dst_sel:DWORD dst_unused:UNUSED_PAD src0_sel:WORD_1 src1_sel:DWORD
	v_and_b32_sdwa v7, v12, v59 dst_sel:DWORD dst_unused:UNUSED_PAD src0_sel:WORD_1 src1_sel:DWORD
	v_add3_u32 v5, v5, v8, s7
	v_add3_u32 v4, v4, v9, s7
	v_add3_u32 v7, v12, v7, s7
	v_add3_u32 v6, v13, v6, s7
	v_and_b32_e32 v5, 0xffff0000, v5
	v_and_b32_e32 v4, 0xffff0000, v4
	v_or_b32_sdwa v5, v5, v6 dst_sel:DWORD dst_unused:UNUSED_PAD src0_sel:DWORD src1_sel:WORD_1
	v_or_b32_sdwa v4, v4, v7 dst_sel:DWORD dst_unused:UNUSED_PAD src0_sel:DWORD src1_sel:WORD_1
	global_store_dwordx2 v[48:49], v[4:5], off offset:3584
	v_lshl_add_u64 v[48:49], v[48:49], 0, s[10:11]
	s_cbranch_scc1 .LBB0_3314

; __device__ __forceinline__ void sgu_ln(const Ctx& c, bf16* P, const float* g) {
;     for (int row = c.gw; row < MT; row += c.NGW) {
;         v4u* vr = (v4u*)(P + (size_t)row * 8192 + 4096) + c.lane;
;         float v[8][8]; float s = 0.f;
; #pragma unroll
;         for (int j = 0; j < 8; ++j) { const v4u y = vr[64 * j];
; #pragma unroll
;             for (int k = 0; k < 4; ++k) { v[j][2 * k] = bflo(y[k]); v[j][2 * k + 1] = bfhi(y[k]); s += v[j][2 * k] + v[j][2 * k + 1]; } }
;         const float mu = wave_sum(s) * (1.f / 4096.f); float q = 0.f;
.LBB0_3519:
	global_load_dwordx4 v[72:75], v[66:67], off
	global_load_dwordx4 v[76:79], v[66:67], off offset:1024
	global_load_dwordx4 v[80:83], v[66:67], off offset:2048
	global_load_dwordx4 v[84:87], v[66:67], off offset:3072
	v_add_co_u32_e32 v70, vcc, s8, v66
	s_add_i32 s11, s11, s86
	s_nop 0
	v_addc_co_u32_e32 v71, vcc, 0, v67, vcc
	global_load_dwordx4 v[88:91], v[70:71], off offset:3072
	global_load_dwordx4 v[92:95], v[70:71], off
	global_load_dwordx4 v[96:99], v[70:71], off offset:1024
	global_load_dwordx4 v[100:103], v[70:71], off offset:2048
	s_cmpk_lt_i32 s11, 0x4000
	s_waitcnt vmcnt(7)
	v_lshlrev_b32_e32 v113, 16, v73
	v_lshlrev_b32_e32 v112, 16, v72
	v_and_b32_e32 v73, 0xffff0000, v73
	v_and_b32_e32 v72, 0xffff0000, v72
	v_pk_add_f32 v[128:129], v[112:113], v[72:73]
	v_lshlrev_b32_e32 v115, 16, v75
	v_lshlrev_b32_e32 v114, 16, v74
	v_and_b32_e32 v75, 0xffff0000, v75
	v_and_b32_e32 v74, 0xffff0000, v74
	v_add_f32_e32 v104, 0, v128
	v_pk_add_f32 v[130:131], v[114:115], v[74:75]
	v_add_f32_e32 v104, v129, v104
	s_waitcnt vmcnt(6)
	v_lshlrev_b32_e32 v117, 16, v77
	v_lshlrev_b32_e32 v116, 16, v76
	v_and_b32_e32 v77, 0xffff0000, v77
	v_and_b32_e32 v76, 0xffff0000, v76
	v_add_f32_e32 v104, v130, v104
	v_pk_add_f32 v[132:133], v[116:117], v[76:77]
	v_add_f32_e32 v104, v131, v104
	v_lshlrev_b32_e32 v119, 16, v79
	v_lshlrev_b32_e32 v118, 16, v78
	v_and_b32_e32 v79, 0xffff0000, v79
	v_and_b32_e32 v78, 0xffff0000, v78
	v_add_f32_e32 v104, v132, v104
	v_pk_add_f32 v[134:135], v[118:119], v[78:79]
	v_add_f32_e32 v104, v133, v104
	s_waitcnt vmcnt(5)
	v_lshlrev_b32_e32 v121, 16, v81
	v_lshlrev_b32_e32 v120, 16, v80
	v_and_b32_e32 v81, 0xffff0000, v81
	v_and_b32_e32 v80, 0xffff0000, v80
	v_add_f32_e32 v104, v134, v104
	v_pk_add_f32 v[136:137], v[120:121], v[80:81]
	v_add_f32_e32 v104, v135, v104
	v_lshlrev_b32_e32 v123, 16, v83
	v_lshlrev_b32_e32 v122, 16, v82
	v_and_b32_e32 v83, 0xffff0000, v83
	v_and_b32_e32 v82, 0xffff0000, v82
	v_add_f32_e32 v104, v136, v104
	v_pk_add_f32 v[138:139], v[122:123], v[82:83]
	v_add_f32_e32 v104, v137, v104
	s_waitcnt vmcnt(4)
	v_lshlrev_b32_e32 v125, 16, v85
	v_lshlrev_b32_e32 v124, 16, v84
	v_and_b32_e32 v85, 0xffff0000, v85
	v_and_b32_e32 v84, 0xffff0000, v84
	v_add_f32_e32 v104, v138, v104
	v_pk_add_f32 v[140:141], v[124:125], v[84:85]
	v_add_f32_e32 v104, v139, v104
	v_lshlrev_b32_e32 v127, 16, v87
	v_lshlrev_b32_e32 v126, 16, v86
	v_and_b32_e32 v87, 0xffff0000, v87
	v_and_b32_e32 v86, 0xffff0000, v86
	v_add_f32_e32 v104, v140, v104
	v_pk_add_f32 v[142:143], v[126:127], v[86:87]
	v_add_f32_e32 v104, v141, v104
	s_waitcnt vmcnt(3)
	v_lshlrev_b32_e32 v145, 16, v89
	v_lshlrev_b32_e32 v144, 16, v88
	v_and_b32_e32 v147, 0xffff0000, v89
	v_and_b32_e32 v146, 0xffff0000, v88
	v_lshlrev_b32_e32 v149, 16, v91
	v_lshlrev_b32_e32 v148, 16, v90
	v_and_b32_e32 v151, 0xffff0000, v91
	v_and_b32_e32 v150, 0xffff0000, v90
	s_waitcnt vmcnt(2)
	v_lshlrev_b32_e32 v89, 16, v93
	v_lshlrev_b32_e32 v88, 16, v92
	v_and_b32_e32 v91, 0xffff0000, v93
	v_and_b32_e32 v90, 0xffff0000, v92
	v_add_f32_e32 v104, v142, v104
	v_pk_add_f32 v[128:129], v[88:89], v[90:91]
	v_add_f32_e32 v104, v143, v104
	v_lshlrev_b32_e32 v93, 16, v95
	v_lshlrev_b32_e32 v92, 16, v94
	v_and_b32_e32 v95, 0xffff0000, v95
	v_and_b32_e32 v94, 0xffff0000, v94
	v_add_f32_e32 v104, v128, v104
	v_pk_add_f32 v[160:161], v[92:93], v[94:95]
	v_add_f32_e32 v104, v129, v104
	s_waitcnt vmcnt(1)
	v_lshlrev_b32_e32 v153, 16, v97
	v_lshlrev_b32_e32 v152, 16, v96
	v_and_b32_e32 v155, 0xffff0000, v97
	v_and_b32_e32 v154, 0xffff0000, v96
	v_add_f32_e32 v104, v160, v104
	v_pk_add_f32 v[162:163], v[152:153], v[154:155]
	v_add_f32_e32 v104, v161, v104
	v_lshlrev_b32_e32 v157, 16, v99
	v_lshlrev_b32_e32 v156, 16, v98
	v_and_b32_e32 v159, 0xffff0000, v99
	v_and_b32_e32 v158, 0xffff0000, v98
	v_add_f32_e32 v104, v162, v104
	v_add_f32_e32 v104, v163, v104
	v_pk_add_f32 v[128:129], v[156:157], v[158:159]
	s_waitcnt vmcnt(0)
	v_and_b32_e32 v131, 0xffff0000, v101
	v_add_f32_e32 v104, v128, v104
	v_add_f32_e32 v104, v129, v104
	v_lshlrev_b32_e32 v129, 16, v101
	v_lshlrev_b32_e32 v128, 16, v100
	v_and_b32_e32 v130, 0xffff0000, v100
	v_pk_add_f32 v[100:101], v[128:129], v[130:131]
	v_lshlrev_b32_e32 v133, 16, v103
	v_add_f32_e32 v100, v100, v104
	v_lshlrev_b32_e32 v132, 16, v102
	v_and_b32_e32 v135, 0xffff0000, v103
	v_and_b32_e32 v134, 0xffff0000, v102
	v_add_f32_e32 v104, v101, v100
	v_pk_add_f32 v[100:101], v[132:133], v[134:135]
	v_pk_add_f32 v[96:97], v[144:145], v[146:147]
	v_add_f32_e32 v100, v100, v104
	v_add_f32_e32 v100, v101, v100
	v_add_f32_e32 v96, v96, v100
	v_pk_add_f32 v[98:99], v[148:149], v[150:151]
	v_add_f32_e32 v96, v97, v96
	v_add_f32_e32 v96, v98, v96
	v_add_f32_e32 v96, v99, v96
	s_waitcnt lgkmcnt(0)
	s_nop 1
	v_add_f32_dpp v96, v96, v96 quad_perm:[1,0,3,2] row_mask:0xf bank_mask:0xf
	s_waitcnt lgkmcnt(0)
	s_nop 1
	v_add_f32_dpp v96, v96, v96 quad_perm:[2,3,0,1] row_mask:0xf bank_mask:0xf
	s_waitcnt lgkmcnt(0)
	s_nop 1
	v_add_f32_dpp v96, v96, v96 row_half_mirror row_mask:0xf bank_mask:0xf
	s_waitcnt lgkmcnt(0)
	s_nop 1
	v_add_f32_dpp v96, v96, v96 row_mirror row_mask:0xf bank_mask:0xf
	s_waitcnt lgkmcnt(0)
	v_mov_b32_e32 v97, v96
	s_nop 1
	v_permlane16_swap_b32_e32 v96, v97
	v_add_f32_e32 v96, v96, v97
	s_waitcnt lgkmcnt(0)
; __device__ __forceinline__ float wave_sum(float v) {
; #pragma unroll
;     for (int o = 1; o < 64; o <<= 1) v += __shfl_xor(v, o);
;     return v;
; __device__ __forceinline__ void sgu_ln(const Ctx& c, bf16* P, const float* g) {
;     ...
;         for (int j = 0; j < 8; ++j) { const v4u y = vr[64 * j];
; #pragma unroll
;             for (int k = 0; k < 4; ++k) { v[j][2 * k] = bflo(y[k]); v[j][2 * k + 1] = bfhi(y[k]); s += v[j][2 * k] + v[j][2 * k + 1]; } }
;         const float mu = wave_sum(s) * (1.f / 4096.f); float q = 0.f;
; #pragma unroll
;         for (int j = 0; j < 8; ++j)
; #pragma unroll
;             for (int k = 0; k < 8; ++k) { v[j][k] -= mu; q += v[j][k] * v[j][k]; }
;         const float rs = rsqrtf(wave_sum(q) * (1.f / 4096.f) + EPS);
	v_mov_b32_e32 v97, v96
	s_nop 1
	v_permlane32_swap_b32_e32 v96, v97
	v_add_f32_e32 v96, v96, v97
	v_mul_f32_e32 v104, 0x39800000, v96
	v_pk_add_f32 v[112:113], v[112:113], v[104:105] op_sel_hi:[1,0] neg_lo:[0,1] neg_hi:[0,1]
	v_pk_add_f32 v[136:137], v[72:73], v[104:105] op_sel_hi:[1,0] neg_lo:[0,1] neg_hi:[0,1]
	v_pk_mul_f32 v[160:161], v[112:113], v[112:113]
	v_pk_mul_f32 v[162:163], v[136:137], v[136:137]
	v_pk_add_f32 v[114:115], v[114:115], v[104:105] op_sel_hi:[1,0] neg_lo:[0,1] neg_hi:[0,1]
	v_pk_add_f32 v[138:139], v[74:75], v[104:105] op_sel_hi:[1,0] neg_lo:[0,1] neg_hi:[0,1]
	v_pk_add_f32 v[116:117], v[116:117], v[104:105] op_sel_hi:[1,0] neg_lo:[0,1] neg_hi:[0,1]
	v_pk_add_f32 v[140:141], v[76:77], v[104:105] op_sel_hi:[1,0] neg_lo:[0,1] neg_hi:[0,1]
	v_pk_add_f32 v[118:119], v[118:119], v[104:105] op_sel_hi:[1,0] neg_lo:[0,1] neg_hi:[0,1]
	v_pk_add_f32 v[142:143], v[78:79], v[104:105] op_sel_hi:[1,0] neg_lo:[0,1] neg_hi:[0,1]
	v_pk_add_f32 v[120:121], v[120:121], v[104:105] op_sel_hi:[1,0] neg_lo:[0,1] neg_hi:[0,1]
	v_pk_add_f32 v[180:181], v[80:81], v[104:105] op_sel_hi:[1,0] neg_lo:[0,1] neg_hi:[0,1]
	v_pk_add_f32 v[122:123], v[122:123], v[104:105] op_sel_hi:[1,0] neg_lo:[0,1] neg_hi:[0,1]
	v_pk_add_f32 v[186:187], v[82:83], v[104:105] op_sel_hi:[1,0] neg_lo:[0,1] neg_hi:[0,1]
	v_pk_add_f32 v[124:125], v[124:125], v[104:105] op_sel_hi:[1,0] neg_lo:[0,1] neg_hi:[0,1]
	v_pk_add_f32 v[192:193], v[84:85], v[104:105] op_sel_hi:[1,0] neg_lo:[0,1] neg_hi:[0,1]
	v_pk_add_f32 v[126:127], v[126:127], v[104:105] op_sel_hi:[1,0] neg_lo:[0,1] neg_hi:[0,1]
	v_pk_add_f32 v[198:199], v[86:87], v[104:105] op_sel_hi:[1,0] neg_lo:[0,1] neg_hi:[0,1]
	v_pk_add_f32 v[96:97], v[88:89], v[104:105] op_sel_hi:[1,0] neg_lo:[0,1] neg_hi:[0,1]
	v_pk_add_f32 v[98:99], v[90:91], v[104:105] op_sel_hi:[1,0] neg_lo:[0,1] neg_hi:[0,1]
	v_pk_add_f32 v[100:101], v[92:93], v[104:105] op_sel_hi:[1,0] neg_lo:[0,1] neg_hi:[0,1]
	v_pk_add_f32 v[102:103], v[94:95], v[104:105] op_sel_hi:[1,0] neg_lo:[0,1] neg_hi:[0,1]
	v_pk_add_f32 v[88:89], v[152:153], v[104:105] op_sel_hi:[1,0] neg_lo:[0,1] neg_hi:[0,1]
	v_pk_add_f32 v[90:91], v[154:155], v[104:105] op_sel_hi:[1,0] neg_lo:[0,1] neg_hi:[0,1]
	v_pk_add_f32 v[92:93], v[156:157], v[104:105] op_sel_hi:[1,0] neg_lo:[0,1] neg_hi:[0,1]
	v_pk_add_f32 v[94:95], v[158:159], v[104:105] op_sel_hi:[1,0] neg_lo:[0,1] neg_hi:[0,1]
	v_pk_add_f32 v[80:81], v[128:129], v[104:105] op_sel_hi:[1,0] neg_lo:[0,1] neg_hi:[0,1]
	v_pk_add_f32 v[82:83], v[130:131], v[104:105] op_sel_hi:[1,0] neg_lo:[0,1] neg_hi:[0,1]
	v_pk_add_f32 v[84:85], v[132:133], v[104:105] op_sel_hi:[1,0] neg_lo:[0,1] neg_hi:[0,1]
	v_pk_add_f32 v[86:87], v[134:135], v[104:105] op_sel_hi:[1,0] neg_lo:[0,1] neg_hi:[0,1]
	v_pk_add_f32 v[74:75], v[144:145], v[104:105] op_sel_hi:[1,0] neg_lo:[0,1] neg_hi:[0,1]
	v_pk_add_f32 v[76:77], v[146:147], v[104:105] op_sel_hi:[1,0] neg_lo:[0,1] neg_hi:[0,1]
	v_pk_add_f32 v[78:79], v[148:149], v[104:105] op_sel_hi:[1,0] neg_lo:[0,1] neg_hi:[0,1]
	v_pk_add_f32 v[72:73], v[150:151], v[104:105] op_sel_hi:[1,0] neg_lo:[0,1] neg_hi:[0,1]
	v_add_f32_e32 v104, v160, v162
	v_add_f32_e32 v104, v161, v104
	v_pk_mul_f32 v[166:167], v[114:115], v[114:115]
	v_add_f32_e32 v104, v163, v104
	v_pk_mul_f32 v[168:169], v[138:139], v[138:139]
	v_add_f32_e32 v104, v166, v104
	v_add_f32_e32 v104, v168, v104
	v_add_f32_e32 v104, v167, v104
	v_pk_mul_f32 v[170:171], v[116:117], v[116:117]
	v_add_f32_e32 v104, v169, v104
	v_pk_mul_f32 v[172:173], v[140:141], v[140:141]
	v_add_f32_e32 v104, v170, v104
	v_add_f32_e32 v104, v172, v104
	v_add_f32_e32 v104, v171, v104
	v_pk_mul_f32 v[174:175], v[118:119], v[118:119]
	v_add_f32_e32 v104, v173, v104
	v_pk_mul_f32 v[176:177], v[142:143], v[142:143]
	v_add_f32_e32 v104, v174, v104
	v_add_f32_e32 v104, v176, v104
	v_add_f32_e32 v104, v175, v104
	v_pk_mul_f32 v[178:179], v[120:121], v[120:121]
	v_add_f32_e32 v104, v177, v104
	v_pk_mul_f32 v[182:183], v[180:181], v[180:181]
	v_add_f32_e32 v104, v178, v104
	v_add_f32_e32 v104, v182, v104
	v_add_f32_e32 v104, v179, v104
	v_pk_mul_f32 v[184:185], v[122:123], v[122:123]
	v_add_f32_e32 v104, v183, v104
	v_pk_mul_f32 v[188:189], v[186:187], v[186:187]
	v_add_f32_e32 v104, v184, v104
	v_add_f32_e32 v104, v188, v104
	v_add_f32_e32 v104, v185, v104
	v_pk_mul_f32 v[190:191], v[124:125], v[124:125]
	v_add_f32_e32 v104, v189, v104
	v_pk_mul_f32 v[194:195], v[192:193], v[192:193]
	v_add_f32_e32 v104, v190, v104
	v_add_f32_e32 v104, v194, v104
	v_add_f32_e32 v104, v191, v104
	v_pk_mul_f32 v[196:197], v[126:127], v[126:127]
	v_add_f32_e32 v104, v195, v104
	v_pk_mul_f32 v[200:201], v[198:199], v[198:199]
	v_add_f32_e32 v104, v196, v104
	v_add_f32_e32 v104, v200, v104
	v_add_f32_e32 v104, v197, v104
	v_pk_mul_f32 v[202:203], v[96:97], v[96:97]
	v_add_f32_e32 v104, v201, v104
	v_pk_mul_f32 v[204:205], v[98:99], v[98:99]
	v_add_f32_e32 v104, v202, v104
	v_add_f32_e32 v104, v204, v104
	v_add_f32_e32 v104, v203, v104
	v_pk_mul_f32 v[206:207], v[100:101], v[100:101]
	v_add_f32_e32 v104, v205, v104
	v_pk_mul_f32 v[208:209], v[102:103], v[102:103]
	v_add_f32_e32 v104, v206, v104
	v_add_f32_e32 v104, v208, v104
	v_add_f32_e32 v104, v207, v104
	v_pk_mul_f32 v[152:153], v[88:89], v[88:89]
	v_add_f32_e32 v104, v209, v104
	v_pk_mul_f32 v[154:155], v[90:91], v[90:91]
	v_add_f32_e32 v104, v152, v104
	v_add_f32_e32 v104, v154, v104
	v_add_f32_e32 v104, v153, v104
	v_pk_mul_f32 v[156:157], v[92:93], v[92:93]
	v_add_f32_e32 v104, v155, v104
	v_pk_mul_f32 v[158:159], v[94:95], v[94:95]
	v_add_f32_e32 v104, v156, v104
	v_add_f32_e32 v104, v158, v104
	v_add_f32_e32 v104, v157, v104
	v_pk_mul_f32 v[128:129], v[80:81], v[80:81]
	v_add_f32_e32 v104, v159, v104
	v_pk_mul_f32 v[130:131], v[82:83], v[82:83]
	v_add_f32_e32 v104, v128, v104
	v_add_f32_e32 v104, v130, v104
	v_add_f32_e32 v104, v129, v104
	v_pk_mul_f32 v[132:133], v[84:85], v[84:85]
	v_add_f32_e32 v104, v131, v104
	v_pk_mul_f32 v[134:135], v[86:87], v[86:87]
	v_add_f32_e32 v104, v132, v104
	v_add_f32_e32 v104, v134, v104
	v_add_f32_e32 v104, v133, v104
	v_pk_mul_f32 v[144:145], v[74:75], v[74:75]
	v_add_f32_e32 v104, v135, v104
	v_pk_mul_f32 v[146:147], v[76:77], v[76:77]
	v_add_f32_e32 v104, v144, v104
	v_add_f32_e32 v104, v146, v104
	v_mov_b32_e32 v148, v72
	v_mov_b32_e32 v149, v78
	v_add_f32_e32 v104, v145, v104
	v_pk_mul_f32 v[148:149], v[148:149], v[148:149]
	v_add_f32_e32 v104, v147, v104
	v_mov_b32_e32 v150, v73
	v_mov_b32_e32 v151, v79
	v_add_f32_e32 v104, v149, v104
	v_pk_mul_f32 v[150:151], v[150:151], v[150:151]
	v_add_f32_e32 v104, v148, v104
	v_add_f32_e32 v104, v151, v104
	v_add_f32_e32 v104, v150, v104
	s_waitcnt lgkmcnt(0)
; __device__ __forceinline__ unsigned pk2(float lo, float hi) { return f2bf(lo) | (f2bf(hi) << 16); }
; __device__ __forceinline__ float wave_sum(float v) {
; #pragma unroll
;     for (int o = 1; o < 64; o <<= 1) v += __shfl_xor(v, o);
;     return v;
; __device__ __forceinline__ void sgu_ln(const Ctx& c, bf16* P, const float* g) {
;     ...
;         const float rs = rsqrtf(wave_sum(q) * (1.f / 4096.f) + EPS);
; #pragma unroll
;         for (int j = 0; j < 8; ++j) { const float* gg = g + (c.lane + 64 * j) * 8; const f32x4 g0 = *(CF4)gg, g1 = *(CF4)(gg + 4);
;             v4u w; w.x = pk2(v[j][0] * rs * g0.x, v[j][1] * rs * g0.y); w.y = pk2(v[j][2] * rs * g0.z, v[j][3] * rs * g0.w); w.z = pk2(v[j][4] * rs * g1.x, v[j][5] * rs * g1.y); w.w = pk2(v[j][6] * rs * g1.z, v[j][7] * rs * g1.w);
;             vr[64 * j] = w; }
	s_nop 1
	v_add_f32_dpp v104, v104, v104 quad_perm:[1,0,3,2] row_mask:0xf bank_mask:0xf
	s_waitcnt lgkmcnt(0)
	s_nop 1
	v_add_f32_dpp v104, v104, v104 quad_perm:[2,3,0,1] row_mask:0xf bank_mask:0xf
	s_waitcnt lgkmcnt(0)
	s_nop 1
	v_add_f32_dpp v104, v104, v104 row_half_mirror row_mask:0xf bank_mask:0xf
	s_waitcnt lgkmcnt(0)
	s_nop 1
	v_add_f32_dpp v104, v104, v104 row_mirror row_mask:0xf bank_mask:0xf
	s_waitcnt lgkmcnt(0)
	v_mov_b32_e32 v111, v104
	s_nop 1
	v_permlane16_swap_b32_e32 v104, v111
	v_add_f32_e32 v104, v104, v111
	s_waitcnt lgkmcnt(0)
	v_mov_b32_e32 v111, v104
	s_nop 1
	v_permlane32_swap_b32_e32 v104, v111
	v_add_f32_e32 v104, v104, v111
	v_fmamk_f32 v104, v104, 0x39800000, v110
	v_mul_f32_e32 v111, 0x4b800000, v104
	v_cmp_gt_f32_e32 vcc, s12, v104
	s_nop 1
	v_cndmask_b32_e32 v104, v104, v111, vcc
	v_rsq_f32_e32 v104, v104
	s_nop 0
	v_mul_f32_e32 v111, 0x45800000, v104
	v_cndmask_b32_e32 v104, v104, v111, vcc
	v_pk_mul_f32 v[128:129], v[136:137], v[104:105] op_sel_hi:[1,0]
	v_pk_mul_f32 v[130:131], v[138:139], v[104:105] op_sel_hi:[1,0]
	v_pk_mul_f32 v[112:113], v[112:113], v[104:105] op_sel_hi:[1,0]
	v_pk_mul_f32 v[128:129], v[68:69], v[128:129]
	v_pk_mul_f32 v[114:115], v[114:115], v[104:105] op_sel_hi:[1,0]
	v_pk_mul_f32 v[130:131], v[6:7], v[130:131]
	v_pk_mul_f32 v[112:113], v[4:5], v[112:113]
	v_pk_mul_f32 v[114:115], v[8:9], v[114:115]
	v_bfe_u32 v111, v131, 16, 1
	s_nop 5
	v_add3_u32 v111, v131, v111, s10
	s_nop 2
	v_bfe_u32 v134, v115, 16, 1
	v_add3_u32 v115, v115, v134, s10
	s_nop 5
	v_lshrrev_b32_e32 v115, 16, v115
	v_and_or_b32 v115, v111, s9, v115
	v_cvt_pk_bf16_f32 v114, v114, v130
	v_cvt_pk_bf16_f32 v113, v113, v129
	v_cvt_pk_bf16_f32 v112, v112, v128
	global_store_dwordx4 v[66:67], v[112:115], off
	v_pk_mul_f32 v[98:99], v[98:99], v[104:105] op_sel_hi:[1,0]
	v_pk_mul_f32 v[102:103], v[102:103], v[104:105] op_sel_hi:[1,0]
	v_pk_mul_f32 v[112:113], v[116:117], v[104:105] op_sel_hi:[1,0]
	v_pk_mul_f32 v[114:115], v[140:141], v[104:105] op_sel_hi:[1,0]
	v_pk_mul_f32 v[116:117], v[118:119], v[104:105] op_sel_hi:[1,0]
	v_pk_mul_f32 v[118:119], v[142:143], v[104:105] op_sel_hi:[1,0]
	v_pk_mul_f32 v[114:115], v[10:11], v[114:115]
	v_pk_mul_f32 v[118:119], v[14:15], v[118:119]
	v_pk_mul_f32 v[112:113], v[12:13], v[112:113]
	v_pk_mul_f32 v[116:117], v[16:17], v[116:117]
	v_bfe_u32 v111, v119, 16, 1
	v_bfe_u32 v128, v118, 16, 1
	v_bfe_u32 v129, v115, 16, 1
	v_bfe_u32 v130, v114, 16, 1
	v_add3_u32 v130, v114, v130, s10
	v_add3_u32 v129, v115, v129, s10
	v_add3_u32 v114, v118, v128, s10
	v_add3_u32 v111, v119, v111, s10
	v_bfe_u32 v115, v112, 16, 1
	v_bfe_u32 v118, v113, 16, 1
	v_bfe_u32 v119, v116, 16, 1
	v_bfe_u32 v128, v117, 16, 1
	v_add3_u32 v117, v117, v128, s10
	v_add3_u32 v116, v116, v119, s10
	v_add3_u32 v113, v113, v118, s10
	v_add3_u32 v112, v112, v115, s10
	v_lshrrev_b32_e32 v112, 16, v112
	v_lshrrev_b32_e32 v113, 16, v113
	v_lshrrev_b32_e32 v116, 16, v116
	v_lshrrev_b32_e32 v115, 16, v117
	v_and_or_b32 v115, v111, s9, v115
	v_and_or_b32 v114, v114, s9, v116
	v_and_or_b32 v113, v129, s9, v113
	v_and_or_b32 v112, v130, s9, v112
	global_store_dwordx4 v[66:67], v[112:115], off offset:1024
	v_pk_mul_f32 v[118:119], v[186:187], v[104:105] op_sel_hi:[1,0]
	v_pk_mul_f32 v[116:117], v[122:123], v[104:105] op_sel_hi:[1,0]
	v_pk_mul_f32 v[114:115], v[180:181], v[104:105] op_sel_hi:[1,0]
	v_pk_mul_f32 v[112:113], v[120:121], v[104:105] op_sel_hi:[1,0]
	v_pk_mul_f32 v[114:115], v[18:19], v[114:115]
	v_pk_mul_f32 v[118:119], v[22:23], v[118:119]
	v_pk_mul_f32 v[112:113], v[20:21], v[112:113]
	v_pk_mul_f32 v[116:117], v[24:25], v[116:117]
	v_bfe_u32 v111, v119, 16, 1
	v_bfe_u32 v120, v118, 16, 1
	v_bfe_u32 v121, v115, 16, 1
	v_bfe_u32 v122, v114, 16, 1
	v_add3_u32 v122, v114, v122, s10
	v_add3_u32 v121, v115, v121, s10
	v_add3_u32 v114, v118, v120, s10
	v_add3_u32 v111, v119, v111, s10
	v_bfe_u32 v115, v112, 16, 1
	v_bfe_u32 v118, v113, 16, 1
	v_bfe_u32 v119, v116, 16, 1
	v_bfe_u32 v120, v117, 16, 1
	v_add3_u32 v117, v117, v120, s10
	v_add3_u32 v116, v116, v119, s10
	v_add3_u32 v113, v113, v118, s10
	v_add3_u32 v112, v112, v115, s10
	v_lshrrev_b32_e32 v112, 16, v112
	v_lshrrev_b32_e32 v113, 16, v113
	v_lshrrev_b32_e32 v116, 16, v116
	v_lshrrev_b32_e32 v115, 16, v117
	v_and_or_b32 v115, v111, s9, v115
	v_and_or_b32 v114, v114, s9, v116
	v_and_or_b32 v113, v121, s9, v113
	v_and_or_b32 v112, v122, s9, v112
	global_store_dwordx4 v[66:67], v[112:115], off offset:2048
	v_pk_mul_f32 v[118:119], v[198:199], v[104:105] op_sel_hi:[1,0]
	v_pk_mul_f32 v[116:117], v[126:127], v[104:105] op_sel_hi:[1,0]
	v_pk_mul_f32 v[114:115], v[192:193], v[104:105] op_sel_hi:[1,0]
	v_pk_mul_f32 v[112:113], v[124:125], v[104:105] op_sel_hi:[1,0]
	v_pk_mul_f32 v[114:115], v[26:27], v[114:115]
	v_pk_mul_f32 v[118:119], v[30:31], v[118:119]
	v_pk_mul_f32 v[112:113], v[28:29], v[112:113]
	v_pk_mul_f32 v[116:117], v[32:33], v[116:117]
	v_bfe_u32 v111, v119, 16, 1
	v_bfe_u32 v120, v118, 16, 1
	v_bfe_u32 v121, v115, 16, 1
	v_bfe_u32 v122, v114, 16, 1
	v_add3_u32 v122, v114, v122, s10
	v_add3_u32 v121, v115, v121, s10
	v_add3_u32 v114, v118, v120, s10
; __device__ __forceinline__ unsigned pk2(float lo, float hi) { return f2bf(lo) | (f2bf(hi) << 16); }
; __device__ __forceinline__ void sgu_ln(const Ctx& c, bf16* P, const float* g) {
;     ...
;         for (int j = 0; j < 8; ++j) { const float* gg = g + (c.lane + 64 * j) * 8; const f32x4 g0 = *(CF4)gg, g1 = *(CF4)(gg + 4);
;             v4u w; w.x = pk2(v[j][0] * rs * g0.x, v[j][1] * rs * g0.y); w.y = pk2(v[j][2] * rs * g0.z, v[j][3] * rs * g0.w); w.z = pk2(v[j][4] * rs * g1.x, v[j][5] * rs * g1.y); w.w = pk2(v[j][6] * rs * g1.z, v[j][7] * rs * g1.w);
;             vr[64 * j] = w; }
	v_add3_u32 v111, v119, v111, s10
	v_bfe_u32 v115, v112, 16, 1
	v_bfe_u32 v118, v113, 16, 1
	v_bfe_u32 v119, v116, 16, 1
	v_bfe_u32 v120, v117, 16, 1
	v_add3_u32 v117, v117, v120, s10
	v_add3_u32 v116, v116, v119, s10
	v_add3_u32 v113, v113, v118, s10
	v_add3_u32 v112, v112, v115, s10
	v_lshrrev_b32_e32 v112, 16, v112
	v_lshrrev_b32_e32 v113, 16, v113
	v_lshrrev_b32_e32 v116, 16, v116
	v_lshrrev_b32_e32 v115, 16, v117
	v_and_or_b32 v115, v111, s9, v115
	v_and_or_b32 v114, v114, s9, v116
	v_and_or_b32 v113, v121, s9, v113
	v_and_or_b32 v112, v122, s9, v112
	v_pk_mul_f32 v[96:97], v[96:97], v[104:105] op_sel_hi:[1,0]
	v_pk_mul_f32 v[98:99], v[34:35], v[98:99]
	v_pk_mul_f32 v[100:101], v[100:101], v[104:105] op_sel_hi:[1,0]
	v_pk_mul_f32 v[102:103], v[38:39], v[102:103]
	global_store_dwordx4 v[66:67], v[112:115], off offset:3072
	v_pk_mul_f32 v[96:97], v[36:37], v[96:97]
	v_pk_mul_f32 v[100:101], v[40:41], v[100:101]
	v_bfe_u32 v111, v103, 16, 1
	v_bfe_u32 v112, v102, 16, 1
	v_bfe_u32 v113, v99, 16, 1
	v_bfe_u32 v114, v98, 16, 1
	v_add3_u32 v114, v98, v114, s10
	v_add3_u32 v113, v99, v113, s10
	v_add3_u32 v98, v102, v112, s10
	v_add3_u32 v99, v103, v111, s10
	v_bfe_u32 v102, v96, 16, 1
	v_bfe_u32 v103, v97, 16, 1
	v_bfe_u32 v111, v100, 16, 1
	v_bfe_u32 v112, v101, 16, 1
	v_add3_u32 v101, v101, v112, s10
	v_add3_u32 v100, v100, v111, s10
	v_add3_u32 v97, v97, v103, s10
	v_add3_u32 v96, v96, v102, s10
	v_lshrrev_b32_e32 v96, 16, v96
	v_lshrrev_b32_e32 v97, 16, v97
	v_lshrrev_b32_e32 v100, 16, v100
	v_lshrrev_b32_e32 v101, 16, v101
	v_pk_mul_f32 v[90:91], v[90:91], v[104:105] op_sel_hi:[1,0]
	v_pk_mul_f32 v[94:95], v[94:95], v[104:105] op_sel_hi:[1,0]
	v_and_or_b32 v99, v99, s9, v101
	v_and_or_b32 v98, v98, s9, v100
	v_and_or_b32 v97, v113, s9, v97
	v_and_or_b32 v96, v114, s9, v96
	v_pk_mul_f32 v[88:89], v[88:89], v[104:105] op_sel_hi:[1,0]
	v_pk_mul_f32 v[90:91], v[42:43], v[90:91]
	v_pk_mul_f32 v[92:93], v[92:93], v[104:105] op_sel_hi:[1,0]
	v_pk_mul_f32 v[94:95], v[50:51], v[94:95]
	global_store_dwordx4 v[70:71], v[96:99], off
	v_pk_mul_f32 v[88:89], v[48:49], v[88:89]
	v_pk_mul_f32 v[92:93], v[44:45], v[92:93]
	v_bfe_u32 v96, v95, 16, 1
	v_bfe_u32 v97, v94, 16, 1
	v_bfe_u32 v98, v91, 16, 1
	v_bfe_u32 v99, v90, 16, 1
	v_add3_u32 v99, v90, v99, s10
	v_add3_u32 v98, v91, v98, s10
	v_add3_u32 v90, v94, v97, s10
	v_add3_u32 v91, v95, v96, s10
	v_bfe_u32 v94, v88, 16, 1
	v_bfe_u32 v95, v89, 16, 1
	v_bfe_u32 v96, v92, 16, 1
	v_bfe_u32 v97, v93, 16, 1
	v_add3_u32 v93, v93, v97, s10
	v_add3_u32 v92, v92, v96, s10
	v_add3_u32 v89, v89, v95, s10
	v_add3_u32 v88, v88, v94, s10
	v_lshrrev_b32_e32 v88, 16, v88
	v_lshrrev_b32_e32 v89, 16, v89
	v_lshrrev_b32_e32 v92, 16, v92
	v_lshrrev_b32_e32 v93, 16, v93
	v_pk_mul_f32 v[82:83], v[82:83], v[104:105] op_sel_hi:[1,0]
	v_pk_mul_f32 v[86:87], v[86:87], v[104:105] op_sel_hi:[1,0]
	v_and_or_b32 v91, v91, s9, v93
	v_and_or_b32 v90, v90, s9, v92
	v_and_or_b32 v89, v98, s9, v89
	v_and_or_b32 v88, v99, s9, v88
	v_pk_mul_f32 v[80:81], v[80:81], v[104:105] op_sel_hi:[1,0]
	v_pk_mul_f32 v[82:83], v[46:47], v[82:83]
	v_pk_mul_f32 v[84:85], v[84:85], v[104:105] op_sel_hi:[1,0]
	v_pk_mul_f32 v[86:87], v[54:55], v[86:87]
	global_store_dwordx4 v[70:71], v[88:91], off offset:1024
	v_pk_mul_f32 v[80:81], v[52:53], v[80:81]
	v_pk_mul_f32 v[84:85], v[56:57], v[84:85]
	v_bfe_u32 v88, v87, 16, 1
	v_bfe_u32 v89, v86, 16, 1
	v_bfe_u32 v90, v83, 16, 1
	v_bfe_u32 v91, v82, 16, 1
	v_add3_u32 v91, v82, v91, s10
	v_add3_u32 v90, v83, v90, s10
	v_add3_u32 v82, v86, v89, s10
	v_add3_u32 v83, v87, v88, s10
	v_bfe_u32 v86, v80, 16, 1
	v_bfe_u32 v87, v81, 16, 1
	v_bfe_u32 v88, v84, 16, 1
	v_bfe_u32 v89, v85, 16, 1
	v_add3_u32 v85, v85, v89, s10
	v_add3_u32 v84, v84, v88, s10
	v_add3_u32 v81, v81, v87, s10
	v_add3_u32 v80, v80, v86, s10
	v_lshrrev_b32_e32 v80, 16, v80
	v_lshrrev_b32_e32 v81, 16, v81
	v_lshrrev_b32_e32 v84, 16, v84
	v_lshrrev_b32_e32 v85, 16, v85
	v_pk_mul_f32 v[76:77], v[76:77], v[104:105] op_sel_hi:[1,0]
	v_pk_mul_f32 v[72:73], v[72:73], v[104:105] op_sel_hi:[1,0]
	v_and_or_b32 v83, v83, s9, v85
	v_and_or_b32 v82, v82, s9, v84
	v_and_or_b32 v81, v90, s9, v81
	v_and_or_b32 v80, v91, s9, v80
	v_pk_mul_f32 v[74:75], v[74:75], v[104:105] op_sel_hi:[1,0]
	v_pk_mul_f32 v[76:77], v[58:59], v[76:77]
	v_pk_mul_f32 v[78:79], v[78:79], v[104:105] op_sel_hi:[1,0]
	v_pk_mul_f32 v[72:73], v[62:63], v[72:73]
	global_store_dwordx4 v[70:71], v[80:83], off offset:2048
	v_pk_mul_f32 v[74:75], v[60:61], v[74:75]
	v_pk_mul_f32 v[78:79], v[64:65], v[78:79]
	s_nop 1
	v_bfe_u32 v82, v77, 16, 1
	v_bfe_u32 v83, v76, 16, 1
	v_add3_u32 v76, v76, v83, s10
	v_add3_u32 v77, v77, v82, s10
	s_nop 1
	v_bfe_u32 v80, v74, 16, 1
	v_bfe_u32 v81, v75, 16, 1
	s_nop 3
	v_add3_u32 v75, v75, v81, s10
	v_add3_u32 v74, v74, v80, s10
	v_lshrrev_b32_e32 v80, 16, v74
	v_lshrrev_b32_e32 v81, 16, v75
	s_nop 1
	v_cvt_pk_bf16_f32 v75, v79, v73
	v_cvt_pk_bf16_f32 v74, v78, v72
	v_and_or_b32 v73, v77, s9, v81
	v_and_or_b32 v72, v76, s9, v80
	v_lshl_add_u64 v[66:67], v[66:67], 0, s[6:7]
	global_store_dwordx4 v[70:71], v[72:75], off offset:3072
	s_cbranch_scc1 .LBB0_3519
	s_mov_b64 s[4:5], s[20:21]

; __device__ __forceinline__ unsigned pk2(float lo, float hi) { return f2bf(lo) | (f2bf(hi) << 16); }
; __device__ __forceinline__ float wave_sum(float v) {
; #pragma unroll
;     for (int o = 1; o < 64; o <<= 1) v += __shfl_xor(v, o);
;     return v;
; __device__ __forceinline__ void rms_row_bf16(const Ctx& c, const float* xrow, const float* gain, bf16* orow, float* copy) {
;     const f32x4* xr = (const f32x4*)xrow + c.lane; f32x4 v[8]; float s = 0.f;
; #pragma unroll
;     for (int j = 0; j < 8; ++j) { v[j] = xr[64 * j]; s += (v[j].x * v[j].x + v[j].y * v[j].y) + (v[j].z * v[j].z + v[j].w * v[j].w); }
;     const float rs = rsqrtf(wave_sum(s) * (1.f / DM) + EPS);
;     if (copy) {
; #pragma unroll
;         for (int j = 0; j < 8; ++j) ((f32x4*)copy + c.lane)[64 * j] = v[j]; }
;     const f32x4* gr = (const f32x4*)gain + c.lane; v2u* o8 = (v2u*)orow + c.lane;
; #pragma unroll
;     for (int j = 0; j < 8; ++j) { const f32x4 g = gr[64 * j]; v2u o; o.x = pk2(v[j].x * rs * g.x, v[j].y * rs * g.y); o.y = pk2(v[j].z * rs * g.z, v[j].w * rs * g.w); o8[64 * j] = o; }
.LBB0_4681:
	global_load_dwordx4 v[54:57], v[42:43], off offset:-4096
	global_load_dwordx4 v[28:31], v[42:43], off offset:-3072
	global_load_dwordx4 v[24:27], v[42:43], off offset:-2048
	global_load_dwordx4 v[16:19], v[42:43], off
	global_load_dwordx4 v[20:23], v[42:43], off offset:-1024
	global_load_dwordx4 v[12:15], v[42:43], off offset:1024
	global_load_dwordx4 v[4:7], v[42:43], off offset:3072
	global_load_dwordx4 v[8:11], v[42:43], off offset:2048
	global_load_dwordx4 v[58:61], v[32:33], off
	s_add_i32 s2, s2, s86
	v_lshl_add_u64 v[42:43], v[42:43], 0, s[6:7]
	s_cmpk_lt_i32 s2, 0x400
	s_waitcnt vmcnt(0)
	v_mov_b32_e32 v64, v55
	v_mov_b32_e32 v65, v29
	v_mov_b32_e32 v68, v57
	v_mov_b32_e32 v69, v31
	v_mov_b32_e32 v62, v54
	v_mov_b32_e32 v63, v28
	v_mov_b32_e32 v66, v56
	v_mov_b32_e32 v67, v30
	v_pk_mul_f32 v[70:71], v[26:27], v[26:27]
	v_pk_mul_f32 v[72:73], v[24:25], v[24:25]
	v_mov_b32_e32 v86, v54
	v_mov_b32_e32 v87, v56
	v_mov_b32_e32 v88, v58
	v_mov_b32_e32 v89, v60
	v_mov_b32_e32 v56, v55
	v_mov_b32_e32 v60, v59
	v_mov_b32_e32 v54, v28
	v_mov_b32_e32 v55, v30
	v_mov_b32_e32 v30, v29
	v_pk_mul_f32 v[28:29], v[64:65], v[64:65]
	v_pk_mul_f32 v[58:59], v[68:69], v[68:69]
	v_pk_mov_b32 v[64:65], v[72:73], v[70:71] op_sel:[1,0]
	v_mov_b32_e32 v73, v71
	v_pk_fma_f32 v[28:29], v[62:63], v[62:63], v[28:29]
	v_pk_fma_f32 v[58:59], v[66:67], v[66:67], v[58:59]
	v_mul_f32_e32 v74, v21, v21
	v_mul_f32_e32 v76, v23, v23
	v_pk_add_f32 v[62:63], v[64:65], v[72:73]
	v_pk_add_f32 v[28:29], v[28:29], v[58:59]
	v_mul_f32_e32 v53, v16, v16
	v_mul_f32_e32 v83, v17, v17
	v_mul_f32_e32 v85, v18, v18
	v_mul_f32_e32 v90, v19, v19
	v_pk_fma_f32 v[68:69], v[20:21], v[20:21], v[74:75] op_sel_hi:[1,1,0]
	v_pk_fma_f32 v[70:71], v[22:23], v[22:23], v[76:77] op_sel_hi:[1,1,0]
	v_pk_add_f32 v[58:59], v[62:63], v[62:63] op_sel:[0,1] op_sel_hi:[1,0]
	v_pk_add_f32 v[28:29], v[28:29], v[28:29] op_sel:[0,1] op_sel_hi:[1,0]
	v_pk_mul_f32 v[78:79], v[14:15], v[14:15]
	v_pk_mul_f32 v[80:81], v[12:13], v[12:13]
	v_mov_b32_e32 v69, v85
	v_mov_b32_e32 v71, v90
	v_mov_b32_e32 v59, v83
	v_mov_b32_e32 v29, v53
	v_pk_mov_b32 v[74:75], v[80:81], v[78:79] op_sel:[1,0]
	v_mov_b32_e32 v81, v79
	v_pk_add_f32 v[62:63], v[68:69], v[70:71]
	v_pk_add_f32 v[28:29], v[28:29], v[58:59]
	v_mul_f32_e32 v82, v9, v9
	v_mul_f32_e32 v84, v11, v11
	v_pk_add_f32 v[64:65], v[74:75], v[80:81]
	v_pk_add_f32 v[28:29], v[28:29], v[62:63]
	v_mul_f32_e32 v91, v4, v4
	v_mul_f32_e32 v92, v5, v5
	v_mul_f32_e32 v93, v6, v6
	v_mul_f32_e32 v94, v7, v7
	v_pk_fma_f32 v[76:77], v[8:9], v[8:9], v[82:83] op_sel_hi:[1,1,0]
	v_pk_fma_f32 v[78:79], v[10:11], v[10:11], v[84:85] op_sel_hi:[1,1,0]
	v_pk_add_f32 v[64:65], v[64:65], v[64:65] op_sel:[0,1] op_sel_hi:[1,0]
	v_pk_add_f32 v[28:29], v[28:29], v[28:29] op_sel:[0,1] op_sel_hi:[1,0]
	v_mov_b32_e32 v77, v93
	v_mov_b32_e32 v79, v94
	v_mov_b32_e32 v65, v92
	v_mov_b32_e32 v29, v91
	v_pk_add_f32 v[66:67], v[76:77], v[78:79]
	v_pk_add_f32 v[28:29], v[28:29], v[64:65]
	s_nop 0
	v_pk_add_f32 v[28:29], v[28:29], v[66:67]
	s_nop 0
	v_add_f32_e32 v28, v28, v29
	s_waitcnt lgkmcnt(0)
	s_nop 1
	v_add_f32_dpp v28, v28, v28 quad_perm:[1,0,3,2] row_mask:0xf bank_mask:0xf
	s_waitcnt lgkmcnt(0)
	s_nop 1
	v_add_f32_dpp v28, v28, v28 quad_perm:[2,3,0,1] row_mask:0xf bank_mask:0xf
	s_waitcnt lgkmcnt(0)
	s_nop 1
	v_add_f32_dpp v28, v28, v28 row_half_mirror row_mask:0xf bank_mask:0xf
	s_waitcnt lgkmcnt(0)
	s_nop 1
	v_add_f32_dpp v28, v28, v28 row_mirror row_mask:0xf bank_mask:0xf
	s_waitcnt lgkmcnt(0)
	v_mov_b32_e32 v29, v28
	s_nop 1
	v_permlane16_swap_b32_e32 v28, v29
	v_add_f32_e32 v28, v28, v29
	s_waitcnt lgkmcnt(0)
	v_mov_b32_e32 v29, v28
	s_nop 1
	v_permlane32_swap_b32_e32 v28, v29
	v_add_f32_e32 v28, v28, v29
	v_fmamk_f32 v28, v28, 0x3a000000, v51
	v_mul_f32_e32 v29, 0x4b800000, v28
	v_cmp_gt_f32_e32 vcc, s3, v28
	s_nop 1
	v_cndmask_b32_e32 v28, v28, v29, vcc
	v_rsq_f32_e32 v28, v28
	s_nop 0
	v_mul_f32_e32 v29, 0x45800000, v28
	v_cndmask_b32_e32 v28, v28, v29, vcc
	v_pk_mul_f32 v[58:59], v[86:87], v[28:29] op_sel_hi:[1,0]
	v_pk_mul_f32 v[56:57], v[56:57], v[28:29] op_sel_hi:[1,0]
	v_pk_mul_f32 v[62:63], v[54:55], v[28:29] op_sel_hi:[1,0]
	v_pk_mul_f32 v[54:55], v[88:89], v[58:59]
	v_pk_mul_f32 v[56:57], v[60:61], v[56:57]
	v_and_b32_sdwa v29, v55, v52 dst_sel:DWORD dst_unused:UNUSED_PAD src0_sel:WORD_1 src1_sel:DWORD
	v_and_b32_sdwa v53, v54, v52 dst_sel:DWORD dst_unused:UNUSED_PAD src0_sel:WORD_1 src1_sel:DWORD
	v_and_b32_sdwa v58, v57, v52 dst_sel:DWORD dst_unused:UNUSED_PAD src0_sel:WORD_1 src1_sel:DWORD
	v_and_b32_sdwa v59, v56, v52 dst_sel:DWORD dst_unused:UNUSED_PAD src0_sel:WORD_1 src1_sel:DWORD
	v_add3_u32 v53, v54, v53, s10
	v_add3_u32 v29, v55, v29, s10
	v_add3_u32 v54, v57, v58, s10
	v_add3_u32 v55, v56, v59, s10
	v_and_b32_e32 v54, 0xffff0000, v54
	v_and_b32_e32 v56, 0xffff0000, v55
	v_or_b32_sdwa v55, v54, v29 dst_sel:DWORD dst_unused:UNUSED_PAD src0_sel:DWORD src1_sel:WORD_1
	v_or_b32_sdwa v54, v56, v53 dst_sel:DWORD dst_unused:UNUSED_PAD src0_sel:DWORD src1_sel:WORD_1
	global_store_dwordx2 v[44:45], v[54:55], off
	global_load_dwordx4 v[54:57], v[32:33], off offset:1024
	v_pk_mul_f32 v[30:31], v[30:31], v[28:29] op_sel_hi:[1,0]
	s_waitcnt vmcnt(0)
; __device__ __forceinline__ unsigned pk2(float lo, float hi) { return f2bf(lo) | (f2bf(hi) << 16); }
; __device__ __forceinline__ void rms_row_bf16(const Ctx& c, const float* xrow, const float* gain, bf16* orow, float* copy) {
;     ...
;     const f32x4* gr = (const f32x4*)gain + c.lane; v2u* o8 = (v2u*)orow + c.lane;
; #pragma unroll
;     for (int j = 0; j < 8; ++j) { const f32x4 g = gr[64 * j]; v2u o; o.x = pk2(v[j].x * rs * g.x, v[j].y * rs * g.y); o.y = pk2(v[j].z * rs * g.z, v[j].w * rs * g.w); o8[64 * j] = o; }
	v_mov_b32_e32 v59, v56
	v_mov_b32_e32 v56, v55
	v_mov_b32_e32 v58, v54
	v_pk_mul_f32 v[30:31], v[56:57], v[30:31]
	v_pk_mul_f32 v[54:55], v[58:59], v[62:63]
	v_and_b32_sdwa v56, v31, v52 dst_sel:DWORD dst_unused:UNUSED_PAD src0_sel:WORD_1 src1_sel:DWORD
	s_nop 0
	v_and_b32_sdwa v29, v55, v52 dst_sel:DWORD dst_unused:UNUSED_PAD src0_sel:WORD_1 src1_sel:DWORD
	s_nop 0
	v_add3_u32 v31, v31, v56, s10
	s_nop 1
	v_add3_u32 v29, v55, v29, s10
	v_and_b32_e32 v31, 0xffff0000, v31
	s_nop 0
	v_or_b32_sdwa v31, v31, v29 dst_sel:DWORD dst_unused:UNUSED_PAD src0_sel:DWORD src1_sel:WORD_1
	v_cvt_pk_bf16_f32 v30, v54, v30
	global_store_dwordx2 v[44:45], v[30:31], off offset:512
	global_load_dwordx4 v[54:57], v[32:33], off offset:2048
	v_mov_b32_e32 v30, v24
	v_mov_b32_e32 v31, v26
	v_mov_b32_e32 v26, v25
	v_pk_mul_f32 v[24:25], v[30:31], v[28:29] op_sel_hi:[1,0]
	v_pk_mul_f32 v[26:27], v[26:27], v[28:29] op_sel_hi:[1,0]
	s_waitcnt vmcnt(0)
	v_mov_b32_e32 v31, v56
	v_mov_b32_e32 v56, v55
	v_mov_b32_e32 v30, v54
	v_pk_mul_f32 v[26:27], v[56:57], v[26:27]
	v_pk_mul_f32 v[24:25], v[30:31], v[24:25]
	v_and_b32_sdwa v31, v27, v52 dst_sel:DWORD dst_unused:UNUSED_PAD src0_sel:WORD_1 src1_sel:DWORD
	s_nop 0
	v_and_b32_sdwa v29, v25, v52 dst_sel:DWORD dst_unused:UNUSED_PAD src0_sel:WORD_1 src1_sel:DWORD
	s_nop 0
	v_add3_u32 v27, v27, v31, s10
	s_nop 1
	v_add3_u32 v25, v25, v29, s10
	v_and_b32_e32 v27, 0xffff0000, v27
	s_nop 0
	v_or_b32_sdwa v25, v27, v25 dst_sel:DWORD dst_unused:UNUSED_PAD src0_sel:DWORD src1_sel:WORD_1
	v_cvt_pk_bf16_f32 v24, v24, v26
	global_store_dwordx2 v[44:45], v[24:25], off offset:1024
	global_load_dwordx4 v[24:27], v[32:33], off offset:3072
	v_mov_b32_e32 v30, v20
	v_mov_b32_e32 v31, v22
	v_mov_b32_e32 v22, v21
	v_pk_mul_f32 v[20:21], v[30:31], v[28:29] op_sel_hi:[1,0]
	v_pk_mul_f32 v[22:23], v[22:23], v[28:29] op_sel_hi:[1,0]
	s_waitcnt vmcnt(0)
	v_mov_b32_e32 v31, v26
	v_mov_b32_e32 v26, v25
	v_mov_b32_e32 v30, v24
	v_pk_mul_f32 v[22:23], v[26:27], v[22:23]
	v_pk_mul_f32 v[20:21], v[30:31], v[20:21]
	s_nop 7
	s_nop 1
	v_cvt_pk_bf16_f32 v21, v21, v23
	v_cvt_pk_bf16_f32 v20, v20, v22
	global_store_dwordx2 v[44:45], v[20:21], off offset:1536
	global_load_dwordx4 v[20:23], v[34:35], off
	v_mov_b32_e32 v24, v16
	v_mov_b32_e32 v25, v18
	v_mov_b32_e32 v18, v17
	v_pk_mul_f32 v[16:17], v[24:25], v[28:29] op_sel_hi:[1,0]
	v_pk_mul_f32 v[18:19], v[18:19], v[28:29] op_sel_hi:[1,0]
	s_waitcnt vmcnt(0)
	v_mov_b32_e32 v25, v22
	v_mov_b32_e32 v22, v21
	v_mov_b32_e32 v24, v20
	v_pk_mul_f32 v[18:19], v[22:23], v[18:19]
	v_pk_mul_f32 v[16:17], v[24:25], v[16:17]
	s_nop 7
	s_nop 1
	v_cvt_pk_bf16_f32 v17, v17, v19
	v_cvt_pk_bf16_f32 v16, v16, v18
	global_store_dwordx2 v[44:45], v[16:17], off offset:2048
	global_load_dwordx4 v[16:19], v[36:37], off
	v_mov_b32_e32 v20, v12
	v_mov_b32_e32 v21, v14
	v_mov_b32_e32 v14, v13
	v_pk_mul_f32 v[12:13], v[20:21], v[28:29] op_sel_hi:[1,0]
	v_pk_mul_f32 v[14:15], v[14:15], v[28:29] op_sel_hi:[1,0]
	s_waitcnt vmcnt(0)
	v_mov_b32_e32 v21, v18
	v_mov_b32_e32 v18, v17
	v_mov_b32_e32 v20, v16
	v_pk_mul_f32 v[14:15], v[18:19], v[14:15]
	v_pk_mul_f32 v[12:13], v[20:21], v[12:13]
	s_nop 7
	s_nop 1
	v_cvt_pk_bf16_f32 v13, v13, v15
	v_cvt_pk_bf16_f32 v12, v12, v14
	global_store_dwordx2 v[44:45], v[12:13], off offset:2560
	global_load_dwordx4 v[12:15], v[38:39], off
	v_mov_b32_e32 v16, v8
	v_mov_b32_e32 v17, v10
	v_mov_b32_e32 v10, v9
	v_pk_mul_f32 v[8:9], v[16:17], v[28:29] op_sel_hi:[1,0]
	v_pk_mul_f32 v[10:11], v[10:11], v[28:29] op_sel_hi:[1,0]
	s_waitcnt vmcnt(0)
	v_mov_b32_e32 v17, v14
	v_mov_b32_e32 v14, v13
	v_mov_b32_e32 v16, v12
	v_pk_mul_f32 v[10:11], v[10:11], v[14:15]
	v_pk_mul_f32 v[8:9], v[8:9], v[16:17]
	s_nop 7
	s_nop 1
	v_cvt_pk_bf16_f32 v9, v9, v11
	v_cvt_pk_bf16_f32 v8, v8, v10
	global_store_dwordx2 v[44:45], v[8:9], off offset:3072
	global_load_dwordx4 v[8:11], v[40:41], off
	v_mov_b32_e32 v12, v4
	v_mov_b32_e32 v13, v6
	v_mov_b32_e32 v6, v5
	v_pk_mul_f32 v[4:5], v[12:13], v[28:29] op_sel_hi:[1,0]
	v_pk_mul_f32 v[6:7], v[6:7], v[28:29] op_sel_hi:[1,0]
	s_waitcnt vmcnt(0)
	v_mov_b32_e32 v13, v10
	v_mov_b32_e32 v10, v9
	v_mov_b32_e32 v12, v8
	v_pk_mul_f32 v[6:7], v[6:7], v[10:11]
	v_pk_mul_f32 v[4:5], v[4:5], v[12:13]
	v_and_b32_sdwa v10, v7, v52 dst_sel:DWORD dst_unused:UNUSED_PAD src0_sel:WORD_1 src1_sel:DWORD
	v_and_b32_sdwa v11, v6, v52 dst_sel:DWORD dst_unused:UNUSED_PAD src0_sel:WORD_1 src1_sel:DWORD
	v_and_b32_sdwa v8, v5, v52 dst_sel:DWORD dst_unused:UNUSED_PAD src0_sel:WORD_1 src1_sel:DWORD
	v_and_b32_sdwa v9, v4, v52 dst_sel:DWORD dst_unused:UNUSED_PAD src0_sel:WORD_1 src1_sel:DWORD
	v_add3_u32 v7, v7, v10, s10
	v_add3_u32 v6, v6, v11, s10
	v_add3_u32 v4, v4, v9, s10
	v_add3_u32 v5, v5, v8, s10
	v_and_b32_e32 v7, 0xffff0000, v7
	v_and_b32_e32 v6, 0xffff0000, v6
	v_or_b32_sdwa v5, v7, v5 dst_sel:DWORD dst_unused:UNUSED_PAD src0_sel:DWORD src1_sel:WORD_1
	v_or_b32_sdwa v4, v6, v4 dst_sel:DWORD dst_unused:UNUSED_PAD src0_sel:DWORD src1_sel:WORD_1
	global_store_dwordx2 v[44:45], v[4:5], off offset:3584
	v_lshl_add_u64 v[44:45], v[44:45], 0, s[8:9]
	s_cbranch_scc1 .LBB0_4681

; __device__ __forceinline__ float wave_sum(float v) {
; #pragma unroll
;     for (int o = 1; o < 64; o <<= 1) v += __shfl_xor(v, o);
;     return v;
; __device__ __forceinline__ void postnorm(const Ctx& c, const bf16* MF, bf16* XB, float* RS, const float* gpost, float* OUT) {
;     ...
;         const v4u* mr = (const v4u*)(MF + (size_t)row * DM) + c.lane; v4u* xr = (v4u*)(XB + (size_t)row * DM) + c.lane;
;         v4u mv[4], xv[4]; float v[4][8]; float s = 0.f;
; #pragma unroll
;         for (int j = 0; j < 4; ++j) { mv[j] = mr[64 * j]; xv[j] = xr[64 * j]; }
; #pragma unroll
;         for (int j = 0; j < 4; ++j)
; #pragma unroll
;             for (int k = 0; k < 4; ++k) { v[j][2 * k] = bflo(mv[j][k]); v[j][2 * k + 1] = bfhi(mv[j][k]); s += v[j][2 * k] * v[j][2 * k] + v[j][2 * k + 1] * v[j][2 * k + 1]; }
;         const float rs = rsqrtf(wave_sum(s) * (1.f / DM) + EPS);
.LBB0_5518:
	v_readlane_b32 s4, v253, 0
	v_readlane_b32 s5, v253, 1
	s_nop 1
	v_lshl_add_u64 v[32:33], s[4:5], 0, v[34:35]
	v_add_co_u32_e32 v58, vcc, 0xd400000, v32
	s_nop 1
	v_addc_co_u32_e32 v59, vcc, 0, v33, vcc
	s_waitcnt lgkmcnt(0)
	global_load_dwordx4 v[46:49], v[58:59], off
	global_load_dwordx4 v[50:53], v[58:59], off offset:1024
	global_load_dwordx4 v[54:57], v[58:59], off offset:2048
	s_nop 0
	global_load_dwordx4 v[58:61], v[58:59], off offset:3072
	v_add_co_u32_e32 v32, vcc, 0x9400000, v32
	s_waitcnt vmcnt(3)
	v_lshlrev_b32_e32 v79, 16, v47
	v_addc_co_u32_e32 v33, vcc, 0, v33, vcc
	global_load_dwordx4 v[62:65], v[32:33], off
	global_load_dwordx4 v[66:69], v[32:33], off offset:1024
	global_load_dwordx4 v[70:73], v[32:33], off offset:2048
	global_load_dwordx4 v[74:77], v[32:33], off offset:3072
	v_lshlrev_b32_e32 v78, 16, v46
	v_and_b32_e32 v47, 0xffff0000, v47
	v_and_b32_e32 v46, 0xffff0000, v46
	v_lshlrev_b32_e32 v81, 16, v49
	v_lshlrev_b32_e32 v80, 16, v48
	v_and_b32_e32 v49, 0xffff0000, v49
	v_and_b32_e32 v48, 0xffff0000, v48
	v_pk_mul_f32 v[94:95], v[46:47], v[46:47]
	v_pk_mul_f32 v[98:99], v[48:49], v[48:49]
	v_pk_fma_f32 v[94:95], v[78:79], v[78:79], v[94:95]
	s_waitcnt vmcnt(6)
	v_lshlrev_b32_e32 v83, 16, v51
	v_lshlrev_b32_e32 v82, 16, v50
	v_and_b32_e32 v51, 0xffff0000, v51
	v_and_b32_e32 v50, 0xffff0000, v50
	v_pk_fma_f32 v[98:99], v[80:81], v[80:81], v[98:99]
	v_add_f32_e32 v45, v94, v95
	v_pk_mul_f32 v[102:103], v[50:51], v[50:51]
	v_add_f32_e32 v45, v98, v45
	v_lshlrev_b32_e32 v85, 16, v53
	v_lshlrev_b32_e32 v84, 16, v52
	v_and_b32_e32 v53, 0xffff0000, v53
	v_and_b32_e32 v52, 0xffff0000, v52
	v_pk_fma_f32 v[102:103], v[82:83], v[82:83], v[102:103]
	v_add_f32_e32 v45, v99, v45
	v_pk_mul_f32 v[104:105], v[52:53], v[52:53]
	v_add_f32_e32 v45, v102, v45
	s_waitcnt vmcnt(5)
	v_lshlrev_b32_e32 v87, 16, v55
	v_lshlrev_b32_e32 v86, 16, v54
	v_and_b32_e32 v55, 0xffff0000, v55
	v_and_b32_e32 v54, 0xffff0000, v54
	v_pk_fma_f32 v[104:105], v[84:85], v[84:85], v[104:105]
	v_add_f32_e32 v45, v103, v45
	v_pk_mul_f32 v[106:107], v[54:55], v[54:55]
	v_add_f32_e32 v45, v104, v45
	v_lshlrev_b32_e32 v89, 16, v57
	v_lshlrev_b32_e32 v88, 16, v56
	v_and_b32_e32 v57, 0xffff0000, v57
	v_and_b32_e32 v56, 0xffff0000, v56
	v_pk_fma_f32 v[106:107], v[86:87], v[86:87], v[106:107]
	v_add_f32_e32 v45, v105, v45
	v_pk_mul_f32 v[108:109], v[56:57], v[56:57]
	v_add_f32_e32 v45, v106, v45
	s_waitcnt vmcnt(4)
	v_lshlrev_b32_e32 v91, 16, v59
	v_lshlrev_b32_e32 v90, 16, v58
	v_and_b32_e32 v59, 0xffff0000, v59
	v_and_b32_e32 v58, 0xffff0000, v58
	v_pk_fma_f32 v[108:109], v[88:89], v[88:89], v[108:109]
	v_add_f32_e32 v45, v107, v45
	v_pk_mul_f32 v[110:111], v[58:59], v[58:59]
	v_add_f32_e32 v45, v108, v45
	v_lshlrev_b32_e32 v93, 16, v61
	v_lshlrev_b32_e32 v92, 16, v60
	v_and_b32_e32 v61, 0xffff0000, v61
	v_and_b32_e32 v60, 0xffff0000, v60
	v_pk_fma_f32 v[110:111], v[90:91], v[90:91], v[110:111]
	v_add_f32_e32 v45, v109, v45
	v_pk_mul_f32 v[112:113], v[60:61], v[60:61]
	v_add_f32_e32 v45, v110, v45
	v_pk_fma_f32 v[112:113], v[92:93], v[92:93], v[112:113]
	v_add_f32_e32 v45, v111, v45
	v_add_f32_e32 v45, v112, v45
	v_add_f32_e32 v45, v113, v45
	s_waitcnt lgkmcnt(0)
	s_nop 1
	v_add_f32_dpp v45, v45, v45 quad_perm:[1,0,3,2] row_mask:0xf bank_mask:0xf
	s_waitcnt lgkmcnt(0)
	s_nop 1
	v_add_f32_dpp v45, v45, v45 quad_perm:[2,3,0,1] row_mask:0xf bank_mask:0xf
	s_waitcnt vmcnt(3)
	v_lshlrev_b32_e32 v97, 16, v63
	v_lshlrev_b32_e32 v96, 16, v62
	v_and_b32_e32 v63, 0xffff0000, v63
	s_waitcnt lgkmcnt(0)
	s_nop 1
	v_add_f32_dpp v45, v45, v45 row_half_mirror row_mask:0xf bank_mask:0xf
	v_and_b32_e32 v62, 0xffff0000, v62
	v_lshlrev_b32_e32 v101, 16, v65
	v_lshlrev_b32_e32 v100, 16, v64
	v_and_b32_e32 v65, 0xffff0000, v65
	s_waitcnt lgkmcnt(0)
	s_nop 1
	v_add_f32_dpp v45, v45, v45 row_mirror row_mask:0xf bank_mask:0xf
	v_and_b32_e32 v64, 0xffff0000, v64
	s_waitcnt vmcnt(0)
	v_lshlrev_b32_e32 v109, 16, v77
	v_and_b32_e32 v77, 0xffff0000, v77
	v_lshlrev_b32_e32 v95, 16, v67
	s_waitcnt lgkmcnt(0)
	v_mov_b32_e32 v106, v45
	s_nop 1
	v_permlane16_swap_b32_e32 v45, v106
	v_add_f32_e32 v45, v45, v106
	v_lshlrev_b32_e32 v94, 16, v66
	v_and_b32_e32 v67, 0xffff0000, v67
	v_and_b32_e32 v66, 0xffff0000, v66
	v_lshlrev_b32_e32 v99, 16, v69
	s_waitcnt lgkmcnt(0)
; __device__ __forceinline__ unsigned pk2(float lo, float hi) { return f2bf(lo) | (f2bf(hi) << 16); }
; __device__ __forceinline__ void postnorm(const Ctx& c, const bf16* MF, bf16* XB, float* RS, const float* gpost, float* OUT) {
;     ...
;         const float rs = rsqrtf(wave_sum(s) * (1.f / DM) + EPS);
;         float s2 = 0.f;
; #pragma unroll
;         for (int j = 0; j < 4; ++j) { const float* gp = gpost + (c.lane + 64 * j) * 8; const f32x4 g0 = *(CF4)gp, g1 = *(CF4)(gp + 4);
; #pragma unroll
;             for (int k = 0; k < 4; ++k) { const float ga = (k < 2) ? g0[2 * k] : g1[2 * k - 4], gb = (k < 2) ? g0[2 * k + 1] : g1[2 * k - 3];
;                 v[j][2 * k] = bflo(xv[j][k]) + v[j][2 * k] * rs * ga; v[j][2 * k + 1] = bfhi(xv[j][k]) + v[j][2 * k + 1] * rs * gb;
;                 s2 += v[j][2 * k] * v[j][2 * k] + v[j][2 * k + 1] * v[j][2 * k + 1]; } }
;         if (OUT) {
; #pragma unroll
;             for (int j = 0; j < 4; ++j) { float* op = OUT + (size_t)row * DM + (c.lane + 64 * j) * 8; *(f32x4*)op = (f32x4){v[j][0], v[j][1], v[j][2], v[j][3]}; *(f32x4*)(op + 4) = (f32x4){v[j][4], v[j][5], v[j][6], v[j][7]}; }
;         } else {
; #pragma unroll
;             for (int j = 0; j < 4; ++j) { v4u o; o.x = pk2(v[j][0], v[j][1]); o.y = pk2(v[j][2], v[j][3]); o.z = pk2(v[j][4], v[j][5]); o.w = pk2(v[j][6], v[j][7]); xr[64 * j] = o; }
;             const float rs2 = rsqrtf(wave_sum(s2) * (1.f / DM) + EPS); if (c.lane == 0) RS[row] = rs2;
	v_mov_b32_e32 v108, v45
	s_nop 1
	v_permlane32_swap_b32_e32 v45, v108
	v_add_f32_e32 v45, v45, v108
	v_fmamk_f32 v45, v45, 0x3a000000, v38
	v_mul_f32_e32 v108, 0x4b800000, v45
	v_cmp_gt_f32_e32 vcc, s15, v45
	v_lshlrev_b32_e32 v98, 16, v68
	v_and_b32_e32 v69, 0xffff0000, v69
	v_cndmask_b32_e32 v45, v45, v108, vcc
	v_rsq_f32_e32 v45, v45
	v_lshlrev_b32_e32 v108, 16, v76
	v_and_b32_e32 v76, 0xffff0000, v76
	v_and_b32_e32 v68, 0xffff0000, v68
	v_mul_f32_e32 v110, 0x45800000, v45
	v_cndmask_b32_e32 v110, v45, v110, vcc
	v_pk_mul_f32 v[46:47], v[110:111], v[46:47] op_sel_hi:[0,1]
	v_pk_mul_f32 v[78:79], v[110:111], v[78:79] op_sel_hi:[0,1]
	v_pk_mul_f32 v[48:49], v[110:111], v[48:49] op_sel_hi:[0,1]
	v_pk_fma_f32 v[46:47], v[36:37], v[46:47], v[62:63]
	v_pk_mul_f32 v[60:61], v[110:111], v[60:61] op_sel_hi:[0,1]
	v_pk_mul_f32 v[80:81], v[110:111], v[80:81] op_sel_hi:[0,1]
	v_pk_fma_f32 v[78:79], v[2:3], v[78:79], v[96:97]
	v_pk_fma_f32 v[48:49], v[4:5], v[48:49], v[64:65]
	v_pk_fma_f32 v[60:61], v[28:29], v[60:61], v[76:77]
	v_pk_mul_f32 v[76:77], v[46:47], v[46:47]
	v_pk_fma_f32 v[62:63], v[6:7], v[80:81], v[100:101]
	v_pk_fma_f32 v[76:77], v[78:79], v[78:79], v[76:77]
	v_pk_mul_f32 v[80:81], v[48:49], v[48:49]
	v_add_f32_e32 v45, v76, v77
	v_pk_fma_f32 v[80:81], v[62:63], v[62:63], v[80:81]
	v_pk_mul_f32 v[50:51], v[110:111], v[50:51] op_sel_hi:[0,1]
	v_add_f32_e32 v45, v80, v45
	v_pk_mul_f32 v[82:83], v[110:111], v[82:83] op_sel_hi:[0,1]
	v_pk_fma_f32 v[50:51], v[8:9], v[50:51], v[66:67]
	v_add_f32_e32 v45, v81, v45
	s_nop 3
	v_pk_mul_f32 v[52:53], v[110:111], v[52:53] op_sel_hi:[0,1]
	v_pk_fma_f32 v[64:65], v[10:11], v[82:83], v[94:95]
	v_pk_mul_f32 v[82:83], v[50:51], v[50:51]
	s_nop 7
	v_pk_mul_f32 v[84:85], v[110:111], v[84:85] op_sel_hi:[0,1]
	v_pk_fma_f32 v[52:53], v[12:13], v[52:53], v[68:69]
	v_pk_fma_f32 v[82:83], v[64:65], v[64:65], v[82:83]
	s_nop 3
	v_lshlrev_b32_e32 v103, 16, v71
	v_lshlrev_b32_e32 v102, 16, v70
	v_and_b32_e32 v71, 0xffff0000, v71
	v_and_b32_e32 v70, 0xffff0000, v70
	v_pk_fma_f32 v[66:67], v[14:15], v[84:85], v[98:99]
	v_pk_mul_f32 v[54:55], v[110:111], v[54:55] op_sel_hi:[0,1]
	v_pk_mul_f32 v[84:85], v[52:53], v[52:53]
	v_add_f32_e32 v45, v82, v45
	s_nop 3
	v_pk_mul_f32 v[68:69], v[110:111], v[86:87] op_sel_hi:[0,1]
	v_pk_fma_f32 v[54:55], v[16:17], v[54:55], v[70:71]
	v_pk_fma_f32 v[84:85], v[66:67], v[66:67], v[84:85]
	v_add_f32_e32 v45, v83, v45
	v_cvt_pk_bf16_f32 v49, v63, v49
	v_cvt_pk_bf16_f32 v48, v62, v48
	v_cvt_pk_bf16_f32 v47, v79, v47
	v_cvt_pk_bf16_f32 v46, v78, v46
	v_lshlrev_b32_e32 v105, 16, v73
	v_lshlrev_b32_e32 v104, 16, v72
	v_and_b32_e32 v73, 0xffff0000, v73
	v_and_b32_e32 v72, 0xffff0000, v72
	v_pk_fma_f32 v[68:69], v[18:19], v[68:69], v[102:103]
	v_pk_mul_f32 v[56:57], v[110:111], v[56:57] op_sel_hi:[0,1]
	v_pk_mul_f32 v[86:87], v[54:55], v[54:55]
	v_add_f32_e32 v45, v84, v45
	global_store_dwordx4 v[32:33], v[46:49], off
	v_pk_mul_f32 v[70:71], v[110:111], v[88:89] op_sel_hi:[0,1]
	v_pk_fma_f32 v[56:57], v[20:21], v[56:57], v[72:73]
	s_nop 3
	v_pk_fma_f32 v[86:87], v[68:69], v[68:69], v[86:87]
	v_add_f32_e32 v45, v85, v45
	s_nop 7
	v_lshlrev_b32_e32 v107, 16, v75
	v_lshlrev_b32_e32 v106, 16, v74
	v_and_b32_e32 v75, 0xffff0000, v75
	v_and_b32_e32 v74, 0xffff0000, v74
	v_pk_fma_f32 v[70:71], v[22:23], v[70:71], v[104:105]
	v_pk_mul_f32 v[58:59], v[110:111], v[58:59] op_sel_hi:[0,1]
	v_pk_mul_f32 v[88:89], v[56:57], v[56:57]
	v_add_f32_e32 v45, v86, v45
	s_nop 3
	v_pk_mul_f32 v[72:73], v[110:111], v[90:91] op_sel_hi:[0,1]
	v_pk_fma_f32 v[58:59], v[24:25], v[58:59], v[74:75]
	v_pk_fma_f32 v[88:89], v[70:71], v[70:71], v[88:89]
	v_add_f32_e32 v45, v87, v45
	s_nop 3
	v_pk_fma_f32 v[72:73], v[26:27], v[72:73], v[106:107]
	v_pk_mul_f32 v[90:91], v[58:59], v[58:59]
	v_add_f32_e32 v45, v88, v45
	v_cvt_pk_bf16_f32 v49, v67, v53
	v_cvt_pk_bf16_f32 v48, v66, v52
	v_cvt_pk_bf16_f32 v47, v65, v51
	v_cvt_pk_bf16_f32 v46, v64, v50
	v_pk_mul_f32 v[74:75], v[110:111], v[92:93] op_sel_hi:[0,1]
	v_pk_fma_f32 v[90:91], v[72:73], v[72:73], v[90:91]
	v_add_f32_e32 v45, v89, v45
	global_store_dwordx4 v[32:33], v[46:49], off offset:1024
	v_pk_fma_f32 v[74:75], v[30:31], v[74:75], v[108:109]
	v_pk_mul_f32 v[92:93], v[60:61], v[60:61]
	s_nop 1
	v_add_f32_e32 v45, v90, v45
	s_nop 5
	v_pk_fma_f32 v[92:93], v[74:75], v[74:75], v[92:93]
	v_add_f32_e32 v45, v91, v45
	s_nop 5
	v_add_f32_e32 v45, v92, v45
	s_nop 5
	v_add_f32_e32 v45, v93, v45
	v_cvt_pk_bf16_f32 v49, v71, v57
	v_cvt_pk_bf16_f32 v48, v70, v56
	v_cvt_pk_bf16_f32 v47, v69, v55
	v_cvt_pk_bf16_f32 v46, v68, v54
	global_store_dwordx4 v[32:33], v[46:49], off offset:2048
	s_nop 3
	s_waitcnt lgkmcnt(0)
	s_nop 1
	v_add_f32_dpp v45, v45, v45 quad_perm:[1,0,3,2] row_mask:0xf bank_mask:0xf
	s_nop 3
	s_waitcnt lgkmcnt(0)
	s_nop 1
	v_add_f32_dpp v45, v45, v45 quad_perm:[2,3,0,1] row_mask:0xf bank_mask:0xf
	s_nop 0
	v_cvt_pk_bf16_f32 v51, v75, v61
	s_nop 1
	s_waitcnt lgkmcnt(0)
	s_nop 1
	v_add_f32_dpp v45, v45, v45 row_half_mirror row_mask:0xf bank_mask:0xf
	s_nop 3
	s_waitcnt lgkmcnt(0)
	s_nop 1
	v_add_f32_dpp v45, v45, v45 row_mirror row_mask:0xf bank_mask:0xf
	s_nop 3
	s_waitcnt lgkmcnt(0)
	v_mov_b32_e32 v47, v45
	s_nop 1
	v_permlane16_swap_b32_e32 v45, v47
	v_add_f32_e32 v45, v45, v47
	ds_bpermute_b32 v46, v44, v45
	s_nop 0
	v_cvt_pk_bf16_f32 v50, v74, v60
	v_cvt_pk_bf16_f32 v49, v73, v59
	v_cvt_pk_bf16_f32 v48, v72, v58
	global_store_dwordx4 v[32:33], v[48:51], off offset:3072
	s_and_saveexec_b64 s[10:11], s[0:1]
	s_cbranch_execz .LBB0_5517
	s_waitcnt lgkmcnt(0)
	v_add_f32_e32 v32, v45, v46
	v_fmamk_f32 v32, v32, 0x3a000000, v38
	v_mul_f32_e32 v33, 0x4b800000, v32
	v_cmp_gt_f32_e32 vcc, s15, v32
	v_readlane_b32 s4, v253, 0
	v_readlane_b32 s5, v253, 1
	v_cndmask_b32_e32 v32, v32, v33, vcc
	v_rsq_f32_e32 v32, v32
	s_add_u32 s18, s4, s13
	s_addc_u32 s19, s5, s14
	v_mul_f32_e32 v33, 0x45800000, v32
	v_cndmask_b32_e32 v32, v32, v33, vcc
	global_store_dword v251, v32, s[18:19]
	s_branch .LBB0_5517

; __device__ __forceinline__ float wave_sum(float v) {
; #pragma unroll
;     for (int o = 1; o < 64; o <<= 1) v += __shfl_xor(v, o);
;     return v;
; __device__ __forceinline__ void postnorm(const Ctx& c, const bf16* MF, bf16* XB, float* RS, const float* gpost, float* OUT) {
;     ...
;         const v4u* mr = (const v4u*)(MF + (size_t)row * DM) + c.lane; v4u* xr = (v4u*)(XB + (size_t)row * DM) + c.lane;
;         v4u mv[4], xv[4]; float v[4][8]; float s = 0.f;
; #pragma unroll
;         for (int j = 0; j < 4; ++j) { mv[j] = mr[64 * j]; xv[j] = xr[64 * j]; }
; #pragma unroll
;         for (int j = 0; j < 4; ++j)
; #pragma unroll
;             for (int k = 0; k < 4; ++k) { v[j][2 * k] = bflo(mv[j][k]); v[j][2 * k + 1] = bfhi(mv[j][k]); s += v[j][2 * k] * v[j][2 * k] + v[j][2 * k + 1] * v[j][2 * k + 1]; }
;         const float rs = rsqrtf(wave_sum(s) * (1.f / DM) + EPS);
.LBB0_5805:
	v_readlane_b32 s18, v253, 0
	v_readlane_b32 s19, v253, 1
	s_nop 1
	v_lshl_add_u64 v[40:41], s[18:19], 0, v[34:35]
	v_add_co_u32_e32 v30, vcc, 0xd400000, v40
	s_waitcnt lgkmcnt(0)
	s_nop 0
	v_addc_co_u32_e32 v31, vcc, 0, v41, vcc
	global_load_dwordx4 v[42:45], v[30:31], off
	s_waitcnt lgkmcnt(0)
	global_load_dwordx4 v[46:49], v[30:31], off offset:1024
	global_load_dwordx4 v[50:53], v[30:31], off offset:2048
	global_load_dwordx4 v[54:57], v[30:31], off offset:3072
	v_add_co_u32_e32 v78, vcc, 0x9400000, v40
	s_waitcnt vmcnt(3)
	v_lshlrev_b32_e32 v81, 16, v45
	v_addc_co_u32_e32 v79, vcc, 0, v41, vcc
	global_load_dwordx4 v[58:61], v[78:79], off
	global_load_dwordx4 v[62:65], v[78:79], off offset:1024
	global_load_dwordx4 v[66:69], v[78:79], off offset:2048
	global_load_dwordx4 v[30:33], v[78:79], off offset:3072
	v_lshlrev_b32_e32 v79, 16, v43
	v_lshlrev_b32_e32 v78, 16, v42
	v_and_b32_e32 v43, 0xffff0000, v43
	v_and_b32_e32 v42, 0xffff0000, v42
	v_lshlrev_b32_e32 v80, 16, v44
	v_and_b32_e32 v45, 0xffff0000, v45
	v_and_b32_e32 v44, 0xffff0000, v44
	s_waitcnt vmcnt(4)
	v_lshlrev_b32_e32 v91, 16, v55
	v_lshlrev_b32_e32 v90, 16, v54
	v_and_b32_e32 v93, 0xffff0000, v55
	v_and_b32_e32 v92, 0xffff0000, v54
	v_pk_mul_f32 v[54:55], v[42:43], v[42:43]
	v_pk_mul_f32 v[98:99], v[44:45], v[44:45]
	v_pk_fma_f32 v[54:55], v[78:79], v[78:79], v[54:55]
	v_lshlrev_b32_e32 v83, 16, v47
	v_lshlrev_b32_e32 v82, 16, v46
	v_and_b32_e32 v47, 0xffff0000, v47
	v_and_b32_e32 v46, 0xffff0000, v46
	v_pk_fma_f32 v[98:99], v[80:81], v[80:81], v[98:99]
	v_add_f32_e32 v54, v54, v55
	v_pk_mul_f32 v[100:101], v[46:47], v[46:47]
	v_add_f32_e32 v54, v98, v54
	v_lshlrev_b32_e32 v85, 16, v49
	v_lshlrev_b32_e32 v84, 16, v48
	v_and_b32_e32 v49, 0xffff0000, v49
	v_and_b32_e32 v48, 0xffff0000, v48
	v_pk_fma_f32 v[100:101], v[82:83], v[82:83], v[100:101]
	v_add_f32_e32 v54, v99, v54
	v_pk_mul_f32 v[102:103], v[48:49], v[48:49]
	v_add_f32_e32 v54, v100, v54
	v_lshlrev_b32_e32 v87, 16, v51
	v_lshlrev_b32_e32 v86, 16, v50
	v_and_b32_e32 v51, 0xffff0000, v51
	v_and_b32_e32 v50, 0xffff0000, v50
	v_pk_fma_f32 v[102:103], v[84:85], v[84:85], v[102:103]
	v_add_f32_e32 v54, v101, v54
	v_pk_mul_f32 v[104:105], v[50:51], v[50:51]
	v_add_f32_e32 v54, v102, v54
	v_lshlrev_b32_e32 v89, 16, v53
	v_lshlrev_b32_e32 v88, 16, v52
	v_and_b32_e32 v53, 0xffff0000, v53
	v_and_b32_e32 v52, 0xffff0000, v52
	v_pk_fma_f32 v[104:105], v[86:87], v[86:87], v[104:105]
	v_add_f32_e32 v54, v103, v54
	v_pk_mul_f32 v[106:107], v[52:53], v[52:53]
	v_add_f32_e32 v54, v104, v54
	v_pk_fma_f32 v[106:107], v[88:89], v[88:89], v[106:107]
	v_add_f32_e32 v54, v105, v54
	v_pk_mul_f32 v[108:109], v[92:93], v[92:93]
	v_add_f32_e32 v54, v106, v54
	v_and_b32_e32 v97, 0xffff0000, v57
	v_and_b32_e32 v96, 0xffff0000, v56
	v_pk_fma_f32 v[108:109], v[90:91], v[90:91], v[108:109]
	v_add_f32_e32 v54, v107, v54
	v_lshlrev_b32_e32 v95, 16, v57
	v_lshlrev_b32_e32 v94, 16, v56
	v_pk_mul_f32 v[110:111], v[96:97], v[96:97]
	v_add_f32_e32 v54, v108, v54
	v_pk_fma_f32 v[110:111], v[94:95], v[94:95], v[110:111]
	v_add_f32_e32 v54, v109, v54
	v_add_f32_e32 v54, v110, v54
	v_add_f32_e32 v77, v111, v54
	s_waitcnt lgkmcnt(0)
	s_nop 1
	v_add_f32_dpp v77, v77, v77 quad_perm:[1,0,3,2] row_mask:0xf bank_mask:0xf
	s_waitcnt lgkmcnt(0)
	s_nop 1
	v_add_f32_dpp v77, v77, v77 quad_perm:[2,3,0,1] row_mask:0xf bank_mask:0xf
	s_waitcnt vmcnt(3)
	v_lshlrev_b32_e32 v57, 16, v59
	s_waitcnt vmcnt(2)
	v_lshlrev_b32_e32 v98, 16, v62
	v_and_b32_e32 v100, 0xffff0000, v62
	s_waitcnt lgkmcnt(0)
	s_nop 1
	v_add_f32_dpp v62, v77, v77 row_half_mirror row_mask:0xf bank_mask:0xf
	v_lshlrev_b32_e32 v99, 16, v63
	v_and_b32_e32 v101, 0xffff0000, v63
	s_waitcnt vmcnt(0)
	v_lshlrev_b32_e32 v114, 16, v30
	v_and_b32_e32 v116, 0xffff0000, v30
	v_lshlrev_b32_e32 v56, 16, v58
	v_and_b32_e32 v55, 0xffff0000, v59
	s_waitcnt lgkmcnt(0)
	s_nop 1
	v_add_f32_dpp v62, v62, v62 row_mirror row_mask:0xf bank_mask:0xf
	v_and_b32_e32 v54, 0xffff0000, v58
	v_lshlrev_b32_e32 v115, 16, v31
	v_and_b32_e32 v117, 0xffff0000, v31
	v_lshlrev_b32_e32 v59, 16, v61
	s_waitcnt lgkmcnt(0)
	v_mov_b32_e32 v63, v62
	s_nop 1
	v_permlane16_swap_b32_e32 v62, v63
	v_add_f32_e32 v62, v62, v63
	v_lshlrev_b32_e32 v58, 16, v60
	v_and_b32_e32 v61, 0xffff0000, v61
	v_and_b32_e32 v60, 0xffff0000, v60
	v_lshlrev_b32_e32 v103, 16, v65
	s_waitcnt lgkmcnt(0)
; __device__ __forceinline__ void postnorm(const Ctx& c, const bf16* MF, bf16* XB, float* RS, const float* gpost, float* OUT) {
;     ...
;         const float rs = rsqrtf(wave_sum(s) * (1.f / DM) + EPS);
;         float s2 = 0.f;
; #pragma unroll
;         for (int j = 0; j < 4; ++j) { const float* gp = gpost + (c.lane + 64 * j) * 8; const f32x4 g0 = *(CF4)gp, g1 = *(CF4)(gp + 4);
; #pragma unroll
;             for (int k = 0; k < 4; ++k) { const float ga = (k < 2) ? g0[2 * k] : g1[2 * k - 4], gb = (k < 2) ? g0[2 * k + 1] : g1[2 * k - 3];
;                 v[j][2 * k] = bflo(xv[j][k]) + v[j][2 * k] * rs * ga; v[j][2 * k + 1] = bfhi(xv[j][k]) + v[j][2 * k + 1] * rs * gb;
;                 s2 += v[j][2 * k] * v[j][2 * k] + v[j][2 * k + 1] * v[j][2 * k + 1]; } }
;         if (OUT) {
; #pragma unroll
;             for (int j = 0; j < 4; ++j) { float* op = OUT + (size_t)row * DM + (c.lane + 64 * j) * 8; *(f32x4*)op = (f32x4){v[j][0], v[j][1], v[j][2], v[j][3]}; *(f32x4*)(op + 4) = (f32x4){v[j][4], v[j][5], v[j][6], v[j][7]}; }
	v_mov_b32_e32 v63, v62
	s_nop 1
	v_permlane32_swap_b32_e32 v62, v63
	v_add_f32_e32 v62, v62, v63
	v_fmamk_f32 v62, v62, 0x3a000000, v76
	v_mul_f32_e32 v63, 0x4b800000, v62
	v_cmp_gt_f32_e32 vcc, s23, v62
	v_lshlrev_b32_e32 v102, 16, v64
	v_and_b32_e32 v105, 0xffff0000, v65
	v_cndmask_b32_e32 v62, v62, v63, vcc
	v_rsq_f32_e32 v62, v62
	v_and_b32_e32 v104, 0xffff0000, v64
	v_lshlrev_b32_e32 v107, 16, v67
	v_lshlrev_b32_e32 v106, 16, v66
	v_mul_f32_e32 v30, 0x45800000, v62
	v_cndmask_b32_e32 v118, v62, v30, vcc
	v_pk_mul_f32 v[30:31], v[118:119], v[78:79] op_sel_hi:[0,1]
	v_pk_mul_f32 v[42:43], v[118:119], v[42:43] op_sel_hi:[0,1]
	v_and_b32_e32 v109, 0xffff0000, v67
	v_and_b32_e32 v108, 0xffff0000, v66
	v_lshlrev_b32_e32 v111, 16, v69
	v_lshlrev_b32_e32 v110, 16, v68
	v_and_b32_e32 v113, 0xffff0000, v69
	v_and_b32_e32 v112, 0xffff0000, v68
	v_pk_mul_f32 v[64:65], v[118:119], v[80:81] op_sel_hi:[0,1]
	v_pk_mul_f32 v[44:45], v[118:119], v[44:45] op_sel_hi:[0,1]
	v_pk_mul_f32 v[78:79], v[118:119], v[82:83] op_sel_hi:[0,1]
	v_pk_mul_f32 v[46:47], v[118:119], v[46:47] op_sel_hi:[0,1]
	v_pk_mul_f32 v[80:81], v[118:119], v[84:85] op_sel_hi:[0,1]
	v_pk_mul_f32 v[48:49], v[118:119], v[48:49] op_sel_hi:[0,1]
	v_pk_mul_f32 v[82:83], v[118:119], v[86:87] op_sel_hi:[0,1]
	v_pk_fma_f32 v[62:63], v[0:1], v[30:31], v[56:57]
	v_pk_fma_f32 v[66:67], v[36:37], v[42:43], v[54:55]
	v_pk_mul_f32 v[30:31], v[118:119], v[88:89] op_sel_hi:[0,1]
	v_pk_mul_f32 v[42:43], v[118:119], v[52:53] op_sel_hi:[0,1]
	v_pk_mul_f32 v[50:51], v[118:119], v[50:51] op_sel_hi:[0,1]
	v_pk_fma_f32 v[64:65], v[4:5], v[64:65], v[58:59]
	v_pk_fma_f32 v[68:69], v[2:3], v[44:45], v[60:61]
	v_pk_fma_f32 v[54:55], v[8:9], v[78:79], v[98:99]
	v_pk_fma_f32 v[58:59], v[6:7], v[46:47], v[100:101]
	v_pk_fma_f32 v[56:57], v[12:13], v[80:81], v[102:103]
	v_pk_fma_f32 v[60:61], v[10:11], v[48:49], v[104:105]
	v_pk_fma_f32 v[46:47], v[16:17], v[82:83], v[106:107]
	v_pk_fma_f32 v[48:49], v[20:21], v[30:31], v[110:111]
	v_pk_fma_f32 v[52:53], v[18:19], v[42:43], v[112:113]
	v_pk_mul_f32 v[30:31], v[118:119], v[90:91] op_sel_hi:[0,1]
	v_pk_mul_f32 v[42:43], v[118:119], v[92:93] op_sel_hi:[0,1]
	v_lshlrev_b32_e32 v45, 16, v33
	v_lshlrev_b32_e32 v44, 16, v32
	v_pk_mul_f32 v[78:79], v[118:119], v[94:95] op_sel_hi:[0,1]
	v_and_b32_e32 v81, 0xffff0000, v33
	v_and_b32_e32 v80, 0xffff0000, v32
	v_pk_mul_f32 v[82:83], v[118:119], v[96:97] op_sel_hi:[0,1]
	v_pk_fma_f32 v[50:51], v[14:15], v[50:51], v[108:109]
	v_pk_fma_f32 v[30:31], v[24:25], v[30:31], v[114:115]
	v_pk_fma_f32 v[42:43], v[22:23], v[42:43], v[116:117]
	v_pk_fma_f32 v[32:33], v[28:29], v[78:79], v[44:45]
	v_pk_fma_f32 v[44:45], v[26:27], v[82:83], v[80:81]
	s_and_b64 vcc, exec, s[2:3]
	s_cbranch_vccz .LBB0_5807
	v_mov_b32_e32 v78, v62
	v_mov_b32_e32 v79, v66
	v_mov_b32_e32 v80, v63
	v_mov_b32_e32 v81, v67
	global_store_dwordx4 v[38:39], v[78:81], off offset:-4096
	s_nop 1
	v_mov_b32_e32 v78, v64
	v_mov_b32_e32 v79, v68
	v_mov_b32_e32 v80, v65
	v_mov_b32_e32 v81, v69
	global_store_dwordx4 v[38:39], v[78:81], off offset:-4080
	s_nop 1
	v_mov_b32_e32 v78, v54
	v_mov_b32_e32 v79, v58
	v_mov_b32_e32 v80, v55
	v_mov_b32_e32 v81, v59
	global_store_dwordx4 v[38:39], v[78:81], off offset:-2048
	s_nop 1
	v_mov_b32_e32 v78, v56
	v_mov_b32_e32 v79, v60
	v_mov_b32_e32 v80, v57
	v_mov_b32_e32 v81, v61
	global_store_dwordx4 v[38:39], v[78:81], off offset:-2032
	s_nop 1
	v_mov_b32_e32 v78, v46
	v_mov_b32_e32 v79, v50
	v_mov_b32_e32 v80, v47
	v_mov_b32_e32 v81, v51
	global_store_dwordx4 v[38:39], v[78:81], off
	s_nop 1
	v_mov_b32_e32 v78, v48
	v_mov_b32_e32 v79, v52
	v_mov_b32_e32 v80, v49
	v_mov_b32_e32 v81, v53
	global_store_dwordx4 v[38:39], v[78:81], off offset:16
	s_nop 1
	v_mov_b32_e32 v78, v30
	v_mov_b32_e32 v79, v42
	v_mov_b32_e32 v80, v31
	v_mov_b32_e32 v81, v43
	global_store_dwordx4 v[38:39], v[78:81], off offset:2048
	s_nop 1
	v_mov_b32_e32 v78, v32
	v_mov_b32_e32 v79, v44
	v_mov_b32_e32 v80, v33
	v_mov_b32_e32 v81, v45
	global_store_dwordx4 v[38:39], v[78:81], off offset:2064
	s_cbranch_execnz .LBB0_5804
	s_branch .LBB0_5808
; __device__ __forceinline__ unsigned pk2(float lo, float hi) { return f2bf(lo) | (f2bf(hi) << 16); }
; __device__ __forceinline__ float wave_sum(float v) {
; #pragma unroll
;     for (int o = 1; o < 64; o <<= 1) v += __shfl_xor(v, o);
;     return v;
; __device__ __forceinline__ void postnorm(const Ctx& c, const bf16* MF, bf16* XB, float* RS, const float* gpost, float* OUT) {
;     ...
;         } else {
; #pragma unroll
;             for (int j = 0; j < 4; ++j) { v4u o; o.x = pk2(v[j][0], v[j][1]); o.y = pk2(v[j][2], v[j][3]); o.z = pk2(v[j][4], v[j][5]); o.w = pk2(v[j][6], v[j][7]); xr[64 * j] = o; }
;             const float rs2 = rsqrtf(wave_sum(s2) * (1.f / DM) + EPS); if (c.lane == 0) RS[row] = rs2;
.LBB0_5807:
.LBB0_5808:
	v_lshl_add_u64 v[78:79], v[40:41], 0, s[10:11]
	v_lshl_add_u64 v[80:81], v[40:41], 0, s[12:13]
	v_lshl_add_u64 v[82:83], v[40:41], 0, s[14:15]
	v_lshl_add_u64 v[84:85], v[40:41], 0, s[16:17]
	v_pk_mul_f32 v[40:41], v[66:67], v[66:67]
	v_pk_mul_f32 v[86:87], v[68:69], v[68:69]
	v_pk_fma_f32 v[40:41], v[62:63], v[62:63], v[40:41]
	v_pk_fma_f32 v[86:87], v[64:65], v[64:65], v[86:87]
	v_add_f32_e32 v40, v40, v41
	v_add_f32_e32 v40, v86, v40
	v_add_f32_e32 v40, v87, v40
	v_bfe_u32 v41, v69, 16, 1
	s_nop 2
	v_pk_mul_f32 v[88:89], v[58:59], v[58:59]
	s_nop 2
	v_add3_u32 v41, v69, v41, s24
	s_nop 2
	v_bfe_u32 v87, v65, 16, 1
	v_pk_fma_f32 v[88:89], v[54:55], v[54:55], v[88:89]
	v_add3_u32 v65, v65, v87, s24
	s_nop 2
	v_pk_mul_f32 v[90:91], v[60:61], v[60:61]
	v_add_f32_e32 v40, v88, v40
	s_nop 2
	v_lshrrev_b32_e32 v65, 16, v65
	v_pk_fma_f32 v[90:91], v[56:57], v[56:57], v[90:91]
	v_add_f32_e32 v40, v89, v40
	v_and_or_b32 v65, v41, s22, v65
	v_cvt_pk_bf16_f32 v64, v64, v68
	v_cvt_pk_bf16_f32 v63, v63, v67
	v_cvt_pk_bf16_f32 v62, v62, v66
	v_pk_mul_f32 v[92:93], v[50:51], v[50:51]
	v_add_f32_e32 v40, v90, v40
	global_store_dwordx4 v[78:79], v[62:65], off
	v_bfe_u32 v41, v61, 16, 1
	v_pk_fma_f32 v[92:93], v[46:47], v[46:47], v[92:93]
	s_nop 2
	v_add_f32_e32 v40, v91, v40
	s_nop 2
	v_add3_u32 v41, v61, v41, s24
	s_nop 2
	v_bfe_u32 v64, v57, 16, 1
	v_pk_mul_f32 v[94:95], v[52:53], v[52:53]
	v_add_f32_e32 v40, v92, v40
	v_add3_u32 v57, v57, v64, s24
	s_nop 2
	v_pk_fma_f32 v[94:95], v[48:49], v[48:49], v[94:95]
	v_add_f32_e32 v40, v93, v40
	s_nop 2
	v_lshrrev_b32_e32 v57, 16, v57
	v_pk_mul_f32 v[96:97], v[42:43], v[42:43]
	v_add_f32_e32 v40, v94, v40
	v_and_or_b32 v57, v41, s22, v57
	v_cvt_pk_bf16_f32 v56, v56, v60
	v_cvt_pk_bf16_f32 v55, v55, v59
	v_cvt_pk_bf16_f32 v54, v54, v58
	v_pk_fma_f32 v[96:97], v[30:31], v[30:31], v[96:97]
	v_add_f32_e32 v40, v95, v40
	global_store_dwordx4 v[80:81], v[54:57], off
	v_bfe_u32 v41, v53, 16, 1
	v_pk_mul_f32 v[98:99], v[44:45], v[44:45]
	s_nop 2
	v_add_f32_e32 v40, v96, v40
	s_nop 2
	v_add3_u32 v41, v53, v41, s24
	s_nop 2
	v_bfe_u32 v56, v49, 16, 1
	v_pk_fma_f32 v[98:99], v[32:33], v[32:33], v[98:99]
	v_add_f32_e32 v40, v97, v40
	v_add3_u32 v49, v49, v56, s24
	s_nop 2
	v_add_f32_e32 v40, v98, v40
	s_nop 2
	v_lshrrev_b32_e32 v49, 16, v49
	v_add_f32_e32 v40, v99, v40
	v_and_or_b32 v49, v41, s22, v49
	v_cvt_pk_bf16_f32 v48, v48, v52
	v_cvt_pk_bf16_f32 v47, v47, v51
	v_cvt_pk_bf16_f32 v46, v46, v50
	global_store_dwordx4 v[82:83], v[46:49], off
	v_bfe_u32 v41, v45, 16, 1
	v_bfe_u32 v49, v42, 16, 1
	v_add3_u32 v49, v42, v49, s24
	v_bfe_u32 v48, v43, 16, 1
	s_waitcnt lgkmcnt(0)
	s_nop 1
	v_add_f32_dpp v40, v40, v40 quad_perm:[1,0,3,2] row_mask:0xf bank_mask:0xf
	v_add3_u32 v46, v43, v48, s24
	v_bfe_u32 v43, v30, 16, 1
	v_add3_u32 v41, v45, v41, s24
	v_bfe_u32 v45, v31, 16, 1
	s_waitcnt lgkmcnt(0)
	s_nop 1
	v_add_f32_dpp v40, v40, v40 quad_perm:[2,3,0,1] row_mask:0xf bank_mask:0xf
	v_add3_u32 v30, v30, v43, s24
	v_add3_u32 v31, v31, v45, s24
	v_lshrrev_b32_e32 v45, 16, v30
	s_nop 0
	s_waitcnt lgkmcnt(0)
	s_nop 1
	v_add_f32_dpp v40, v40, v40 row_half_mirror row_mask:0xf bank_mask:0xf
	v_bfe_u32 v48, v33, 16, 1
	s_nop 1
	v_add3_u32 v33, v33, v48, s24
	s_waitcnt lgkmcnt(0)
	s_nop 1
	v_add_f32_dpp v30, v40, v40 row_mirror row_mask:0xf bank_mask:0xf
	s_nop 0
	v_lshrrev_b32_e32 v47, 16, v31
	v_lshrrev_b32_e32 v31, 16, v33
	v_and_or_b32 v43, v41, s22, v31
	s_waitcnt lgkmcnt(0)
	v_mov_b32_e32 v40, v30
	s_nop 1
	v_permlane16_swap_b32_e32 v30, v40
	v_add_f32_e32 v30, v30, v40
	ds_bpermute_b32 v31, v75, v30
	s_nop 0
	v_cvt_pk_bf16_f32 v42, v32, v44
	v_and_or_b32 v41, v46, s22, v47
	v_and_or_b32 v40, v49, s22, v45
	global_store_dwordx4 v[84:85], v[40:43], off
	s_and_saveexec_b64 s[18:19], s[0:1]
	s_cbranch_execz .LBB0_5803
	s_waitcnt lgkmcnt(0)
	v_add_f32_e32 v30, v30, v31
	v_fmamk_f32 v30, v30, 0x3a000000, v76
	v_mul_f32_e32 v31, 0x4b800000, v30
	v_cmp_gt_f32_e32 vcc, s23, v30
	v_readlane_b32 s26, v253, 0
	v_readlane_b32 s27, v253, 1
	v_cndmask_b32_e32 v30, v30, v31, vcc
	v_rsq_f32_e32 v30, v30
	s_add_u32 s26, s26, s20
	s_addc_u32 s27, s27, s21
	v_mul_f32_e32 v31, 0x45800000, v30
	v_cndmask_b32_e32 v30, v30, v31, vcc
	global_store_dword v251, v30, s[26:27]
	s_branch .LBB0_5803
